# on top of v25: remaining multi-use DMA address adds converted to SGPR-base form (base copied to s[100:101] where it changes before the last use); 18 more VALU removed
# speedup vs baseline: 1.0112x; 1.0012x over previous
; #define PG8_STAGE(bufoff, gbase) do { _Pragma("unroll") for (int _i = 0; _i < 2; ++_i) \
;         __builtin_amdgcn_global_load_lds((const unsigned*)((const char*)(gbase) + voff[_i]), (LAS unsigned*)(lds + (bufoff) + ldsw + _i * 8192), 16, 0, 0); } while (0)
; #define PG8_LDA(dst, b, h) do { _Pragma("unroll") for (int m = 0; m < 4; ++m) _Pragma("unroll") for (int k = 0; k < 2; ++k) dst[m][k] = *(const LAS bf16x8*)(lds + PG8_SA(b, h) + aoff + m * 2048 + k * 1024); } while (0)
; #define PG8_LDB(dst, b, h) do { _Pragma("unroll") for (int n = 0; n < 2; ++n) _Pragma("unroll") for (int k = 0; k < 2; ++k) dst[n][k] = *(const LAS bf16x8*)(lds + PG8_SB(b, h) + boff + n * 2048 + k * 1024); } while (0)
; #define PG8_MMA(ai, bj, At, Bt) do { __builtin_amdgcn_s_setprio(1); _Pragma("unroll") for (int m = 0; m < 4; ++m) _Pragma("unroll") for (int n = 0; n < 2; ++n) _Pragma("unroll") for (int k = 0; k < 2; ++k) \
;         acc[ai][bj][m][n] = __builtin_amdgcn_mfma_f32_16x16x32_bf16(Bt[n][k], At[m][k], acc[ai][bj][m][n], 0, 0, 0); __builtin_amdgcn_s_setprio(0); } while (0)
; #define PG8_WAIT_V(n) asm volatile("s_waitcnt vmcnt(" #n ")" ::: "memory")
; #define PG8_WAIT_L(n) asm volatile("s_waitcnt lgkmcnt(" #n ")" ::: "memory")
; #define PG8_BAR __builtin_amdgcn_s_barrier()
; #define PG8_SCHED __builtin_amdgcn_sched_barrier(0)
; template <class Epi>
; DI void gemm_phase(LAS unsigned char* lds, const Gemm g, const StaticOrder& S, const Epi& E) {
;     ...
;             PG8_LDB(B0, 0, 0); PG8_SCHED; PG8_LDA(At, 0, 0); PG8_STAGE(PG8_SA(1, 1), a1 + hstep);
;             PG8_WAIT_L(8); PG8_BAR; PG8_WAIT_L(0); PG8_MMA(0, 0, At, B0); PG8_BAR; PG8_SCHED;
;             PG8_LDB(B1, 0, 1); PG8_STAGE(PG8_SB(0, 0), b2);
;             PG8_BAR; PG8_WAIT_L(0); PG8_MMA(0, 1, At, B1); PG8_BAR;
;             PG8_LDA(At, 0, 1); PG8_STAGE(PG8_SA(0, 0), a2);
;             PG8_BAR; PG8_WAIT_L(0); PG8_MMA(1, 0, At, B0); PG8_BAR; PG8_SCHED;
;             PG8_STAGE(PG8_SB(0, 1), b2 + hstep);
;             PG8_WAIT_V(6); PG8_BAR; PG8_MMA(1, 1, At, B1); PG8_BAR;
.LBB0_37:
	s_add_u32 s20, s18, 0xfff80080
	s_addc_u32 s21, s19, -1
	s_add_i32 s39, 0, 0x10000
	ds_read_b128 v[138:141], v135
	ds_read_b128 v[142:145], v135 offset:1024
	ds_read_b128 v[146:149], v135 offset:2048
	ds_read_b128 v[150:153], v135 offset:3072
	s_cmp_eq_u32 s38, 28
	s_cselect_b32 s23, s4, s21
	s_cselect_b32 s22, s5, s20
	s_cselect_b32 s21, s9, s37
	s_cselect_b32 s20, s11, s33
	s_add_i32 m0, s28, 0xc000
	ds_read_b128 v[186:189], v137
	ds_read_b128 v[190:193], v137 offset:1024
	ds_read_b128 v[194:197], v137 offset:2048
	ds_read_b128 v[198:201], v137 offset:3072
	ds_read_b128 v[202:205], v137 offset:4096
	ds_read_b128 v[206:209], v137 offset:5120
	ds_read_b128 v[210:213], v137 offset:6144
	ds_read_b128 v[214:217], v137 offset:7168
	global_load_lds_dwordx4 v130, s[18:19]
	s_add_i32 m0, s28, 0xe000
	s_nop 0
	global_load_lds_dwordx4 v132, s[18:19]
	s_waitcnt lgkmcnt(8)
	s_setprio 1
	s_barrier
	s_waitcnt lgkmcnt(0)
	v_mfma_f32_16x16x32_bf16 v[124:127], v[138:141], v[186:189], v[124:127]
	v_mfma_f32_16x16x32_bf16 v[120:123], v[146:149], v[186:189], v[120:123]
	v_mfma_f32_16x16x32_bf16 v[108:111], v[138:141], v[194:197], v[108:111]
	v_mfma_f32_16x16x32_bf16 v[104:107], v[146:149], v[194:197], v[104:107]
	v_mfma_f32_16x16x32_bf16 v[92:95], v[138:141], v[202:205], v[92:95]
	v_mfma_f32_16x16x32_bf16 v[88:91], v[146:149], v[202:205], v[88:91]
	v_mfma_f32_16x16x32_bf16 v[76:79], v[138:141], v[210:213], v[76:79]
	v_mfma_f32_16x16x32_bf16 v[72:75], v[146:149], v[210:213], v[72:75]
	v_mfma_f32_16x16x32_bf16 v[124:127], v[142:145], v[190:193], v[124:127]
	v_mfma_f32_16x16x32_bf16 v[120:123], v[150:153], v[190:193], v[120:123]
	v_mfma_f32_16x16x32_bf16 v[108:111], v[142:145], v[198:201], v[108:111]
	v_mfma_f32_16x16x32_bf16 v[104:107], v[150:153], v[198:201], v[104:107]
	v_mfma_f32_16x16x32_bf16 v[92:95], v[142:145], v[206:209], v[92:95]
	v_mfma_f32_16x16x32_bf16 v[88:91], v[150:153], v[206:209], v[88:91]
	v_mfma_f32_16x16x32_bf16 v[76:79], v[142:145], v[214:217], v[76:79]
	s_setprio 0
	v_mfma_f32_16x16x32_bf16 v[72:75], v[150:153], v[214:217], v[72:75]
	s_barrier
	s_add_i32 s42, 0, 0x14000
	s_add_i32 s39, s39, s27
	ds_read_b128 v[226:229], v135 offset:16384
	ds_read_b128 v[230:233], v135 offset:17408
	ds_read_b128 v[234:237], v135 offset:18432
	ds_read_b128 v[238:241], v135 offset:19456
	s_mov_b32 m0, s39
	s_nop 0
	global_load_lds_dwordx4 v158, s[20:21]
	s_add_i32 m0, s39, 0x2000
	s_nop 0
	global_load_lds_dwordx4 v128, s[20:21]
	s_waitcnt lgkmcnt(0)
	s_setprio 1
	s_barrier
	v_mfma_f32_16x16x32_bf16 v[116:119], v[226:229], v[186:189], v[116:119]
	v_mfma_f32_16x16x32_bf16 v[112:115], v[234:237], v[186:189], v[112:115]
	v_mfma_f32_16x16x32_bf16 v[100:103], v[226:229], v[194:197], v[100:103]
	v_mfma_f32_16x16x32_bf16 v[96:99], v[234:237], v[194:197], v[96:99]
	v_mfma_f32_16x16x32_bf16 v[84:87], v[226:229], v[202:205], v[84:87]
	v_mfma_f32_16x16x32_bf16 v[80:83], v[234:237], v[202:205], v[80:83]
	v_mfma_f32_16x16x32_bf16 v[68:71], v[226:229], v[210:213], v[68:71]
	v_mfma_f32_16x16x32_bf16 v[64:67], v[234:237], v[210:213], v[64:67]
	v_mfma_f32_16x16x32_bf16 v[116:119], v[230:233], v[190:193], v[116:119]
	s_mov_b32 m0, s28
	v_mfma_f32_16x16x32_bf16 v[112:115], v[238:241], v[190:193], v[112:115]
	v_lshl_add_u64 v[220:221], s[22:23], 0, v[158:159]
	v_mfma_f32_16x16x32_bf16 v[100:103], v[230:233], v[198:201], v[100:103]
	v_mfma_f32_16x16x32_bf16 v[96:99], v[238:241], v[198:201], v[96:99]
	v_mfma_f32_16x16x32_bf16 v[84:87], v[230:233], v[206:209], v[84:87]
	v_mfma_f32_16x16x32_bf16 v[80:83], v[238:241], v[206:209], v[80:83]
	v_mfma_f32_16x16x32_bf16 v[68:71], v[230:233], v[214:217], v[68:71]
	s_setprio 0
	v_mfma_f32_16x16x32_bf16 v[64:67], v[238:241], v[214:217], v[64:67]
	s_barrier
	ds_read_b128 v[186:189], v137 offset:16384
	ds_read_b128 v[190:193], v137 offset:17408
	ds_read_b128 v[194:197], v137 offset:18432
	ds_read_b128 v[198:201], v137 offset:19456
	ds_read_b128 v[202:205], v137 offset:20480
	ds_read_b128 v[206:209], v137 offset:21504
	ds_read_b128 v[210:213], v137 offset:22528
	ds_read_b128 v[214:217], v137 offset:23552
	global_load_lds_dwordx4 v[220:221], off
	s_mov_b64 s[100:101], s[22:23]
	s_mov_b32 m0, s29
	s_nop 0
	global_load_lds_dwordx4 v128, s[22:23]
	s_waitcnt lgkmcnt(0)
	s_setprio 1
	s_barrier
	v_mfma_f32_16x16x32_bf16 v[60:63], v[138:141], v[186:189], v[60:63]
	v_mfma_f32_16x16x32_bf16 v[56:59], v[146:149], v[186:189], v[56:59]
	v_mfma_f32_16x16x32_bf16 v[44:47], v[138:141], v[194:197], v[44:47]
	v_mfma_f32_16x16x32_bf16 v[40:43], v[146:149], v[194:197], v[40:43]
	v_mfma_f32_16x16x32_bf16 v[28:31], v[138:141], v[202:205], v[28:31]
	v_mfma_f32_16x16x32_bf16 v[24:27], v[146:149], v[202:205], v[24:27]
	v_mfma_f32_16x16x32_bf16 v[12:15], v[138:141], v[210:213], v[12:15]
	v_mfma_f32_16x16x32_bf16 v[8:11], v[146:149], v[210:213], v[8:11]
	v_mfma_f32_16x16x32_bf16 v[60:63], v[142:145], v[190:193], v[60:63]
	v_mfma_f32_16x16x32_bf16 v[56:59], v[150:153], v[190:193], v[56:59]
	v_mfma_f32_16x16x32_bf16 v[44:47], v[142:145], v[198:201], v[44:47]
	v_mfma_f32_16x16x32_bf16 v[40:43], v[150:153], v[198:201], v[40:43]
	v_mfma_f32_16x16x32_bf16 v[28:31], v[142:145], v[206:209], v[28:31]
	v_mfma_f32_16x16x32_bf16 v[24:27], v[150:153], v[206:209], v[24:27]
	v_mfma_f32_16x16x32_bf16 v[12:15], v[142:145], v[214:217], v[12:15]
	s_setprio 0
	v_mfma_f32_16x16x32_bf16 v[8:11], v[150:153], v[214:217], v[8:11]
	s_barrier
	s_add_u32 s40, s20, 0x80000
	s_addc_u32 s41, s21, 0
	s_add_i32 s39, s42, s27
	s_mov_b32 m0, s39
	s_nop 0
	global_load_lds_dwordx4 v158, s[40:41]
	s_add_i32 m0, s39, 0x2000
	s_nop 0
	global_load_lds_dwordx4 v128, s[40:41]
	s_waitcnt vmcnt(6)
	s_setprio 1
	s_barrier
; #define PG8_STAGE(bufoff, gbase) do { _Pragma("unroll") for (int _i = 0; _i < 2; ++_i) \
;         __builtin_amdgcn_global_load_lds((const unsigned*)((const char*)(gbase) + voff[_i]), (LAS unsigned*)(lds + (bufoff) + ldsw + _i * 8192), 16, 0, 0); } while (0)
; #define PG8_LDA(dst, b, h) do { _Pragma("unroll") for (int m = 0; m < 4; ++m) _Pragma("unroll") for (int k = 0; k < 2; ++k) dst[m][k] = *(const LAS bf16x8*)(lds + PG8_SA(b, h) + aoff + m * 2048 + k * 1024); } while (0)
; #define PG8_LDB(dst, b, h) do { _Pragma("unroll") for (int n = 0; n < 2; ++n) _Pragma("unroll") for (int k = 0; k < 2; ++k) dst[n][k] = *(const LAS bf16x8*)(lds + PG8_SB(b, h) + boff + n * 2048 + k * 1024); } while (0)
; #define PG8_MMA(ai, bj, At, Bt) do { __builtin_amdgcn_s_setprio(1); _Pragma("unroll") for (int m = 0; m < 4; ++m) _Pragma("unroll") for (int n = 0; n < 2; ++n) _Pragma("unroll") for (int k = 0; k < 2; ++k) \
;         acc[ai][bj][m][n] = __builtin_amdgcn_mfma_f32_16x16x32_bf16(Bt[n][k], At[m][k], acc[ai][bj][m][n], 0, 0, 0); __builtin_amdgcn_s_setprio(0); } while (0)
; #define PG8_WAIT_V(n) asm volatile("s_waitcnt vmcnt(" #n ")" ::: "memory")
; #define PG8_WAIT_L(n) asm volatile("s_waitcnt lgkmcnt(" #n ")" ::: "memory")
; #define PG8_BAR __builtin_amdgcn_s_barrier()
; #define PG8_SCHED __builtin_amdgcn_sched_barrier(0)
; template <class Epi>
; DI void gemm_phase(LAS unsigned char* lds, const Gemm g, const StaticOrder& S, const Epi& E) {
;     ...
;             PG8_WAIT_V(6); PG8_BAR; PG8_MMA(1, 1, At, B1); PG8_BAR;
;             PG8_LDB(B0, 1, 0); PG8_SCHED; PG8_LDA(At, 1, 0); PG8_STAGE(PG8_SA(0, 1), a2 + hstep);
;             PG8_WAIT_L(8); PG8_BAR; PG8_WAIT_L(0); PG8_MMA(0, 0, At, B0); PG8_BAR; PG8_SCHED;
;             PG8_LDB(B1, 1, 1); PG8_STAGE(PG8_SB(1, 0), b3);
;             PG8_BAR; PG8_WAIT_L(0); PG8_MMA(0, 1, At, B1); PG8_BAR;
;             PG8_LDA(At, 1, 1); PG8_STAGE(PG8_SA(1, 0), a3);
;             PG8_BAR; PG8_WAIT_L(0); PG8_MMA(1, 0, At, B0); PG8_BAR; PG8_SCHED;
	v_mfma_f32_16x16x32_bf16 v[52:55], v[226:229], v[186:189], v[52:55]
	v_mfma_f32_16x16x32_bf16 v[48:51], v[234:237], v[186:189], v[48:51]
	v_mfma_f32_16x16x32_bf16 v[36:39], v[226:229], v[194:197], v[36:39]
	v_mfma_f32_16x16x32_bf16 v[32:35], v[234:237], v[194:197], v[32:35]
	v_mfma_f32_16x16x32_bf16 v[20:23], v[226:229], v[202:205], v[20:23]
	v_mfma_f32_16x16x32_bf16 v[16:19], v[234:237], v[202:205], v[16:19]
	v_mfma_f32_16x16x32_bf16 v[4:7], v[226:229], v[210:213], v[4:7]
	v_mfma_f32_16x16x32_bf16 v[0:3], v[234:237], v[210:213], v[0:3]
	v_mfma_f32_16x16x32_bf16 v[52:55], v[230:233], v[190:193], v[52:55]
	s_add_i32 s39, 0, 0x18000
	v_mfma_f32_16x16x32_bf16 v[48:51], v[238:241], v[190:193], v[48:51]
	v_mfma_f32_16x16x32_bf16 v[36:39], v[230:233], v[198:201], v[36:39]
	v_mfma_f32_16x16x32_bf16 v[32:35], v[238:241], v[198:201], v[32:35]
	v_mfma_f32_16x16x32_bf16 v[20:23], v[230:233], v[206:209], v[20:23]
	v_mfma_f32_16x16x32_bf16 v[16:19], v[238:241], v[206:209], v[16:19]
	v_mfma_f32_16x16x32_bf16 v[4:7], v[230:233], v[214:217], v[4:7]
	s_setprio 0
	v_mfma_f32_16x16x32_bf16 v[0:3], v[238:241], v[214:217], v[0:3]
	s_barrier
	ds_read_b128 v[138:141], v135 offset:32768
	ds_read_b128 v[142:145], v135 offset:33792
	ds_read_b128 v[146:149], v135 offset:34816
	ds_read_b128 v[150:153], v135 offset:35840
	s_add_u32 s22, s22, 0x80000
	s_addc_u32 s23, s23, 0
	s_mov_b32 m0, s30
	ds_read_b128 v[186:189], v137 offset:32768
	ds_read_b128 v[190:193], v137 offset:33792
	ds_read_b128 v[194:197], v137 offset:34816
	ds_read_b128 v[198:201], v137 offset:35840
	ds_read_b128 v[202:205], v137 offset:36864
	ds_read_b128 v[206:209], v137 offset:37888
	ds_read_b128 v[210:213], v137 offset:38912
	ds_read_b128 v[214:217], v137 offset:39936
	global_load_lds_dwordx4 v158, s[22:23]
	s_mov_b32 m0, s31
	s_nop 0
	global_load_lds_dwordx4 v128, s[22:23]
	s_waitcnt lgkmcnt(8)
	s_setprio 1
	s_barrier
	s_waitcnt lgkmcnt(0)
	v_mfma_f32_16x16x32_bf16 v[124:127], v[138:141], v[186:189], v[124:127]
	v_mfma_f32_16x16x32_bf16 v[120:123], v[146:149], v[186:189], v[120:123]
	v_mfma_f32_16x16x32_bf16 v[108:111], v[138:141], v[194:197], v[108:111]
	v_mfma_f32_16x16x32_bf16 v[104:107], v[146:149], v[194:197], v[104:107]
	v_mfma_f32_16x16x32_bf16 v[92:95], v[138:141], v[202:205], v[92:95]
	v_mfma_f32_16x16x32_bf16 v[88:91], v[146:149], v[202:205], v[88:91]
	v_mfma_f32_16x16x32_bf16 v[76:79], v[138:141], v[210:213], v[76:79]
	v_mfma_f32_16x16x32_bf16 v[72:75], v[146:149], v[210:213], v[72:75]
	v_mfma_f32_16x16x32_bf16 v[124:127], v[142:145], v[190:193], v[124:127]
	v_mfma_f32_16x16x32_bf16 v[120:123], v[150:153], v[190:193], v[120:123]
	v_mfma_f32_16x16x32_bf16 v[108:111], v[142:145], v[198:201], v[108:111]
	v_mfma_f32_16x16x32_bf16 v[104:107], v[150:153], v[198:201], v[104:107]
	v_mfma_f32_16x16x32_bf16 v[92:95], v[142:145], v[206:209], v[92:95]
	v_mfma_f32_16x16x32_bf16 v[88:91], v[150:153], v[206:209], v[88:91]
	v_mfma_f32_16x16x32_bf16 v[76:79], v[142:145], v[214:217], v[76:79]
	s_setprio 0
	v_mfma_f32_16x16x32_bf16 v[72:75], v[150:153], v[214:217], v[72:75]
	s_barrier
	s_add_i32 s22, 0, 0x1c000
	s_add_i32 s23, s39, s27
	s_add_i32 m0, s23, 0xffffff80
	ds_read_b128 v[226:229], v135 offset:49152
	ds_read_b128 v[230:233], v135 offset:50176
	ds_read_b128 v[234:237], v135 offset:51200
	ds_read_b128 v[238:241], v135 offset:52224
	global_load_lds_dwordx4 v158, s[20:21] offset:128
	s_add_i32 m0, s23, 0x1f80
	s_nop 0
	global_load_lds_dwordx4 v128, s[20:21] offset:128
	s_waitcnt lgkmcnt(0)
	s_setprio 1
	s_barrier
	v_mfma_f32_16x16x32_bf16 v[116:119], v[226:229], v[186:189], v[116:119]
	v_mfma_f32_16x16x32_bf16 v[112:115], v[234:237], v[186:189], v[112:115]
	v_mfma_f32_16x16x32_bf16 v[100:103], v[226:229], v[194:197], v[100:103]
	v_mfma_f32_16x16x32_bf16 v[96:99], v[234:237], v[194:197], v[96:99]
	v_mfma_f32_16x16x32_bf16 v[84:87], v[226:229], v[202:205], v[84:87]
	v_mfma_f32_16x16x32_bf16 v[80:83], v[234:237], v[202:205], v[80:83]
	v_mfma_f32_16x16x32_bf16 v[68:71], v[226:229], v[210:213], v[68:71]
	v_mfma_f32_16x16x32_bf16 v[64:67], v[234:237], v[210:213], v[64:67]
	v_mfma_f32_16x16x32_bf16 v[116:119], v[230:233], v[190:193], v[116:119]
	s_mov_b32 m0, s34
	v_mfma_f32_16x16x32_bf16 v[112:115], v[238:241], v[190:193], v[112:115]
	v_lshl_add_u64 v[154:155], v[220:221], 0, s[94:95]
	v_mfma_f32_16x16x32_bf16 v[100:103], v[230:233], v[198:201], v[100:103]
	v_mfma_f32_16x16x32_bf16 v[96:99], v[238:241], v[198:201], v[96:99]
	v_mfma_f32_16x16x32_bf16 v[84:87], v[230:233], v[206:209], v[84:87]
	v_mfma_f32_16x16x32_bf16 v[80:83], v[238:241], v[206:209], v[80:83]
	v_mfma_f32_16x16x32_bf16 v[68:71], v[230:233], v[214:217], v[68:71]
	s_setprio 0
	v_mfma_f32_16x16x32_bf16 v[64:67], v[238:241], v[214:217], v[64:67]
	s_barrier
	ds_read_b128 v[186:189], v137 offset:49152
	ds_read_b128 v[190:193], v137 offset:50176
	ds_read_b128 v[194:197], v137 offset:51200
	ds_read_b128 v[198:201], v137 offset:52224
	ds_read_b128 v[202:205], v137 offset:53248
	ds_read_b128 v[206:209], v137 offset:54272
	ds_read_b128 v[210:213], v137 offset:55296
	ds_read_b128 v[214:217], v137 offset:56320
	global_load_lds_dwordx4 v[154:155], off
	s_add_i32 m0, s35, 0xffffff80
	s_nop 0
	global_load_lds_dwordx4 v128, s[100:101] offset:128
	s_waitcnt lgkmcnt(0)
	s_setprio 1
	s_barrier
; #define PG8_STAGE(bufoff, gbase) do { _Pragma("unroll") for (int _i = 0; _i < 2; ++_i) \
;         __builtin_amdgcn_global_load_lds((const unsigned*)((const char*)(gbase) + voff[_i]), (LAS unsigned*)(lds + (bufoff) + ldsw + _i * 8192), 16, 0, 0); } while (0)
; #define PG8_MMA(ai, bj, At, Bt) do { __builtin_amdgcn_s_setprio(1); _Pragma("unroll") for (int m = 0; m < 4; ++m) _Pragma("unroll") for (int n = 0; n < 2; ++n) _Pragma("unroll") for (int k = 0; k < 2; ++k) \
;         acc[ai][bj][m][n] = __builtin_amdgcn_mfma_f32_16x16x32_bf16(Bt[n][k], At[m][k], acc[ai][bj][m][n], 0, 0, 0); __builtin_amdgcn_s_setprio(0); } while (0)
; #define PG8_WAIT_V(n) asm volatile("s_waitcnt vmcnt(" #n ")" ::: "memory")
; #define PG8_BAR __builtin_amdgcn_s_barrier()
; template <class Epi>
; DI void gemm_phase(LAS unsigned char* lds, const Gemm g, const StaticOrder& S, const Epi& E) {
;     ...
;             PG8_STAGE(PG8_SB(1, 1), b3 + hstep);
;             PG8_WAIT_V(6); PG8_BAR; PG8_MMA(1, 1, At, B1); PG8_BAR;
;     DI void operator()(const f32x4 (&acc)[2][2][4][2], const Unit& u, int wr, int wc, int fr, int fq) const {
;         const int row0 = u.pm * BM + wr * 64 + fr, col0 = u.pn * HALF + wc * 32 + 8 * fq;
; #pragma unroll
;         for (int ai = 0; ai < 2; ++ai)
; #pragma unroll
;             for (int m = 0; m < 4; ++m) { float hv[8];
; #pragma unroll
;                 for (int n = 0; n < 2; ++n)
; #pragma unroll
;                     for (int e = 0; e < 4; ++e) { const float gt = acc[ai][0][m][n][e], up = acc[ai][1][m][n][e];
;                         hv[n * 4 + e] = gt * __builtin_amdgcn_rcpf(1.f + __builtin_amdgcn_exp2f(-1.4426950408889634f * gt)) * up; }
;                 *(u32x4*)(H + (size_t)(row0 + ai * HALF + m * 16) * DFF + col0) = (u32x4){pk(hv[0], hv[1]), pk(hv[2], hv[3]), pk(hv[4], hv[5]), pk(hv[6], hv[7])}; }
	v_mfma_f32_16x16x32_bf16 v[60:63], v[138:141], v[186:189], v[60:63]
	v_mfma_f32_16x16x32_bf16 v[56:59], v[146:149], v[186:189], v[56:59]
	v_mfma_f32_16x16x32_bf16 v[44:47], v[138:141], v[194:197], v[44:47]
	v_mfma_f32_16x16x32_bf16 v[40:43], v[146:149], v[194:197], v[40:43]
	v_mfma_f32_16x16x32_bf16 v[28:31], v[138:141], v[202:205], v[28:31]
	v_mfma_f32_16x16x32_bf16 v[24:27], v[146:149], v[202:205], v[24:27]
	v_mfma_f32_16x16x32_bf16 v[12:15], v[138:141], v[210:213], v[12:15]
	v_mfma_f32_16x16x32_bf16 v[8:11], v[146:149], v[210:213], v[8:11]
	v_mfma_f32_16x16x32_bf16 v[60:63], v[142:145], v[190:193], v[60:63]
	v_mfma_f32_16x16x32_bf16 v[56:59], v[150:153], v[190:193], v[56:59]
	v_mfma_f32_16x16x32_bf16 v[44:47], v[142:145], v[198:201], v[44:47]
	v_mfma_f32_16x16x32_bf16 v[40:43], v[150:153], v[198:201], v[40:43]
	v_mfma_f32_16x16x32_bf16 v[28:31], v[142:145], v[206:209], v[28:31]
	v_mfma_f32_16x16x32_bf16 v[24:27], v[150:153], v[206:209], v[24:27]
	v_mfma_f32_16x16x32_bf16 v[12:15], v[142:145], v[214:217], v[12:15]
	s_setprio 0
	v_mfma_f32_16x16x32_bf16 v[8:11], v[150:153], v[214:217], v[8:11]
	s_barrier
	s_add_u32 s20, s20, 0x80080
	s_addc_u32 s21, s21, 0
	s_add_i32 s22, s22, s27
	s_mov_b32 m0, s22
	s_nop 0
	global_load_lds_dwordx4 v158, s[20:21]
	s_add_i32 m0, s22, 0x2000
	s_nop 0
	global_load_lds_dwordx4 v128, s[20:21]
	s_waitcnt vmcnt(6)
	s_setprio 1
	s_barrier
	v_mfma_f32_16x16x32_bf16 v[52:55], v[226:229], v[186:189], v[52:55]
	v_mfma_f32_16x16x32_bf16 v[48:51], v[234:237], v[186:189], v[48:51]
	v_mfma_f32_16x16x32_bf16 v[36:39], v[226:229], v[194:197], v[36:39]
	v_mfma_f32_16x16x32_bf16 v[32:35], v[234:237], v[194:197], v[32:35]
	v_mfma_f32_16x16x32_bf16 v[20:23], v[226:229], v[202:205], v[20:23]
	v_mfma_f32_16x16x32_bf16 v[16:19], v[234:237], v[202:205], v[16:19]
	v_mfma_f32_16x16x32_bf16 v[4:7], v[226:229], v[210:213], v[4:7]
	v_mfma_f32_16x16x32_bf16 v[0:3], v[234:237], v[210:213], v[0:3]
	v_mfma_f32_16x16x32_bf16 v[52:55], v[230:233], v[190:193], v[52:55]
	s_add_i32 s38, s38, 2
	v_mfma_f32_16x16x32_bf16 v[48:51], v[238:241], v[190:193], v[48:51]
	s_add_u32 s18, s18, 0x100
	v_mfma_f32_16x16x32_bf16 v[36:39], v[230:233], v[198:201], v[36:39]
	s_addc_u32 s19, s19, 0
	v_mfma_f32_16x16x32_bf16 v[32:35], v[238:241], v[198:201], v[32:35]
	s_add_u32 s33, s33, 0x100
	v_mfma_f32_16x16x32_bf16 v[20:23], v[230:233], v[206:209], v[20:23]
	s_addc_u32 s37, s37, 0
	v_mfma_f32_16x16x32_bf16 v[16:19], v[238:241], v[206:209], v[16:19]
	s_cmp_gt_u32 s38, 29
	v_mfma_f32_16x16x32_bf16 v[4:7], v[230:233], v[214:217], v[4:7]
	s_setprio 0
	v_mfma_f32_16x16x32_bf16 v[0:3], v[238:241], v[214:217], v[0:3]
	s_barrier
	s_cbranch_scc0 .LBB0_37
	v_mul_f32_e32 v139, 0xbfb8aa3b, v124
	v_exp_f32_e32 v139, v139
	v_lshl_or_b32 v140, s2, 7, v136
	v_lshl_add_u32 v138, s3, 8, v134
	v_ashrrev_i32_e32 v141, 31, v140
	v_add_f32_e32 v139, 1.0, v139
	v_rcp_f32_e32 v142, v139
	v_mul_f32_e32 v139, 0xbfb8aa3b, v125
	v_exp_f32_e32 v139, v139
	s_movk_i32 s4, 0x2c00
	s_and_b64 vcc, exec, s[6:7]
	s_mov_b64 s[20:21], s[16:17]
	v_add_f32_e32 v139, 1.0, v139
	v_rcp_f32_e32 v143, v139
	v_mul_f32_e32 v139, 0xbfb8aa3b, v126
	v_exp_f32_e32 v139, v139
	s_mov_b64 s[18:19], s[14:15]
	v_pk_mul_f32 v[124:125], v[124:125], v[142:143]
	v_add_f32_e32 v139, 1.0, v139
	v_rcp_f32_e32 v144, v139
	v_mul_f32_e32 v139, 0xbfb8aa3b, v127
	v_exp_f32_e32 v139, v139
	v_pk_mul_f32 v[116:117], v[124:125], v[116:117]
	v_add_f32_e32 v139, 1.0, v139
	v_rcp_f32_e32 v145, v139
	v_mul_f32_e32 v139, 0xbfb8aa3b, v120
	v_exp_f32_e32 v139, v139
	v_cvt_pk_bf16_f32 v116, v116, v117
	v_pk_mul_f32 v[124:125], v[126:127], v[144:145]
	v_add_f32_e32 v139, 1.0, v139
	v_rcp_f32_e32 v146, v139
	v_mul_f32_e32 v139, 0xbfb8aa3b, v121
	v_exp_f32_e32 v139, v139
	v_pk_mul_f32 v[118:119], v[124:125], v[118:119]
	v_add_f32_e32 v139, 1.0, v139
	v_rcp_f32_e32 v147, v139
	v_mul_f32_e32 v139, 0xbfb8aa3b, v122
	v_exp_f32_e32 v139, v139
	v_cvt_pk_bf16_f32 v117, v118, v119
	v_pk_mul_f32 v[118:119], v[120:121], v[146:147]
	v_add_f32_e32 v139, 1.0, v139
	v_rcp_f32_e32 v148, v139
	v_mul_f32_e32 v139, 0xbfb8aa3b, v123
	v_exp_f32_e32 v139, v139
	v_pk_mul_f32 v[112:113], v[118:119], v[112:113]
	v_add_f32_e32 v139, 1.0, v139
	v_rcp_f32_e32 v149, v139
	v_cvt_pk_bf16_f32 v118, v112, v113
	v_pk_mul_f32 v[112:113], v[122:123], v[148:149]
	s_nop 0
	v_pk_mul_f32 v[112:113], v[112:113], v[114:115]
	v_lshlrev_b64 v[114:115], 1, v[140:141]
	v_cvt_pk_bf16_f32 v119, v112, v113
	v_mov_b64_e32 v[112:113], s[54:55]
	v_mad_i64_i32 v[120:121], s[2:3], v138, s4, v[112:113]
	v_lshl_add_u64 v[120:121], v[120:121], 0, v[114:115]
	global_store_dwordx4 v[120:121], v[116:119], off
	v_mul_f32_e32 v120, 0xbfb8aa3b, v104
	v_mul_f32_e32 v121, 0xbfb8aa3b, v105
	v_mul_f32_e32 v116, 0xbfb8aa3b, v108
	v_mul_f32_e32 v117, 0xbfb8aa3b, v109
	v_exp_f32_e32 v116, v116
	v_exp_f32_e32 v117, v117
	v_mul_f32_e32 v118, 0xbfb8aa3b, v110
	v_mul_f32_e32 v119, 0xbfb8aa3b, v111
	v_exp_f32_e32 v118, v118
	v_exp_f32_e32 v119, v119
	v_exp_f32_e32 v120, v120
	v_exp_f32_e32 v121, v121
	v_add_f32_e32 v116, 1.0, v116
	v_add_f32_e32 v117, 1.0, v117
	v_mul_f32_e32 v122, 0xbfb8aa3b, v106
	v_mul_f32_e32 v123, 0xbfb8aa3b, v107
	v_rcp_f32_e32 v116, v116
	v_rcp_f32_e32 v117, v117
	v_add_f32_e32 v118, 1.0, v118
	v_add_f32_e32 v119, 1.0, v119
	v_exp_f32_e32 v122, v122
	v_exp_f32_e32 v123, v123
	v_rcp_f32_e32 v118, v118
	v_rcp_f32_e32 v119, v119
	v_add_f32_e32 v120, 1.0, v120
	v_add_f32_e32 v121, 1.0, v121
	v_rcp_f32_e32 v120, v120
	v_rcp_f32_e32 v121, v121
	v_add_f32_e32 v122, 1.0, v122
	v_add_f32_e32 v123, 1.0, v123
	v_pk_mul_f32 v[108:109], v[108:109], v[116:117]
	v_rcp_f32_e32 v122, v122
;     DI void operator()(const f32x4 (&acc)[2][2][4][2], const Unit& u, int wr, int wc, int fr, int fq) const {
;     ...
;             for (int m = 0; m < 4; ++m) { float hv[8];
; #pragma unroll
;                 for (int n = 0; n < 2; ++n)
; #pragma unroll
;                     for (int e = 0; e < 4; ++e) { const float gt = acc[ai][0][m][n][e], up = acc[ai][1][m][n][e];
;                         hv[n * 4 + e] = gt * __builtin_amdgcn_rcpf(1.f + __builtin_amdgcn_exp2f(-1.4426950408889634f * gt)) * up; }
;                 *(u32x4*)(H + (size_t)(row0 + ai * HALF + m * 16) * DFF + col0) = (u32x4){pk(hv[0], hv[1]), pk(hv[2], hv[3]), pk(hv[4], hv[5]), pk(hv[6], hv[7])}; }
	v_rcp_f32_e32 v123, v123
	v_pk_mul_f32 v[100:101], v[108:109], v[100:101]
	v_pk_mul_f32 v[108:109], v[110:111], v[118:119]
	v_cvt_pk_bf16_f32 v100, v100, v101
	v_pk_mul_f32 v[102:103], v[108:109], v[102:103]
	s_nop 0
	v_cvt_pk_bf16_f32 v101, v102, v103
	v_pk_mul_f32 v[102:103], v[104:105], v[120:121]
	s_nop 0
	v_pk_mul_f32 v[96:97], v[102:103], v[96:97]
	s_nop 0
	v_cvt_pk_bf16_f32 v102, v96, v97
	v_pk_mul_f32 v[96:97], v[106:107], v[122:123]
	s_nop 0
	v_pk_mul_f32 v[96:97], v[96:97], v[98:99]
	v_mul_f32_e32 v98, 0xbfb8aa3b, v94
	v_cvt_pk_bf16_f32 v103, v96, v97
	v_or_b32_e32 v96, 16, v138
	v_mad_i64_i32 v[96:97], s[2:3], v96, s4, v[112:113]
	v_lshl_add_u64 v[96:97], v[96:97], 0, v[114:115]
	global_store_dwordx4 v[96:97], v[100:103], off
	v_mul_f32_e32 v96, 0xbfb8aa3b, v92
	v_mul_f32_e32 v97, 0xbfb8aa3b, v93
	v_exp_f32_e32 v96, v96
	v_exp_f32_e32 v97, v97
	v_mul_f32_e32 v99, 0xbfb8aa3b, v95
	v_exp_f32_e32 v98, v98
	v_exp_f32_e32 v99, v99
	v_mul_f32_e32 v100, 0xbfb8aa3b, v88
	v_mul_f32_e32 v101, 0xbfb8aa3b, v89
	v_exp_f32_e32 v100, v100
	v_exp_f32_e32 v101, v101
	v_add_f32_e32 v96, 1.0, v96
	v_add_f32_e32 v97, 1.0, v97
	v_mul_f32_e32 v102, 0xbfb8aa3b, v90
	v_mul_f32_e32 v103, 0xbfb8aa3b, v91
	v_rcp_f32_e32 v96, v96
	v_rcp_f32_e32 v97, v97
	v_add_f32_e32 v98, 1.0, v98
	v_add_f32_e32 v99, 1.0, v99
	v_exp_f32_e32 v102, v102
	v_exp_f32_e32 v103, v103
	v_rcp_f32_e32 v98, v98
	v_rcp_f32_e32 v99, v99
	v_add_f32_e32 v100, 1.0, v100
	v_add_f32_e32 v101, 1.0, v101
	v_rcp_f32_e32 v100, v100
	v_rcp_f32_e32 v101, v101
	v_add_f32_e32 v102, 1.0, v102
	v_add_f32_e32 v103, 1.0, v103
	v_pk_mul_f32 v[92:93], v[92:93], v[96:97]
	v_rcp_f32_e32 v102, v102
	v_rcp_f32_e32 v103, v103
	v_pk_mul_f32 v[84:85], v[92:93], v[84:85]
	v_pk_mul_f32 v[92:93], v[94:95], v[98:99]
	v_cvt_pk_bf16_f32 v84, v84, v85
	v_pk_mul_f32 v[86:87], v[92:93], v[86:87]
	s_nop 0
	v_cvt_pk_bf16_f32 v85, v86, v87
	v_pk_mul_f32 v[86:87], v[88:89], v[100:101]
	s_nop 0
	v_pk_mul_f32 v[80:81], v[86:87], v[80:81]
	s_nop 0
	v_cvt_pk_bf16_f32 v86, v80, v81
	v_pk_mul_f32 v[80:81], v[90:91], v[102:103]
	s_nop 0
	v_pk_mul_f32 v[80:81], v[80:81], v[82:83]
	v_mul_f32_e32 v82, 0xbfb8aa3b, v78
	v_cvt_pk_bf16_f32 v87, v80, v81
	v_or_b32_e32 v80, 32, v138
	v_mad_i64_i32 v[80:81], s[2:3], v80, s4, v[112:113]
	v_lshl_add_u64 v[80:81], v[80:81], 0, v[114:115]
	global_store_dwordx4 v[80:81], v[84:87], off
	v_mul_f32_e32 v80, 0xbfb8aa3b, v76
	v_mul_f32_e32 v81, 0xbfb8aa3b, v77
	v_exp_f32_e32 v80, v80
	v_exp_f32_e32 v81, v81
	v_mul_f32_e32 v83, 0xbfb8aa3b, v79
	v_exp_f32_e32 v82, v82
	v_exp_f32_e32 v83, v83
	v_mul_f32_e32 v84, 0xbfb8aa3b, v72
	v_mul_f32_e32 v85, 0xbfb8aa3b, v73
	v_exp_f32_e32 v84, v84
	v_exp_f32_e32 v85, v85
	v_add_f32_e32 v80, 1.0, v80
	v_add_f32_e32 v81, 1.0, v81
	v_mul_f32_e32 v86, 0xbfb8aa3b, v74
	v_mul_f32_e32 v87, 0xbfb8aa3b, v75
	v_rcp_f32_e32 v80, v80
	v_rcp_f32_e32 v81, v81
	v_add_f32_e32 v82, 1.0, v82
	v_add_f32_e32 v83, 1.0, v83
	v_exp_f32_e32 v86, v86
	v_exp_f32_e32 v87, v87
	v_rcp_f32_e32 v82, v82
	v_rcp_f32_e32 v83, v83
	v_add_f32_e32 v84, 1.0, v84
	v_add_f32_e32 v85, 1.0, v85
	v_rcp_f32_e32 v84, v84
	v_rcp_f32_e32 v85, v85
	v_add_f32_e32 v86, 1.0, v86
	v_add_f32_e32 v87, 1.0, v87
	v_pk_mul_f32 v[76:77], v[76:77], v[80:81]
	v_rcp_f32_e32 v86, v86
	v_rcp_f32_e32 v87, v87
	v_pk_mul_f32 v[68:69], v[76:77], v[68:69]
	v_pk_mul_f32 v[76:77], v[78:79], v[82:83]
	v_cvt_pk_bf16_f32 v68, v68, v69
	v_pk_mul_f32 v[70:71], v[76:77], v[70:71]
	s_nop 0
	v_cvt_pk_bf16_f32 v69, v70, v71
	v_pk_mul_f32 v[70:71], v[72:73], v[84:85]
	v_add_u32_e32 v72, 0x80, v138
	v_pk_mul_f32 v[64:65], v[70:71], v[64:65]
	s_nop 0
	v_cvt_pk_bf16_f32 v70, v64, v65
	v_pk_mul_f32 v[64:65], v[74:75], v[86:87]
	s_nop 0
	v_pk_mul_f32 v[64:65], v[64:65], v[66:67]
	v_mul_f32_e32 v66, 0xbfb8aa3b, v62
	v_cvt_pk_bf16_f32 v71, v64, v65
	v_or_b32_e32 v64, 48, v138
	v_mad_i64_i32 v[64:65], s[2:3], v64, s4, v[112:113]
	v_lshl_add_u64 v[64:65], v[64:65], 0, v[114:115]
	global_store_dwordx4 v[64:65], v[68:71], off
	v_mul_f32_e32 v64, 0xbfb8aa3b, v60
	v_mul_f32_e32 v65, 0xbfb8aa3b, v61
	v_exp_f32_e32 v64, v64
	v_exp_f32_e32 v65, v65
	v_mul_f32_e32 v67, 0xbfb8aa3b, v63
	v_exp_f32_e32 v66, v66
	v_exp_f32_e32 v67, v67
	v_mul_f32_e32 v68, 0xbfb8aa3b, v56
	v_mul_f32_e32 v69, 0xbfb8aa3b, v57
	v_exp_f32_e32 v68, v68
	v_exp_f32_e32 v69, v69
	v_add_f32_e32 v64, 1.0, v64
	v_add_f32_e32 v65, 1.0, v65
	v_mul_f32_e32 v70, 0xbfb8aa3b, v58
	v_mul_f32_e32 v71, 0xbfb8aa3b, v59
	v_rcp_f32_e32 v64, v64
	v_rcp_f32_e32 v65, v65
	v_add_f32_e32 v66, 1.0, v66
	v_add_f32_e32 v67, 1.0, v67
	v_exp_f32_e32 v70, v70
	v_exp_f32_e32 v71, v71
	v_rcp_f32_e32 v66, v66
	v_rcp_f32_e32 v67, v67
	v_add_f32_e32 v68, 1.0, v68
	v_add_f32_e32 v69, 1.0, v69
	v_rcp_f32_e32 v68, v68
	v_rcp_f32_e32 v69, v69
	v_add_f32_e32 v70, 1.0, v70
	v_add_f32_e32 v71, 1.0, v71
	v_pk_mul_f32 v[60:61], v[60:61], v[64:65]
	v_rcp_f32_e32 v70, v70
	v_rcp_f32_e32 v71, v71
	v_pk_mul_f32 v[52:53], v[60:61], v[52:53]
	v_pk_mul_f32 v[60:61], v[62:63], v[66:67]
	v_cvt_pk_bf16_f32 v52, v52, v53
	v_pk_mul_f32 v[54:55], v[60:61], v[54:55]
	s_nop 0
	v_cvt_pk_bf16_f32 v53, v54, v55
	v_pk_mul_f32 v[54:55], v[56:57], v[68:69]
	s_nop 0
	v_pk_mul_f32 v[48:49], v[54:55], v[48:49]
; #define PG8_WAIT_V(n) asm volatile("s_waitcnt vmcnt(" #n ")" ::: "memory")
; #define PG8_BAR __builtin_amdgcn_s_barrier()
; template <class Epi>
; DI void gemm_phase(LAS unsigned char* lds, const Gemm g, const StaticOrder& S, const Epi& E) {
;     ...
;     PG8_WAIT_V(0);
;     if (wr == 0) PG8_BAR;
;     DI void operator()(const f32x4 (&acc)[2][2][4][2], const Unit& u, int wr, int wc, int fr, int fq) const {
;     ...
;             for (int m = 0; m < 4; ++m) { float hv[8];
; #pragma unroll
;                 for (int n = 0; n < 2; ++n)
; #pragma unroll
;                     for (int e = 0; e < 4; ++e) { const float gt = acc[ai][0][m][n][e], up = acc[ai][1][m][n][e];
;                         hv[n * 4 + e] = gt * __builtin_amdgcn_rcpf(1.f + __builtin_amdgcn_exp2f(-1.4426950408889634f * gt)) * up; }
;                 *(u32x4*)(H + (size_t)(row0 + ai * HALF + m * 16) * DFF + col0) = (u32x4){pk(hv[0], hv[1]), pk(hv[2], hv[3]), pk(hv[4], hv[5]), pk(hv[6], hv[7])}; }
	s_nop 0
	v_cvt_pk_bf16_f32 v54, v48, v49
	v_pk_mul_f32 v[48:49], v[58:59], v[70:71]
	s_nop 0
	v_pk_mul_f32 v[48:49], v[48:49], v[50:51]
	v_mul_f32_e32 v50, 0xbfb8aa3b, v46
	v_cvt_pk_bf16_f32 v55, v48, v49
	v_mad_i64_i32 v[48:49], s[2:3], v72, s4, v[112:113]
	v_lshl_add_u64 v[48:49], v[48:49], 0, v[114:115]
	global_store_dwordx4 v[48:49], v[52:55], off
	v_mul_f32_e32 v48, 0xbfb8aa3b, v44
	v_mul_f32_e32 v49, 0xbfb8aa3b, v45
	v_exp_f32_e32 v48, v48
	v_exp_f32_e32 v49, v49
	v_mul_f32_e32 v51, 0xbfb8aa3b, v47
	v_exp_f32_e32 v50, v50
	v_exp_f32_e32 v51, v51
	v_mul_f32_e32 v52, 0xbfb8aa3b, v40
	v_mul_f32_e32 v53, 0xbfb8aa3b, v41
	v_exp_f32_e32 v52, v52
	v_exp_f32_e32 v53, v53
	v_add_f32_e32 v48, 1.0, v48
	v_add_f32_e32 v49, 1.0, v49
	v_mul_f32_e32 v54, 0xbfb8aa3b, v42
	v_mul_f32_e32 v55, 0xbfb8aa3b, v43
	v_rcp_f32_e32 v48, v48
	v_rcp_f32_e32 v49, v49
	v_add_f32_e32 v50, 1.0, v50
	v_add_f32_e32 v51, 1.0, v51
	v_exp_f32_e32 v54, v54
	v_exp_f32_e32 v55, v55
	v_rcp_f32_e32 v50, v50
	v_rcp_f32_e32 v51, v51
	v_add_f32_e32 v52, 1.0, v52
	v_add_f32_e32 v53, 1.0, v53
	v_rcp_f32_e32 v52, v52
	v_rcp_f32_e32 v53, v53
	v_add_f32_e32 v54, 1.0, v54
	v_add_f32_e32 v55, 1.0, v55
	v_pk_mul_f32 v[44:45], v[44:45], v[48:49]
	v_rcp_f32_e32 v54, v54
	v_rcp_f32_e32 v55, v55
	v_pk_mul_f32 v[36:37], v[44:45], v[36:37]
	v_pk_mul_f32 v[44:45], v[46:47], v[50:51]
	v_cvt_pk_bf16_f32 v36, v36, v37
	v_pk_mul_f32 v[38:39], v[44:45], v[38:39]
	s_nop 0
	v_cvt_pk_bf16_f32 v37, v38, v39
	v_pk_mul_f32 v[38:39], v[40:41], v[52:53]
	s_nop 0
	v_pk_mul_f32 v[32:33], v[38:39], v[32:33]
	s_nop 0
	v_cvt_pk_bf16_f32 v38, v32, v33
	v_pk_mul_f32 v[32:33], v[42:43], v[54:55]
	s_nop 0
	v_pk_mul_f32 v[32:33], v[32:33], v[34:35]
	v_mul_f32_e32 v34, 0xbfb8aa3b, v30
	v_cvt_pk_bf16_f32 v39, v32, v33
	v_add_u32_e32 v32, 0x90, v138
	v_mad_i64_i32 v[32:33], s[2:3], v32, s4, v[112:113]
	v_lshl_add_u64 v[32:33], v[32:33], 0, v[114:115]
	global_store_dwordx4 v[32:33], v[36:39], off
	v_mul_f32_e32 v32, 0xbfb8aa3b, v28
	v_mul_f32_e32 v33, 0xbfb8aa3b, v29
	v_exp_f32_e32 v32, v32
	v_exp_f32_e32 v33, v33
	v_mul_f32_e32 v35, 0xbfb8aa3b, v31
	v_exp_f32_e32 v34, v34
	v_exp_f32_e32 v35, v35
	v_mul_f32_e32 v36, 0xbfb8aa3b, v24
	v_mul_f32_e32 v37, 0xbfb8aa3b, v25
	v_exp_f32_e32 v36, v36
	v_exp_f32_e32 v37, v37
	v_add_f32_e32 v32, 1.0, v32
	v_add_f32_e32 v33, 1.0, v33
	v_mul_f32_e32 v38, 0xbfb8aa3b, v26
	v_mul_f32_e32 v39, 0xbfb8aa3b, v27
	v_rcp_f32_e32 v32, v32
	v_rcp_f32_e32 v33, v33
	v_add_f32_e32 v34, 1.0, v34
	v_add_f32_e32 v35, 1.0, v35
	v_exp_f32_e32 v38, v38
	v_exp_f32_e32 v39, v39
	v_rcp_f32_e32 v34, v34
	v_rcp_f32_e32 v35, v35
	v_add_f32_e32 v36, 1.0, v36
	v_add_f32_e32 v37, 1.0, v37
	v_rcp_f32_e32 v36, v36
	v_rcp_f32_e32 v37, v37
	v_add_f32_e32 v38, 1.0, v38
	v_add_f32_e32 v39, 1.0, v39
	v_pk_mul_f32 v[28:29], v[28:29], v[32:33]
	v_rcp_f32_e32 v38, v38
	v_rcp_f32_e32 v39, v39
	v_pk_mul_f32 v[20:21], v[28:29], v[20:21]
	v_pk_mul_f32 v[28:29], v[30:31], v[34:35]
	v_cvt_pk_bf16_f32 v20, v20, v21
	v_pk_mul_f32 v[22:23], v[28:29], v[22:23]
	s_nop 0
	v_cvt_pk_bf16_f32 v21, v22, v23
	v_pk_mul_f32 v[22:23], v[24:25], v[36:37]
	s_nop 0
	v_pk_mul_f32 v[16:17], v[22:23], v[16:17]
	s_nop 0
	v_cvt_pk_bf16_f32 v22, v16, v17
	v_pk_mul_f32 v[16:17], v[26:27], v[38:39]
	s_nop 0
	v_pk_mul_f32 v[16:17], v[16:17], v[18:19]
	v_mul_f32_e32 v18, 0xbfb8aa3b, v14
	v_cvt_pk_bf16_f32 v23, v16, v17
	v_add_u32_e32 v16, 0xa0, v138
	v_mad_i64_i32 v[16:17], s[2:3], v16, s4, v[112:113]
	v_lshl_add_u64 v[16:17], v[16:17], 0, v[114:115]
	global_store_dwordx4 v[16:17], v[20:23], off
	v_mul_f32_e32 v16, 0xbfb8aa3b, v12
	v_mul_f32_e32 v17, 0xbfb8aa3b, v13
	v_exp_f32_e32 v16, v16
	v_exp_f32_e32 v17, v17
	v_mul_f32_e32 v19, 0xbfb8aa3b, v15
	v_exp_f32_e32 v18, v18
	v_exp_f32_e32 v19, v19
	v_mul_f32_e32 v20, 0xbfb8aa3b, v8
	v_mul_f32_e32 v21, 0xbfb8aa3b, v9
	v_exp_f32_e32 v20, v20
	v_exp_f32_e32 v21, v21
	v_add_f32_e32 v16, 1.0, v16
	v_add_f32_e32 v17, 1.0, v17
	v_mul_f32_e32 v22, 0xbfb8aa3b, v10
	v_mul_f32_e32 v23, 0xbfb8aa3b, v11
	v_rcp_f32_e32 v16, v16
	v_rcp_f32_e32 v17, v17
	v_add_f32_e32 v18, 1.0, v18
	v_add_f32_e32 v19, 1.0, v19
	v_exp_f32_e32 v22, v22
	v_exp_f32_e32 v23, v23
	v_rcp_f32_e32 v18, v18
	v_rcp_f32_e32 v19, v19
	v_add_f32_e32 v20, 1.0, v20
	v_add_f32_e32 v21, 1.0, v21
	v_rcp_f32_e32 v20, v20
	v_rcp_f32_e32 v21, v21
	v_add_f32_e32 v22, 1.0, v22
	v_add_f32_e32 v23, 1.0, v23
	v_pk_mul_f32 v[12:13], v[12:13], v[16:17]
	v_rcp_f32_e32 v22, v22
	v_rcp_f32_e32 v23, v23
	v_pk_mul_f32 v[4:5], v[12:13], v[4:5]
	v_pk_mul_f32 v[12:13], v[14:15], v[18:19]
	v_cvt_pk_bf16_f32 v4, v4, v5
	v_pk_mul_f32 v[6:7], v[12:13], v[6:7]
	s_nop 0
	v_cvt_pk_bf16_f32 v5, v6, v7
	v_pk_mul_f32 v[6:7], v[8:9], v[20:21]
	s_nop 0
	v_pk_mul_f32 v[0:1], v[6:7], v[0:1]
	s_nop 0
	v_cvt_pk_bf16_f32 v6, v0, v1
	v_pk_mul_f32 v[0:1], v[10:11], v[22:23]
	s_nop 0
	v_pk_mul_f32 v[0:1], v[0:1], v[2:3]
	s_nop 0
	v_cvt_pk_bf16_f32 v7, v0, v1
	v_add_u32_e32 v0, 0xb0, v138
	v_mad_i64_i32 v[0:1], s[2:3], v0, s4, v[112:113]
	v_lshl_add_u64 v[0:1], v[0:1], 0, v[114:115]
	s_mov_b32 s2, s8
	s_mov_b32 s3, s10
	global_store_dwordx4 v[0:1], v[4:7], off
	s_cbranch_vccz .LBB0_34
	s_waitcnt vmcnt(0)
	s_cmpk_gt_u32 s24, 0xff
	s_cbranch_scc1 .LBB0_41
	s_barrier

; #define PG8_STAGE(bufoff, gbase) do { _Pragma("unroll") for (int _i = 0; _i < 2; ++_i) \
;         __builtin_amdgcn_global_load_lds((const unsigned*)((const char*)(gbase) + voff[_i]), (LAS unsigned*)(lds + (bufoff) + ldsw + _i * 8192), 16, 0, 0); } while (0)
; #define PG8_LDA(dst, b, h) do { _Pragma("unroll") for (int m = 0; m < 4; ++m) _Pragma("unroll") for (int k = 0; k < 2; ++k) dst[m][k] = *(const LAS bf16x8*)(lds + PG8_SA(b, h) + aoff + m * 2048 + k * 1024); } while (0)
; #define PG8_LDB(dst, b, h) do { _Pragma("unroll") for (int n = 0; n < 2; ++n) _Pragma("unroll") for (int k = 0; k < 2; ++k) dst[n][k] = *(const LAS bf16x8*)(lds + PG8_SB(b, h) + boff + n * 2048 + k * 1024); } while (0)
; #define PG8_MMA(ai, bj, At, Bt) do { __builtin_amdgcn_s_setprio(1); _Pragma("unroll") for (int m = 0; m < 4; ++m) _Pragma("unroll") for (int n = 0; n < 2; ++n) _Pragma("unroll") for (int k = 0; k < 2; ++k) \
;         acc[ai][bj][m][n] = __builtin_amdgcn_mfma_f32_16x16x32_bf16(Bt[n][k], At[m][k], acc[ai][bj][m][n], 0, 0, 0); __builtin_amdgcn_s_setprio(0); } while (0)
; #define PG8_WAIT_V(n) asm volatile("s_waitcnt vmcnt(" #n ")" ::: "memory")
; #define PG8_WAIT_L(n) asm volatile("s_waitcnt lgkmcnt(" #n ")" ::: "memory")
; #define PG8_BAR __builtin_amdgcn_s_barrier()
; #define PG8_SCHED __builtin_amdgcn_sched_barrier(0)
; template <class Epi>
; DI void gemm_phase(LAS unsigned char* lds, const Gemm g, const StaticOrder& S, const Epi& E) {
;     ...
;             PG8_LDB(B0, 0, 0); PG8_SCHED; PG8_LDA(At, 0, 0); PG8_STAGE(PG8_SA(1, 1), a1 + hstep);
;             PG8_WAIT_L(8); PG8_BAR; PG8_WAIT_L(0); PG8_MMA(0, 0, At, B0); PG8_BAR; PG8_SCHED;
;             PG8_LDB(B1, 0, 1); PG8_STAGE(PG8_SB(0, 0), b2);
;             PG8_BAR; PG8_WAIT_L(0); PG8_MMA(0, 1, At, B1); PG8_BAR;
;             PG8_LDA(At, 0, 1); PG8_STAGE(PG8_SA(0, 0), a2);
;             PG8_BAR; PG8_WAIT_L(0); PG8_MMA(1, 0, At, B0); PG8_BAR; PG8_SCHED;
;             PG8_STAGE(PG8_SB(0, 1), b2 + hstep);
;             PG8_WAIT_V(6); PG8_BAR; PG8_MMA(1, 1, At, B1); PG8_BAR;
.LBB0_77:
	s_add_u32 s22, s20, 0x100
	s_addc_u32 s23, s21, 0
	s_add_i32 s43, 0, 0x10000
	ds_read_b128 v[128:131], v226
	ds_read_b128 v[132:135], v226 offset:1024
	ds_read_b128 v[136:139], v226 offset:2048
	ds_read_b128 v[140:143], v226 offset:3072
	s_cmp_eq_u32 s33, 32
	s_cselect_b32 s27, s9, s23
	s_cselect_b32 s26, s8, s22
	s_cselect_b32 s25, s11, s5
	s_cselect_b32 s24, s10, s4
	v_lshl_add_u64 v[214:215], s[20:21], 0, v[190:191]
	s_add_i32 m0, s34, 0xc000
	ds_read_b128 v[144:147], v228
	ds_read_b128 v[148:151], v228 offset:1024
	ds_read_b128 v[152:155], v228 offset:2048
	ds_read_b128 v[194:197], v228 offset:3072
	ds_read_b128 v[198:201], v228 offset:4096
	ds_read_b128 v[202:205], v228 offset:5120
	ds_read_b128 v[206:209], v228 offset:6144
	ds_read_b128 v[210:213], v228 offset:7168
	global_load_lds_dwordx4 v[214:215], off
	v_lshl_add_u64 v[214:215], s[20:21], 0, v[192:193]
	s_add_i32 m0, s34, 0xe000
	s_nop 0
	global_load_lds_dwordx4 v[214:215], off
	s_waitcnt lgkmcnt(8)
	s_setprio 1
	s_barrier
	s_waitcnt lgkmcnt(0)
	v_mfma_f32_16x16x32_bf16 v[124:127], v[128:131], v[144:147], v[124:127]
	v_mfma_f32_16x16x32_bf16 v[120:123], v[136:139], v[144:147], v[120:123]
	v_mfma_f32_16x16x32_bf16 v[116:119], v[128:131], v[152:155], v[116:119]
	v_mfma_f32_16x16x32_bf16 v[112:115], v[136:139], v[152:155], v[112:115]
	v_mfma_f32_16x16x32_bf16 v[108:111], v[128:131], v[198:201], v[108:111]
	v_mfma_f32_16x16x32_bf16 v[104:107], v[136:139], v[198:201], v[104:107]
	v_mfma_f32_16x16x32_bf16 v[100:103], v[128:131], v[206:209], v[100:103]
	v_mfma_f32_16x16x32_bf16 v[96:99], v[136:139], v[206:209], v[96:99]
	v_mfma_f32_16x16x32_bf16 v[124:127], v[132:135], v[148:151], v[124:127]
	v_mfma_f32_16x16x32_bf16 v[120:123], v[140:143], v[148:151], v[120:123]
	v_mfma_f32_16x16x32_bf16 v[116:119], v[132:135], v[194:197], v[116:119]
	v_mfma_f32_16x16x32_bf16 v[112:115], v[140:143], v[194:197], v[112:115]
	v_mfma_f32_16x16x32_bf16 v[108:111], v[132:135], v[202:205], v[108:111]
	v_mfma_f32_16x16x32_bf16 v[104:107], v[140:143], v[202:205], v[104:107]
	v_mfma_f32_16x16x32_bf16 v[100:103], v[132:135], v[210:213], v[100:103]
	s_setprio 0
	v_mfma_f32_16x16x32_bf16 v[96:99], v[140:143], v[210:213], v[96:99]
	s_barrier
	s_add_i32 s44, 0, 0x14000
	s_add_i32 s20, s43, s31
	s_mov_b32 m0, s20
	ds_read_b128 v[214:217], v226 offset:16384
	ds_read_b128 v[230:233], v226 offset:17408
	ds_read_b128 v[234:237], v226 offset:18432
	ds_read_b128 v[238:241], v226 offset:19456
	global_load_lds_dwordx4 v188, s[24:25]
	s_add_i32 m0, s20, 0x2000
	s_nop 0
	global_load_lds_dwordx4 v186, s[24:25]
	s_waitcnt lgkmcnt(0)
	s_setprio 1
	s_barrier
	v_mfma_f32_16x16x32_bf16 v[60:63], v[214:217], v[144:147], v[60:63]
	v_mfma_f32_16x16x32_bf16 v[56:59], v[234:237], v[144:147], v[56:59]
	v_mfma_f32_16x16x32_bf16 v[52:55], v[214:217], v[152:155], v[52:55]
	v_mfma_f32_16x16x32_bf16 v[48:51], v[234:237], v[152:155], v[48:51]
	v_mfma_f32_16x16x32_bf16 v[44:47], v[214:217], v[198:201], v[44:47]
	v_mfma_f32_16x16x32_bf16 v[40:43], v[234:237], v[198:201], v[40:43]
	v_mfma_f32_16x16x32_bf16 v[36:39], v[214:217], v[206:209], v[36:39]
	v_mfma_f32_16x16x32_bf16 v[32:35], v[234:237], v[206:209], v[32:35]
	v_mfma_f32_16x16x32_bf16 v[60:63], v[230:233], v[148:151], v[60:63]
	s_mov_b32 m0, s34
	v_mfma_f32_16x16x32_bf16 v[56:59], v[238:241], v[148:151], v[56:59]
	v_lshl_add_u64 v[242:243], s[26:27], 0, v[188:189]
	v_mfma_f32_16x16x32_bf16 v[52:55], v[230:233], v[194:197], v[52:55]
	v_mfma_f32_16x16x32_bf16 v[48:51], v[238:241], v[194:197], v[48:51]
	v_mfma_f32_16x16x32_bf16 v[44:47], v[230:233], v[202:205], v[44:47]
	v_mfma_f32_16x16x32_bf16 v[40:43], v[238:241], v[202:205], v[40:43]
	v_mfma_f32_16x16x32_bf16 v[36:39], v[230:233], v[210:213], v[36:39]
	s_setprio 0
	v_mfma_f32_16x16x32_bf16 v[32:35], v[238:241], v[210:213], v[32:35]
	s_barrier
	ds_read_b128 v[144:147], v228 offset:16384
	ds_read_b128 v[148:151], v228 offset:17408
	ds_read_b128 v[152:155], v228 offset:18432
	ds_read_b128 v[194:197], v228 offset:19456
	ds_read_b128 v[198:201], v228 offset:20480
	ds_read_b128 v[202:205], v228 offset:21504
	ds_read_b128 v[206:209], v228 offset:22528
	ds_read_b128 v[210:213], v228 offset:23552
	global_load_lds_dwordx4 v[242:243], off
	s_mov_b64 s[100:101], s[26:27]
	s_mov_b32 m0, s35
	s_nop 0
	global_load_lds_dwordx4 v186, s[26:27]
	s_waitcnt lgkmcnt(0)
	s_setprio 1
	s_barrier
	v_mfma_f32_16x16x32_bf16 v[92:95], v[128:131], v[144:147], v[92:95]
	v_mfma_f32_16x16x32_bf16 v[88:91], v[136:139], v[144:147], v[88:91]
	v_mfma_f32_16x16x32_bf16 v[84:87], v[128:131], v[152:155], v[84:87]
	v_mfma_f32_16x16x32_bf16 v[80:83], v[136:139], v[152:155], v[80:83]
	v_mfma_f32_16x16x32_bf16 v[76:79], v[128:131], v[198:201], v[76:79]
	v_mfma_f32_16x16x32_bf16 v[72:75], v[136:139], v[198:201], v[72:75]
	v_mfma_f32_16x16x32_bf16 v[68:71], v[128:131], v[206:209], v[68:71]
	v_mfma_f32_16x16x32_bf16 v[64:67], v[136:139], v[206:209], v[64:67]
	v_mfma_f32_16x16x32_bf16 v[92:95], v[132:135], v[148:151], v[92:95]
	v_mfma_f32_16x16x32_bf16 v[88:91], v[140:143], v[148:151], v[88:91]
	v_mfma_f32_16x16x32_bf16 v[84:87], v[132:135], v[194:197], v[84:87]
	v_mfma_f32_16x16x32_bf16 v[80:83], v[140:143], v[194:197], v[80:83]
	v_mfma_f32_16x16x32_bf16 v[76:79], v[132:135], v[202:205], v[76:79]
	v_mfma_f32_16x16x32_bf16 v[72:75], v[140:143], v[202:205], v[72:75]
	v_mfma_f32_16x16x32_bf16 v[68:71], v[132:135], v[210:213], v[68:71]
	s_setprio 0
	v_mfma_f32_16x16x32_bf16 v[64:67], v[140:143], v[210:213], v[64:67]
	s_barrier
	s_add_u32 s20, s24, 0x90000
	s_addc_u32 s21, s25, 0
	s_add_i32 s43, s44, s31
	s_mov_b32 m0, s43
	s_nop 0
	global_load_lds_dwordx4 v188, s[20:21]
	s_add_i32 m0, s43, 0x2000
	s_nop 0
	global_load_lds_dwordx4 v186, s[20:21]
	s_waitcnt vmcnt(6)
	s_setprio 1
	s_barrier
; #define PG8_STAGE(bufoff, gbase) do { _Pragma("unroll") for (int _i = 0; _i < 2; ++_i) \
;         __builtin_amdgcn_global_load_lds((const unsigned*)((const char*)(gbase) + voff[_i]), (LAS unsigned*)(lds + (bufoff) + ldsw + _i * 8192), 16, 0, 0); } while (0)
; #define PG8_LDA(dst, b, h) do { _Pragma("unroll") for (int m = 0; m < 4; ++m) _Pragma("unroll") for (int k = 0; k < 2; ++k) dst[m][k] = *(const LAS bf16x8*)(lds + PG8_SA(b, h) + aoff + m * 2048 + k * 1024); } while (0)
; #define PG8_LDB(dst, b, h) do { _Pragma("unroll") for (int n = 0; n < 2; ++n) _Pragma("unroll") for (int k = 0; k < 2; ++k) dst[n][k] = *(const LAS bf16x8*)(lds + PG8_SB(b, h) + boff + n * 2048 + k * 1024); } while (0)
; #define PG8_MMA(ai, bj, At, Bt) do { __builtin_amdgcn_s_setprio(1); _Pragma("unroll") for (int m = 0; m < 4; ++m) _Pragma("unroll") for (int n = 0; n < 2; ++n) _Pragma("unroll") for (int k = 0; k < 2; ++k) \
;         acc[ai][bj][m][n] = __builtin_amdgcn_mfma_f32_16x16x32_bf16(Bt[n][k], At[m][k], acc[ai][bj][m][n], 0, 0, 0); __builtin_amdgcn_s_setprio(0); } while (0)
; #define PG8_WAIT_V(n) asm volatile("s_waitcnt vmcnt(" #n ")" ::: "memory")
; #define PG8_WAIT_L(n) asm volatile("s_waitcnt lgkmcnt(" #n ")" ::: "memory")
; #define PG8_BAR __builtin_amdgcn_s_barrier()
; #define PG8_SCHED __builtin_amdgcn_sched_barrier(0)
; template <class Epi>
; DI void gemm_phase(LAS unsigned char* lds, const Gemm g, const StaticOrder& S, const Epi& E) {
;     ...
;             PG8_WAIT_V(6); PG8_BAR; PG8_MMA(1, 1, At, B1); PG8_BAR;
;             PG8_LDB(B0, 1, 0); PG8_SCHED; PG8_LDA(At, 1, 0); PG8_STAGE(PG8_SA(0, 1), a2 + hstep);
;             PG8_WAIT_L(8); PG8_BAR; PG8_WAIT_L(0); PG8_MMA(0, 0, At, B0); PG8_BAR; PG8_SCHED;
;             PG8_LDB(B1, 1, 1); PG8_STAGE(PG8_SB(1, 0), b3);
;             PG8_BAR; PG8_WAIT_L(0); PG8_MMA(0, 1, At, B1); PG8_BAR;
;             PG8_LDA(At, 1, 1); PG8_STAGE(PG8_SA(1, 0), a3);
;             PG8_BAR; PG8_WAIT_L(0); PG8_MMA(1, 0, At, B0); PG8_BAR; PG8_SCHED;
	v_mfma_f32_16x16x32_bf16 v[28:31], v[214:217], v[144:147], v[28:31]
	v_mfma_f32_16x16x32_bf16 v[24:27], v[234:237], v[144:147], v[24:27]
	v_mfma_f32_16x16x32_bf16 v[20:23], v[214:217], v[152:155], v[20:23]
	v_mfma_f32_16x16x32_bf16 v[16:19], v[234:237], v[152:155], v[16:19]
	v_mfma_f32_16x16x32_bf16 v[12:15], v[214:217], v[198:201], v[12:15]
	v_mfma_f32_16x16x32_bf16 v[8:11], v[234:237], v[198:201], v[8:11]
	v_mfma_f32_16x16x32_bf16 v[4:7], v[214:217], v[206:209], v[4:7]
	v_mfma_f32_16x16x32_bf16 v[0:3], v[234:237], v[206:209], v[0:3]
	v_mfma_f32_16x16x32_bf16 v[28:31], v[230:233], v[148:151], v[28:31]
	s_add_i32 s43, 0, 0x18000
	v_mfma_f32_16x16x32_bf16 v[24:27], v[238:241], v[148:151], v[24:27]
	v_mfma_f32_16x16x32_bf16 v[20:23], v[230:233], v[194:197], v[20:23]
	v_mfma_f32_16x16x32_bf16 v[16:19], v[238:241], v[194:197], v[16:19]
	v_mfma_f32_16x16x32_bf16 v[12:15], v[230:233], v[202:205], v[12:15]
	v_mfma_f32_16x16x32_bf16 v[8:11], v[238:241], v[202:205], v[8:11]
	v_mfma_f32_16x16x32_bf16 v[4:7], v[230:233], v[210:213], v[4:7]
	s_setprio 0
	v_mfma_f32_16x16x32_bf16 v[0:3], v[238:241], v[210:213], v[0:3]
	s_barrier
	ds_read_b128 v[128:131], v226 offset:32768
	ds_read_b128 v[132:135], v226 offset:33792
	ds_read_b128 v[136:139], v226 offset:34816
	ds_read_b128 v[140:143], v226 offset:35840
	s_add_u32 s20, s26, 0x90000
	s_addc_u32 s21, s27, 0
	s_mov_b32 m0, s36
	ds_read_b128 v[144:147], v228 offset:32768
	ds_read_b128 v[148:151], v228 offset:33792
	ds_read_b128 v[152:155], v228 offset:34816
	ds_read_b128 v[194:197], v228 offset:35840
	ds_read_b128 v[198:201], v228 offset:36864
	ds_read_b128 v[202:205], v228 offset:37888
	ds_read_b128 v[206:209], v228 offset:38912
	ds_read_b128 v[210:213], v228 offset:39936
	global_load_lds_dwordx4 v188, s[20:21]
	s_mov_b32 m0, s37
	s_nop 0
	global_load_lds_dwordx4 v186, s[20:21]
	s_waitcnt lgkmcnt(8)
	s_setprio 1
	s_barrier
	s_waitcnt lgkmcnt(0)
	v_mfma_f32_16x16x32_bf16 v[124:127], v[128:131], v[144:147], v[124:127]
	v_mfma_f32_16x16x32_bf16 v[120:123], v[136:139], v[144:147], v[120:123]
	v_mfma_f32_16x16x32_bf16 v[116:119], v[128:131], v[152:155], v[116:119]
	v_mfma_f32_16x16x32_bf16 v[112:115], v[136:139], v[152:155], v[112:115]
	v_mfma_f32_16x16x32_bf16 v[108:111], v[128:131], v[198:201], v[108:111]
	v_mfma_f32_16x16x32_bf16 v[104:107], v[136:139], v[198:201], v[104:107]
	v_mfma_f32_16x16x32_bf16 v[100:103], v[128:131], v[206:209], v[100:103]
	v_mfma_f32_16x16x32_bf16 v[96:99], v[136:139], v[206:209], v[96:99]
	v_mfma_f32_16x16x32_bf16 v[124:127], v[132:135], v[148:151], v[124:127]
	v_mfma_f32_16x16x32_bf16 v[120:123], v[140:143], v[148:151], v[120:123]
	v_mfma_f32_16x16x32_bf16 v[116:119], v[132:135], v[194:197], v[116:119]
	v_mfma_f32_16x16x32_bf16 v[112:115], v[140:143], v[194:197], v[112:115]
	v_mfma_f32_16x16x32_bf16 v[108:111], v[132:135], v[202:205], v[108:111]
	v_mfma_f32_16x16x32_bf16 v[104:107], v[140:143], v[202:205], v[104:107]
	v_mfma_f32_16x16x32_bf16 v[100:103], v[132:135], v[210:213], v[100:103]
	s_setprio 0
	v_mfma_f32_16x16x32_bf16 v[96:99], v[140:143], v[210:213], v[96:99]
	s_barrier
	s_add_i32 s26, 0, 0x1c000
	s_add_i32 s20, s43, s31
	s_add_i32 m0, s20, 0xffffff80
	ds_read_b128 v[214:217], v226 offset:49152
	ds_read_b128 v[230:233], v226 offset:50176
	ds_read_b128 v[234:237], v226 offset:51200
	ds_read_b128 v[238:241], v226 offset:52224
	global_load_lds_dwordx4 v188, s[24:25] offset:128
	s_add_i32 m0, s20, 0x1f80
	s_nop 0
	global_load_lds_dwordx4 v186, s[24:25] offset:128
	s_waitcnt lgkmcnt(0)
	s_setprio 1
	s_barrier
	v_mfma_f32_16x16x32_bf16 v[60:63], v[214:217], v[144:147], v[60:63]
	v_mfma_f32_16x16x32_bf16 v[56:59], v[234:237], v[144:147], v[56:59]
	v_mfma_f32_16x16x32_bf16 v[52:55], v[214:217], v[152:155], v[52:55]
	v_mfma_f32_16x16x32_bf16 v[48:51], v[234:237], v[152:155], v[48:51]
	v_mfma_f32_16x16x32_bf16 v[44:47], v[214:217], v[198:201], v[44:47]
	v_mfma_f32_16x16x32_bf16 v[40:43], v[234:237], v[198:201], v[40:43]
	v_mfma_f32_16x16x32_bf16 v[36:39], v[214:217], v[206:209], v[36:39]
	v_mfma_f32_16x16x32_bf16 v[32:35], v[234:237], v[206:209], v[32:35]
	v_mfma_f32_16x16x32_bf16 v[60:63], v[230:233], v[148:151], v[60:63]
	s_mov_b32 m0, s38
	v_mfma_f32_16x16x32_bf16 v[56:59], v[238:241], v[148:151], v[56:59]
	v_lshl_add_u64 v[218:219], v[242:243], 0, s[94:95]
	v_mfma_f32_16x16x32_bf16 v[52:55], v[230:233], v[194:197], v[52:55]
	v_mfma_f32_16x16x32_bf16 v[48:51], v[238:241], v[194:197], v[48:51]
	v_mfma_f32_16x16x32_bf16 v[44:47], v[230:233], v[202:205], v[44:47]
	v_mfma_f32_16x16x32_bf16 v[40:43], v[238:241], v[202:205], v[40:43]
	v_mfma_f32_16x16x32_bf16 v[36:39], v[230:233], v[210:213], v[36:39]
	s_setprio 0
	v_mfma_f32_16x16x32_bf16 v[32:35], v[238:241], v[210:213], v[32:35]
	s_barrier
	ds_read_b128 v[144:147], v228 offset:49152
	ds_read_b128 v[148:151], v228 offset:50176
	ds_read_b128 v[152:155], v228 offset:51200
	ds_read_b128 v[194:197], v228 offset:52224
	ds_read_b128 v[198:201], v228 offset:53248
	ds_read_b128 v[202:205], v228 offset:54272
	ds_read_b128 v[206:209], v228 offset:55296
	ds_read_b128 v[210:213], v228 offset:56320
	global_load_lds_dwordx4 v[218:219], off
	s_add_i32 m0, s39, 0xffffff80
	s_nop 0
	global_load_lds_dwordx4 v186, s[100:101] offset:128
	s_waitcnt lgkmcnt(0)
	s_setprio 1
	s_barrier
; #define PG8_STAGE(bufoff, gbase) do { _Pragma("unroll") for (int _i = 0; _i < 2; ++_i) \
;         __builtin_amdgcn_global_load_lds((const unsigned*)((const char*)(gbase) + voff[_i]), (LAS unsigned*)(lds + (bufoff) + ldsw + _i * 8192), 16, 0, 0); } while (0)
; #define PG8_MMA(ai, bj, At, Bt) do { __builtin_amdgcn_s_setprio(1); _Pragma("unroll") for (int m = 0; m < 4; ++m) _Pragma("unroll") for (int n = 0; n < 2; ++n) _Pragma("unroll") for (int k = 0; k < 2; ++k) \
;         acc[ai][bj][m][n] = __builtin_amdgcn_mfma_f32_16x16x32_bf16(Bt[n][k], At[m][k], acc[ai][bj][m][n], 0, 0, 0); __builtin_amdgcn_s_setprio(0); } while (0)
; #define PG8_WAIT_V(n) asm volatile("s_waitcnt vmcnt(" #n ")" ::: "memory")
; #define PG8_BAR __builtin_amdgcn_s_barrier()
; template <class Epi>
; DI void gemm_phase(LAS unsigned char* lds, const Gemm g, const StaticOrder& S, const Epi& E) {
;     ...
;             PG8_STAGE(PG8_SB(1, 1), b3 + hstep);
;             PG8_WAIT_V(6); PG8_BAR; PG8_MMA(1, 1, At, B1); PG8_BAR;
;     template <bool LN, int BJ> DI void load_gb(unsigned col0, f32x4 (&gv)[2], f32x4 (&bv)[2]) const {
; #pragma unroll
;         for (int n = 0; n < 2; ++n) {
;             if (LN) { gv[n] = *(const f32x4*)(gam + col0 + BJ * HALF + n * 16) * ALPHA; bv[n] = *(const f32x4*)(bet + col0 + BJ * HALF + n * 16) * ALPHA; }
;             else { gv[n] = (f32x4){ALPHA, ALPHA, ALPHA, ALPHA}; bv[n] = (f32x4){0.f, 0.f, 0.f, 0.f}; }
;         }
;     }
;     template <bool LN> DI void run(const f32x4 (&acc)[2][2][4][2], const Unit& u, int wr, int wc, int fr, int fq) const {
;         const unsigned row0 = u.pm * BM + wr * 64 + fr, col0 = u.pn * BM + wc * 32 + 4 * fq;
;         f32x4 gv[2], bv[2];
;         load_gb<LN, 0>(col0, gv, bv);
;         batch<LN, 0, 0, 4>(acc, row0, col0, gv, bv);
;         batch<LN, 0, 4, 8>(acc, row0, col0, gv, bv);
;         batch<LN, 0, 8, 12>(acc, row0, col0, gv, bv);
;         batch<LN, 0, 12, 16>(acc, row0, col0, gv, bv);
	v_mfma_f32_16x16x32_bf16 v[92:95], v[128:131], v[144:147], v[92:95]
	v_mfma_f32_16x16x32_bf16 v[88:91], v[136:139], v[144:147], v[88:91]
	v_mfma_f32_16x16x32_bf16 v[84:87], v[128:131], v[152:155], v[84:87]
	v_mfma_f32_16x16x32_bf16 v[80:83], v[136:139], v[152:155], v[80:83]
	v_mfma_f32_16x16x32_bf16 v[76:79], v[128:131], v[198:201], v[76:79]
	v_mfma_f32_16x16x32_bf16 v[72:75], v[136:139], v[198:201], v[72:75]
	v_mfma_f32_16x16x32_bf16 v[68:71], v[128:131], v[206:209], v[68:71]
	v_mfma_f32_16x16x32_bf16 v[64:67], v[136:139], v[206:209], v[64:67]
	v_mfma_f32_16x16x32_bf16 v[92:95], v[132:135], v[148:151], v[92:95]
	v_mfma_f32_16x16x32_bf16 v[88:91], v[140:143], v[148:151], v[88:91]
	v_mfma_f32_16x16x32_bf16 v[84:87], v[132:135], v[194:197], v[84:87]
	v_mfma_f32_16x16x32_bf16 v[80:83], v[140:143], v[194:197], v[80:83]
	v_mfma_f32_16x16x32_bf16 v[76:79], v[132:135], v[202:205], v[76:79]
	v_mfma_f32_16x16x32_bf16 v[72:75], v[140:143], v[202:205], v[72:75]
	v_mfma_f32_16x16x32_bf16 v[68:71], v[132:135], v[210:213], v[68:71]
	s_setprio 0
	v_mfma_f32_16x16x32_bf16 v[64:67], v[140:143], v[210:213], v[64:67]
	s_barrier
	s_add_u32 s20, s24, 0x90080
	s_addc_u32 s21, s25, 0
	s_add_i32 s24, s26, s31
	s_mov_b32 m0, s24
	s_nop 0
	global_load_lds_dwordx4 v188, s[20:21]
	s_add_i32 m0, s24, 0x2000
	s_nop 0
	global_load_lds_dwordx4 v186, s[20:21]
	s_waitcnt vmcnt(6)
	s_setprio 1
	s_barrier
	v_mfma_f32_16x16x32_bf16 v[28:31], v[214:217], v[144:147], v[28:31]
	v_mfma_f32_16x16x32_bf16 v[24:27], v[234:237], v[144:147], v[24:27]
	v_mfma_f32_16x16x32_bf16 v[20:23], v[214:217], v[152:155], v[20:23]
	v_mfma_f32_16x16x32_bf16 v[16:19], v[234:237], v[152:155], v[16:19]
	v_mfma_f32_16x16x32_bf16 v[12:15], v[214:217], v[198:201], v[12:15]
	v_mfma_f32_16x16x32_bf16 v[8:11], v[234:237], v[198:201], v[8:11]
	v_mfma_f32_16x16x32_bf16 v[4:7], v[214:217], v[206:209], v[4:7]
	v_mfma_f32_16x16x32_bf16 v[0:3], v[234:237], v[206:209], v[0:3]
	v_mfma_f32_16x16x32_bf16 v[28:31], v[230:233], v[148:151], v[28:31]
	s_add_i32 s33, s33, 2
	v_mfma_f32_16x16x32_bf16 v[24:27], v[238:241], v[148:151], v[24:27]
	s_add_u32 s4, s4, 0x100
	v_mfma_f32_16x16x32_bf16 v[20:23], v[230:233], v[194:197], v[20:23]
	s_addc_u32 s5, s5, 0
	v_mfma_f32_16x16x32_bf16 v[16:19], v[238:241], v[194:197], v[16:19]
	s_cmp_gt_u32 s33, 33
	v_mfma_f32_16x16x32_bf16 v[12:15], v[230:233], v[202:205], v[12:15]
	s_mov_b64 s[20:21], s[22:23]
	v_mfma_f32_16x16x32_bf16 v[8:11], v[238:241], v[202:205], v[8:11]
	v_mfma_f32_16x16x32_bf16 v[4:7], v[230:233], v[210:213], v[4:7]
	s_setprio 0
	v_mfma_f32_16x16x32_bf16 v[0:3], v[238:241], v[210:213], v[0:3]
	s_barrier
	s_cbranch_scc0 .LBB0_77
	v_lshl_add_u32 v206, s3, 8, v225
	v_lshl_or_b32 v158, s2, 8, v227
	v_lshlrev_b32_e32 v232, 11, v206
	s_andn2_b64 vcc, exec, s[14:15]
	v_or_b32_e32 v231, 16, v158
	v_add_u32_e32 v194, v232, v158
	v_or_b32_e32 v230, 0x80, v158
	v_or_b32_e32 v229, 0x90, v158
	s_cbranch_vccnz .LBB0_80
	v_lshlrev_b64 v[132:133], 2, v[158:159]
	v_lshl_add_u64 v[140:141], s[16:17], 0, v[132:133]
	global_load_dwordx4 v[128:131], v[140:141], off
	v_lshl_add_u64 v[142:143], s[18:19], 0, v[132:133]
	v_readlane_b32 s2, v253, 8
	v_mov_b32_e32 v195, v159
	v_lshlrev_b32_e32 v136, 1, v206
	v_mov_b32_e32 v137, v159
	v_readlane_b32 s3, v253, 9
	v_lshlrev_b64 v[212:213], 2, v[194:195]
	v_add_u32_e32 v146, v232, v231
	v_lshl_add_u64 v[144:145], v[136:137], 2, s[2:3]
	v_lshl_add_u64 v[136:137], s[88:89], 0, v[212:213]
	v_mov_b32_e32 v147, v159
	v_lshl_add_u64 v[146:147], v[146:147], 2, s[88:89]
	v_or_b32_e32 v195, 16, v206
	v_mov_b32_e32 v201, v159
	v_mov_b32_e32 v209, v159
	v_lshl_add_u64 v[212:213], s[90:91], 0, v[212:213]
	s_waitcnt vmcnt(0)
	v_pk_mul_f32 v[152:153], v[130:131], s[78:79] op_sel_hi:[1,0]
	v_pk_mul_f32 v[154:155], v[128:129], s[78:79] op_sel_hi:[1,0]
	global_load_dwordx4 v[132:135], v[142:143], off
	global_load_dwordx4 v[128:131], v[140:141], off offset:64
	global_load_dwordx2 v[204:205], v[144:145], off
	global_load_dwordx4 v[196:199], v[146:147], off
	v_lshlrev_b32_e32 v146, 1, v195
	global_load_dwordx4 v[136:139], v[136:137], off
	v_lshlrev_b32_e32 v195, 11, v195
	v_mov_b32_e32 v147, v159
	v_add_u32_e32 v200, v195, v158
	v_lshl_add_u64 v[146:147], v[146:147], 2, s[2:3]
	v_lshl_add_u64 v[200:201], v[200:201], 2, s[88:89]
	global_load_dwordx2 v[214:215], v[146:147], off
	v_add_u32_e32 v208, v195, v231
	global_load_dwordx4 v[200:203], v[200:201], off
	v_lshl_add_u64 v[208:209], v[208:209], 2, s[88:89]
	global_load_dwordx4 v[208:211], v[208:209], off
	s_waitcnt vmcnt(0)
	v_pk_mul_f32 v[148:149], v[130:131], s[78:79] op_sel_hi:[1,0]
	v_pk_mul_f32 v[150:151], v[128:129], s[78:79] op_sel_hi:[1,0]
	global_load_dwordx4 v[128:131], v[142:143], off offset:64
	v_sub_f32_e32 v137, v137, v204
	v_sub_f32_e32 v136, v136, v204
	v_sub_f32_e32 v139, v139, v204
	v_sub_f32_e32 v138, v138, v204
	v_pk_mul_f32 v[138:139], v[204:205], v[138:139] op_sel:[1,0]
	v_pk_mul_f32 v[136:137], v[204:205], v[136:137] op_sel:[1,0]
	v_pk_fma_f32 v[138:139], v[152:153], v[138:139], v[126:127]
	v_pk_fma_f32 v[136:137], v[154:155], v[136:137], v[124:125]
	v_pk_fma_f32 v[138:139], v[134:135], s[78:79], v[138:139] op_sel_hi:[1,0,1]
	v_pk_fma_f32 v[136:137], v[132:133], s[78:79], v[136:137] op_sel_hi:[1,0,1]
	global_store_dwordx4 v[212:213], v[136:139], off
	s_nop 1
	v_sub_f32_e32 v137, v197, v204
	v_sub_f32_e32 v136, v196, v204
	v_sub_f32_e32 v139, v199, v204
	v_sub_f32_e32 v138, v198, v204
	v_pk_mul_f32 v[138:139], v[204:205], v[138:139] op_sel:[1,0]
	v_pk_mul_f32 v[136:137], v[204:205], v[136:137] op_sel:[1,0]
	v_pk_fma_f32 v[138:139], v[148:149], v[138:139], v[122:123]
	v_pk_fma_f32 v[136:137], v[150:151], v[136:137], v[120:121]
	v_or_b32_e32 v196, 16, v194
	v_mov_b32_e32 v197, v159
	v_lshl_add_u64 v[196:197], v[196:197], 2, s[90:91]
	s_waitcnt vmcnt(0)
;     template <bool LN, int BJ, int LO, int HI> DI void batch(const f32x4 (&acc)[2][2][4][2], unsigned row0, unsigned col0, const f32x4 (&gv)[2], const f32x4 (&bv)[2]) const {
;         f32x4 r[HI - LO]; float mean[(HI - LO) / 2], rstd[(HI - LO) / 2];
; #pragma unroll
;         for (int i = LO; i < HI; ++i) { const int ai = i >> 3, m = (i >> 1) & 3, n = i & 1; const unsigned row = row0 + ai * HALF + m * 16;
;             if (n == 0) { mean[(i - LO) >> 1] = 0.f; rstd[(i - LO) >> 1] = 1.f;
;                 if (LN) { const float2 st = *(const float2*)(stats + row * 2u); mean[(i - LO) >> 1] = st.x; rstd[(i - LO) >> 1] = st.y; } }
;             r[i - LO] = *(const f32x4*)(src + (row * (unsigned)DM + col0 + BJ * HALF + n * 16)); }
; #pragma unroll
;         for (int i = LO; i < HI; ++i) { const int ai = i >> 3, m = (i >> 1) & 3, n = i & 1; const unsigned row = row0 + ai * HALF + m * 16;
;             *(f32x4*)(Y + (row * (unsigned)DM + col0 + BJ * HALF + n * 16)) = acc[ai][BJ][m][n] + ((r[i - LO] - mean[(i - LO) >> 1]) * rstd[(i - LO) >> 1]) * gv[n] + bv[n]; }
	v_pk_fma_f32 v[138:139], v[130:131], s[78:79], v[138:139] op_sel_hi:[1,0,1]
	v_pk_fma_f32 v[136:137], v[128:129], s[78:79], v[136:137] op_sel_hi:[1,0,1]
	global_store_dwordx4 v[196:197], v[136:139], off
	v_add_u32_e32 v196, 0x8000, v194
	v_mov_b32_e32 v197, v159
	v_sub_f32_e32 v137, v201, v214
	v_sub_f32_e32 v136, v200, v214
	v_sub_f32_e32 v139, v203, v214
	v_sub_f32_e32 v138, v202, v214
	v_pk_mul_f32 v[138:139], v[214:215], v[138:139] op_sel:[1,0]
	v_pk_mul_f32 v[136:137], v[214:215], v[136:137] op_sel:[1,0]
	v_pk_fma_f32 v[138:139], v[152:153], v[138:139], v[118:119]
	v_pk_fma_f32 v[136:137], v[154:155], v[136:137], v[116:117]
	v_pk_fma_f32 v[138:139], v[134:135], s[78:79], v[138:139] op_sel_hi:[1,0,1]
	v_pk_fma_f32 v[136:137], v[132:133], s[78:79], v[136:137] op_sel_hi:[1,0,1]
	v_lshl_add_u64 v[196:197], v[196:197], 2, s[90:91]
	global_store_dwordx4 v[196:197], v[136:139], off
	v_add_u32_e32 v196, 0x8010, v194
	v_mov_b32_e32 v197, v159
	v_sub_f32_e32 v137, v209, v214
	v_sub_f32_e32 v136, v208, v214
	v_sub_f32_e32 v139, v211, v214
	v_sub_f32_e32 v138, v210, v214
	v_pk_mul_f32 v[138:139], v[214:215], v[138:139] op_sel:[1,0]
	v_pk_mul_f32 v[136:137], v[214:215], v[136:137] op_sel:[1,0]
	v_pk_fma_f32 v[138:139], v[148:149], v[138:139], v[114:115]
	v_pk_fma_f32 v[136:137], v[150:151], v[136:137], v[112:113]
	v_pk_fma_f32 v[138:139], v[130:131], s[78:79], v[138:139] op_sel_hi:[1,0,1]
	v_pk_fma_f32 v[136:137], v[128:129], s[78:79], v[136:137] op_sel_hi:[1,0,1]
	v_lshl_add_u64 v[196:197], v[196:197], 2, s[90:91]
	global_store_dwordx4 v[196:197], v[136:139], off
	s_nop 1
	v_or_b32_e32 v138, 32, v206
	v_lshlrev_b32_e32 v136, 1, v138
	v_mov_b32_e32 v137, v159
	v_lshlrev_b32_e32 v236, 11, v138
	v_lshl_add_u64 v[200:201], v[136:137], 2, s[2:3]
	v_add_u32_e32 v136, v236, v158
	v_lshl_add_u64 v[136:137], v[136:137], 2, s[88:89]
	global_load_dwordx2 v[204:205], v[200:201], off
	v_add_u32_e32 v196, v236, v231
	global_load_dwordx4 v[136:139], v[136:137], off
	v_mov_b32_e32 v197, v159
	v_lshl_add_u64 v[196:197], v[196:197], 2, s[88:89]
	global_load_dwordx4 v[196:199], v[196:197], off
	v_or_b32_e32 v207, 48, v206
	v_lshlrev_b32_e32 v235, 11, v207
	v_lshlrev_b32_e32 v202, 1, v207
	v_mov_b32_e32 v203, v159
	v_add_u32_e32 v208, v235, v158
	v_mov_b32_e32 v209, v159
	v_lshl_add_u64 v[202:203], v[202:203], 2, s[2:3]
	v_lshl_add_u64 v[208:209], v[208:209], 2, s[88:89]
	global_load_dwordx2 v[216:217], v[202:203], off
	v_add_u32_e32 v212, v235, v231
	global_load_dwordx4 v[208:211], v[208:209], off
	v_mov_b32_e32 v213, v159
	v_lshl_add_u64 v[212:213], v[212:213], 2, s[88:89]
	global_load_dwordx4 v[212:215], v[212:213], off
	v_add_u32_e32 v218, 0x10000, v194
	v_mov_b32_e32 v219, v159
	v_lshl_add_u64 v[218:219], v[218:219], 2, s[90:91]
	s_waitcnt vmcnt(0)
	v_sub_f32_e32 v137, v137, v204
	v_sub_f32_e32 v136, v136, v204
	v_sub_f32_e32 v139, v139, v204
	v_sub_f32_e32 v138, v138, v204
	v_pk_mul_f32 v[138:139], v[204:205], v[138:139] op_sel:[1,0]
	v_pk_mul_f32 v[136:137], v[204:205], v[136:137] op_sel:[1,0]
	v_pk_fma_f32 v[138:139], v[152:153], v[138:139], v[110:111]
	v_pk_fma_f32 v[136:137], v[154:155], v[136:137], v[108:109]
	v_pk_fma_f32 v[138:139], v[134:135], s[78:79], v[138:139] op_sel_hi:[1,0,1]
	v_pk_fma_f32 v[136:137], v[132:133], s[78:79], v[136:137] op_sel_hi:[1,0,1]
	global_store_dwordx4 v[218:219], v[136:139], off
	s_nop 1
	v_sub_f32_e32 v137, v197, v204
	v_sub_f32_e32 v136, v196, v204
	v_sub_f32_e32 v139, v199, v204
	v_sub_f32_e32 v138, v198, v204
	v_pk_mul_f32 v[138:139], v[204:205], v[138:139] op_sel:[1,0]
	v_pk_mul_f32 v[136:137], v[204:205], v[136:137] op_sel:[1,0]
	v_pk_fma_f32 v[138:139], v[148:149], v[138:139], v[106:107]
	v_pk_fma_f32 v[136:137], v[150:151], v[136:137], v[104:105]
	v_add_u32_e32 v196, 0x10010, v194
	v_mov_b32_e32 v197, v159
	v_pk_fma_f32 v[138:139], v[130:131], s[78:79], v[138:139] op_sel_hi:[1,0,1]
	v_pk_fma_f32 v[136:137], v[128:129], s[78:79], v[136:137] op_sel_hi:[1,0,1]
	v_lshl_add_u64 v[196:197], v[196:197], 2, s[90:91]
	global_store_dwordx4 v[196:197], v[136:139], off
	v_add_u32_e32 v196, 0x18000, v194
	v_mov_b32_e32 v197, v159
	v_sub_f32_e32 v137, v209, v216
	v_sub_f32_e32 v136, v208, v216
	v_sub_f32_e32 v139, v211, v216
	v_sub_f32_e32 v138, v210, v216
	v_pk_mul_f32 v[138:139], v[216:217], v[138:139] op_sel:[1,0]
	v_pk_mul_f32 v[136:137], v[216:217], v[136:137] op_sel:[1,0]
	v_pk_fma_f32 v[138:139], v[152:153], v[138:139], v[102:103]
	v_pk_fma_f32 v[136:137], v[154:155], v[136:137], v[100:101]
	v_pk_fma_f32 v[138:139], v[134:135], s[78:79], v[138:139] op_sel_hi:[1,0,1]
	v_pk_fma_f32 v[136:137], v[132:133], s[78:79], v[136:137] op_sel_hi:[1,0,1]
	v_lshl_add_u64 v[196:197], v[196:197], 2, s[90:91]
	global_store_dwordx4 v[196:197], v[136:139], off
	v_add_u32_e32 v196, 0x18010, v194
	v_mov_b32_e32 v197, v159
	v_sub_f32_e32 v137, v213, v216
	v_sub_f32_e32 v136, v212, v216
	v_sub_f32_e32 v139, v215, v216
	v_sub_f32_e32 v138, v214, v216
	v_pk_mul_f32 v[138:139], v[216:217], v[138:139] op_sel:[1,0]
	v_pk_mul_f32 v[136:137], v[216:217], v[136:137] op_sel:[1,0]
	v_pk_fma_f32 v[138:139], v[148:149], v[138:139], v[98:99]
	v_pk_fma_f32 v[136:137], v[150:151], v[136:137], v[96:97]
	v_pk_fma_f32 v[138:139], v[130:131], s[78:79], v[138:139] op_sel_hi:[1,0,1]
	v_pk_fma_f32 v[136:137], v[128:129], s[78:79], v[136:137] op_sel_hi:[1,0,1]
	v_lshl_add_u64 v[196:197], v[196:197], 2, s[90:91]
	global_store_dwordx4 v[196:197], v[136:139], off
	s_nop 1
	v_add_u32_e32 v138, 0x80, v206
	v_lshlrev_b32_e32 v136, 1, v138
	v_mov_b32_e32 v137, v159
	v_lshlrev_b32_e32 v233, 11, v138
	v_lshl_add_u64 v[196:197], v[136:137], 2, s[2:3]
	v_add_u32_e32 v136, v233, v158
	v_lshl_add_u64 v[136:137], v[136:137], 2, s[88:89]
	global_load_dwordx2 v[204:205], v[196:197], off
	v_add_u32_e32 v198, v233, v231
	global_load_dwordx4 v[136:139], v[136:137], off
	v_mov_b32_e32 v199, v159
	v_add_u32_e32 v207, 0x90, v206
	v_lshl_add_u64 v[198:199], v[198:199], 2, s[88:89]
	v_lshlrev_b32_e32 v234, 11, v207
	global_load_dwordx4 v[208:211], v[198:199], off
	v_add_u32_e32 v212, v234, v158
	v_mov_b32_e32 v213, v159
	v_lshl_add_u64 v[212:213], v[212:213], 2, s[88:89]
	global_load_dwordx4 v[212:215], v[212:213], off
	v_lshlrev_b32_e32 v198, 1, v207
	v_mov_b32_e32 v199, v159
	v_lshl_add_u64 v[198:199], v[198:199], 2, s[2:3]
	global_load_dwordx2 v[220:221], v[198:199], off
	v_add_u32_e32 v216, v234, v231
	v_mov_b32_e32 v217, v159
	v_lshl_add_u64 v[216:217], v[216:217], 2, s[88:89]
	global_load_dwordx4 v[216:219], v[216:217], off
	v_add_u32_e32 v238, 0x40000, v194
	v_mov_b32_e32 v239, v159
	v_lshl_add_u64 v[238:239], v[238:239], 2, s[90:91]
	s_waitcnt vmcnt(0)
;     template <bool LN, int BJ, int LO, int HI> DI void batch(const f32x4 (&acc)[2][2][4][2], unsigned row0, unsigned col0, const f32x4 (&gv)[2], const f32x4 (&bv)[2]) const {
;         f32x4 r[HI - LO]; float mean[(HI - LO) / 2], rstd[(HI - LO) / 2];
; #pragma unroll
;         for (int i = LO; i < HI; ++i) { const int ai = i >> 3, m = (i >> 1) & 3, n = i & 1; const unsigned row = row0 + ai * HALF + m * 16;
;             if (n == 0) { mean[(i - LO) >> 1] = 0.f; rstd[(i - LO) >> 1] = 1.f;
;                 if (LN) { const float2 st = *(const float2*)(stats + row * 2u); mean[(i - LO) >> 1] = st.x; rstd[(i - LO) >> 1] = st.y; } }
;             r[i - LO] = *(const f32x4*)(src + (row * (unsigned)DM + col0 + BJ * HALF + n * 16)); }
; #pragma unroll
;         for (int i = LO; i < HI; ++i) { const int ai = i >> 3, m = (i >> 1) & 3, n = i & 1; const unsigned row = row0 + ai * HALF + m * 16;
;             *(f32x4*)(Y + (row * (unsigned)DM + col0 + BJ * HALF + n * 16)) = acc[ai][BJ][m][n] + ((r[i - LO] - mean[(i - LO) >> 1]) * rstd[(i - LO) >> 1]) * gv[n] + bv[n]; }
	v_sub_f32_e32 v137, v137, v204
	v_sub_f32_e32 v136, v136, v204
	v_sub_f32_e32 v139, v139, v204
	v_sub_f32_e32 v138, v138, v204
	v_pk_mul_f32 v[138:139], v[204:205], v[138:139] op_sel:[1,0]
	v_pk_mul_f32 v[136:137], v[204:205], v[136:137] op_sel:[1,0]
	v_pk_fma_f32 v[138:139], v[152:153], v[138:139], v[94:95]
	v_pk_fma_f32 v[136:137], v[154:155], v[136:137], v[92:93]
	v_pk_fma_f32 v[138:139], v[134:135], s[78:79], v[138:139] op_sel_hi:[1,0,1]
	v_pk_fma_f32 v[136:137], v[132:133], s[78:79], v[136:137] op_sel_hi:[1,0,1]
	global_store_dwordx4 v[238:239], v[136:139], off
	s_nop 1
	v_sub_f32_e32 v137, v209, v204
	v_sub_f32_e32 v136, v208, v204
	v_sub_f32_e32 v139, v211, v204
	v_sub_f32_e32 v138, v210, v204
	v_pk_mul_f32 v[138:139], v[204:205], v[138:139] op_sel:[1,0]
	v_pk_mul_f32 v[136:137], v[204:205], v[136:137] op_sel:[1,0]
	v_pk_fma_f32 v[138:139], v[148:149], v[138:139], v[90:91]
	v_pk_fma_f32 v[136:137], v[150:151], v[136:137], v[88:89]
	v_add_u32_e32 v204, 0x40010, v194
	v_mov_b32_e32 v205, v159
	v_pk_fma_f32 v[138:139], v[130:131], s[78:79], v[138:139] op_sel_hi:[1,0,1]
	v_pk_fma_f32 v[136:137], v[128:129], s[78:79], v[136:137] op_sel_hi:[1,0,1]
	v_lshl_add_u64 v[204:205], v[204:205], 2, s[90:91]
	global_store_dwordx4 v[204:205], v[136:139], off
	v_add_u32_e32 v204, 0x48000, v194
	v_mov_b32_e32 v205, v159
	v_sub_f32_e32 v137, v213, v220
	v_sub_f32_e32 v136, v212, v220
	v_sub_f32_e32 v139, v215, v220
	v_sub_f32_e32 v138, v214, v220
	v_pk_mul_f32 v[138:139], v[220:221], v[138:139] op_sel:[1,0]
	v_pk_mul_f32 v[136:137], v[220:221], v[136:137] op_sel:[1,0]
	v_pk_fma_f32 v[138:139], v[152:153], v[138:139], v[86:87]
	v_pk_fma_f32 v[136:137], v[154:155], v[136:137], v[84:85]
	v_pk_fma_f32 v[138:139], v[134:135], s[78:79], v[138:139] op_sel_hi:[1,0,1]
	v_pk_fma_f32 v[136:137], v[132:133], s[78:79], v[136:137] op_sel_hi:[1,0,1]
	v_lshl_add_u64 v[204:205], v[204:205], 2, s[90:91]
	global_store_dwordx4 v[204:205], v[136:139], off
	v_add_u32_e32 v204, 0x48010, v194
	v_mov_b32_e32 v205, v159
	v_sub_f32_e32 v137, v217, v220
	v_sub_f32_e32 v136, v216, v220
	v_sub_f32_e32 v139, v219, v220
	v_sub_f32_e32 v138, v218, v220
	v_pk_mul_f32 v[138:139], v[220:221], v[138:139] op_sel:[1,0]
	v_pk_mul_f32 v[136:137], v[220:221], v[136:137] op_sel:[1,0]
	v_pk_fma_f32 v[138:139], v[148:149], v[138:139], v[82:83]
	v_pk_fma_f32 v[136:137], v[150:151], v[136:137], v[80:81]
	v_pk_fma_f32 v[138:139], v[130:131], s[78:79], v[138:139] op_sel_hi:[1,0,1]
	v_pk_fma_f32 v[136:137], v[128:129], s[78:79], v[136:137] op_sel_hi:[1,0,1]
	v_lshl_add_u64 v[204:205], v[204:205], 2, s[90:91]
	global_store_dwordx4 v[204:205], v[136:139], off
	s_nop 1
	v_add_u32_e32 v138, 0xa0, v206
	v_lshlrev_b32_e32 v136, 1, v138
	v_mov_b32_e32 v137, v159
	v_lshlrev_b32_e32 v237, 11, v138
	v_lshl_add_u64 v[204:205], v[136:137], 2, s[2:3]
	v_add_u32_e32 v136, v237, v158
	v_lshl_add_u64 v[136:137], v[136:137], 2, s[88:89]
	global_load_dwordx2 v[220:221], v[204:205], off
	v_add_u32_e32 v208, v237, v231
	global_load_dwordx4 v[136:139], v[136:137], off
	v_mov_b32_e32 v209, v159
	v_lshl_add_u64 v[208:209], v[208:209], 2, s[88:89]
	global_load_dwordx4 v[212:215], v[208:209], off
	v_add_u32_e32 v208, 0xb0, v206
	v_lshlrev_b32_e32 v206, 1, v208
	v_mov_b32_e32 v207, v159
	v_lshlrev_b32_e32 v238, 11, v208
	v_lshl_add_u64 v[210:211], v[206:207], 2, s[2:3]
	v_add_u32_e32 v206, v238, v158
	v_lshl_add_u64 v[206:207], v[206:207], 2, s[88:89]
	global_load_dwordx2 v[240:241], v[210:211], off
	v_add_u32_e32 v216, v238, v231
	global_load_dwordx4 v[206:209], v[206:207], off
	v_mov_b32_e32 v217, v159
	v_lshl_add_u64 v[216:217], v[216:217], 2, s[88:89]
	global_load_dwordx4 v[216:219], v[216:217], off
	v_add_u32_e32 v242, 0x50000, v194
	v_mov_b32_e32 v243, v159
	v_lshl_add_u64 v[242:243], v[242:243], 2, s[90:91]
	s_waitcnt vmcnt(0)
	v_sub_f32_e32 v137, v137, v220
	v_sub_f32_e32 v136, v136, v220
	v_sub_f32_e32 v139, v139, v220
	v_sub_f32_e32 v138, v138, v220
	v_pk_mul_f32 v[138:139], v[220:221], v[138:139] op_sel:[1,0]
	v_pk_mul_f32 v[136:137], v[220:221], v[136:137] op_sel:[1,0]
	v_pk_fma_f32 v[138:139], v[152:153], v[138:139], v[78:79]
	v_pk_fma_f32 v[136:137], v[154:155], v[136:137], v[76:77]
	v_pk_fma_f32 v[138:139], v[134:135], s[78:79], v[138:139] op_sel_hi:[1,0,1]
	v_pk_fma_f32 v[136:137], v[132:133], s[78:79], v[136:137] op_sel_hi:[1,0,1]
	global_store_dwordx4 v[242:243], v[136:139], off
	s_nop 1
	v_sub_f32_e32 v137, v213, v220
	v_sub_f32_e32 v136, v212, v220
	v_sub_f32_e32 v139, v215, v220
	v_sub_f32_e32 v138, v214, v220
	v_pk_mul_f32 v[138:139], v[220:221], v[138:139] op_sel:[1,0]
	v_pk_mul_f32 v[136:137], v[220:221], v[136:137] op_sel:[1,0]
	v_pk_fma_f32 v[138:139], v[148:149], v[138:139], v[74:75]
	v_pk_fma_f32 v[136:137], v[150:151], v[136:137], v[72:73]
	v_add_u32_e32 v212, 0x50010, v194
	v_mov_b32_e32 v213, v159
	v_pk_fma_f32 v[138:139], v[130:131], s[78:79], v[138:139] op_sel_hi:[1,0,1]
	v_pk_fma_f32 v[136:137], v[128:129], s[78:79], v[136:137] op_sel_hi:[1,0,1]
	v_lshl_add_u64 v[212:213], v[212:213], 2, s[90:91]
	global_store_dwordx4 v[212:213], v[136:139], off
	s_nop 1
	v_sub_f32_e32 v137, v207, v240
	v_sub_f32_e32 v136, v206, v240
	v_sub_f32_e32 v139, v209, v240
	v_sub_f32_e32 v138, v208, v240
	v_pk_mul_f32 v[136:137], v[240:241], v[136:137] op_sel:[1,0]
	v_pk_mul_f32 v[138:139], v[240:241], v[138:139] op_sel:[1,0]
	v_pk_fma_f32 v[136:137], v[154:155], v[136:137], v[68:69]
	v_pk_fma_f32 v[138:139], v[152:153], v[138:139], v[70:71]
	v_pk_fma_f32 v[132:133], v[132:133], s[78:79], v[136:137] op_sel_hi:[1,0,1]
	v_add_u32_e32 v136, 0x58000, v194
	v_mov_b32_e32 v137, v159
	v_pk_fma_f32 v[134:135], v[134:135], s[78:79], v[138:139] op_sel_hi:[1,0,1]
	v_lshl_add_u64 v[136:137], v[136:137], 2, s[90:91]
	global_store_dwordx4 v[136:137], v[132:135], off
	s_nop 1
	v_sub_f32_e32 v133, v217, v240
	v_sub_f32_e32 v132, v216, v240
	v_sub_f32_e32 v135, v219, v240
	v_sub_f32_e32 v134, v218, v240
	v_pk_mul_f32 v[132:133], v[240:241], v[132:133] op_sel:[1,0]
	v_pk_mul_f32 v[134:135], v[240:241], v[134:135] op_sel:[1,0]
	v_pk_fma_f32 v[132:133], v[150:151], v[132:133], v[64:65]
	v_pk_fma_f32 v[134:135], v[148:149], v[134:135], v[66:67]
	v_pk_fma_f32 v[128:129], v[128:129], s[78:79], v[132:133] op_sel_hi:[1,0,1]
	v_add_u32_e32 v132, 0x58010, v194
	v_mov_b32_e32 v133, v159
	v_pk_fma_f32 v[130:131], v[130:131], s[78:79], v[134:135] op_sel_hi:[1,0,1]
	v_lshl_add_u64 v[132:133], v[132:133], 2, s[90:91]
	global_store_dwordx4 v[132:133], v[128:131], off
	global_load_dwordx4 v[128:131], v[140:141], off offset:512
	v_add_u32_e32 v136, v232, v230
	v_mov_b32_e32 v137, v159
	v_lshl_add_u64 v[136:137], v[136:137], 2, s[88:89]
	s_waitcnt vmcnt(0)
;     template <bool LN, int BJ, int LO, int HI> DI void batch(const f32x4 (&acc)[2][2][4][2], unsigned row0, unsigned col0, const f32x4 (&gv)[2], const f32x4 (&bv)[2]) const {
;         f32x4 r[HI - LO]; float mean[(HI - LO) / 2], rstd[(HI - LO) / 2];
; #pragma unroll
;         for (int i = LO; i < HI; ++i) { const int ai = i >> 3, m = (i >> 1) & 3, n = i & 1; const unsigned row = row0 + ai * HALF + m * 16;
;             if (n == 0) { mean[(i - LO) >> 1] = 0.f; rstd[(i - LO) >> 1] = 1.f;
;                 if (LN) { const float2 st = *(const float2*)(stats + row * 2u); mean[(i - LO) >> 1] = st.x; rstd[(i - LO) >> 1] = st.y; } }
;             r[i - LO] = *(const f32x4*)(src + (row * (unsigned)DM + col0 + BJ * HALF + n * 16)); }
; #pragma unroll
;         for (int i = LO; i < HI; ++i) { const int ai = i >> 3, m = (i >> 1) & 3, n = i & 1; const unsigned row = row0 + ai * HALF + m * 16;
;             *(f32x4*)(Y + (row * (unsigned)DM + col0 + BJ * HALF + n * 16)) = acc[ai][BJ][m][n] + ((r[i - LO] - mean[(i - LO) >> 1]) * rstd[(i - LO) >> 1]) * gv[n] + bv[n]; }
;     template <bool LN, int BJ> DI void load_gb(unsigned col0, f32x4 (&gv)[2], f32x4 (&bv)[2]) const {
; #pragma unroll
;         for (int n = 0; n < 2; ++n) {
;             if (LN) { gv[n] = *(const f32x4*)(gam + col0 + BJ * HALF + n * 16) * ALPHA; bv[n] = *(const f32x4*)(bet + col0 + BJ * HALF + n * 16) * ALPHA; }
;             else { gv[n] = (f32x4){ALPHA, ALPHA, ALPHA, ALPHA}; bv[n] = (f32x4){0.f, 0.f, 0.f, 0.f}; }
;         }
;     }
;     template <bool LN> DI void run(const f32x4 (&acc)[2][2][4][2], const Unit& u, int wr, int wc, int fr, int fq) const {
;         const unsigned row0 = u.pm * BM + wr * 64 + fr, col0 = u.pn * BM + wc * 32 + 4 * fq;
;         f32x4 gv[2], bv[2];
;         load_gb<LN, 0>(col0, gv, bv);
;         batch<LN, 0, 0, 4>(acc, row0, col0, gv, bv);
;         batch<LN, 0, 4, 8>(acc, row0, col0, gv, bv);
;         batch<LN, 0, 8, 12>(acc, row0, col0, gv, bv);
;         batch<LN, 0, 12, 16>(acc, row0, col0, gv, bv);
;         load_gb<LN, 1>(col0, gv, bv);
;         batch<LN, 1, 0, 8>(acc, row0, col0, gv, bv);
	v_pk_mul_f32 v[212:213], v[130:131], s[78:79] op_sel_hi:[1,0]
	v_pk_mul_f32 v[214:215], v[128:129], s[78:79] op_sel_hi:[1,0]
	global_load_dwordx4 v[132:135], v[142:143], off offset:512
	global_load_dwordx4 v[128:131], v[140:141], off offset:576
	s_waitcnt vmcnt(0)
	v_pk_mul_f32 v[206:207], v[130:131], s[78:79] op_sel_hi:[1,0]
	v_pk_mul_f32 v[208:209], v[128:129], s[78:79] op_sel_hi:[1,0]
	global_load_dwordx4 v[128:131], v[142:143], off offset:576
	global_load_dwordx2 v[220:221], v[144:145], off
	global_load_dwordx4 v[240:243], v[136:137], off
	v_add_u32_e32 v136, v232, v229
	v_mov_b32_e32 v137, v159
	v_lshl_add_u64 v[136:137], v[136:137], 2, s[88:89]
	global_load_dwordx4 v[244:247], v[136:137], off
	global_load_dwordx2 v[218:219], v[146:147], off
	v_add_u32_e32 v136, v195, v230
	v_mov_b32_e32 v137, v159
	v_lshl_add_u64 v[136:137], v[136:137], 2, s[88:89]
	global_load_dwordx4 v[248:251], v[136:137], off
	v_add_u32_e32 v136, v195, v229
	v_mov_b32_e32 v137, v159
	v_lshl_add_u64 v[136:137], v[136:137], 2, s[88:89]
	global_load_dwordx4 v[152:155], v[136:137], off
	global_load_dwordx2 v[216:217], v[200:201], off
	v_add_u32_e32 v136, v236, v230
	v_mov_b32_e32 v137, v159
	v_lshl_add_u64 v[136:137], v[136:137], 2, s[88:89]
	global_load_dwordx4 v[148:151], v[136:137], off
	v_add_u32_e32 v136, v236, v229
	v_mov_b32_e32 v137, v159
	v_lshl_add_u64 v[136:137], v[136:137], 2, s[88:89]
	global_load_dwordx4 v[144:147], v[136:137], off
	global_load_dwordx2 v[200:201], v[202:203], off
	v_add_u32_e32 v136, v235, v230
	v_mov_b32_e32 v137, v159
	v_lshl_add_u64 v[136:137], v[136:137], 2, s[88:89]
	global_load_dwordx4 v[140:143], v[136:137], off
	v_add_u32_e32 v136, v235, v229
	v_mov_b32_e32 v137, v159
	v_lshl_add_u64 v[136:137], v[136:137], 2, s[88:89]
	global_load_dwordx4 v[136:139], v[136:137], off
	v_add_u32_e32 v202, 0x80, v194
	v_mov_b32_e32 v203, v159
	v_lshl_add_u64 v[202:203], v[202:203], 2, s[90:91]
	s_waitcnt vmcnt(0)
	v_sub_f32_e32 v241, v241, v220
	v_sub_f32_e32 v240, v240, v220
	v_sub_f32_e32 v243, v243, v220
	v_sub_f32_e32 v242, v242, v220
	v_pk_mul_f32 v[242:243], v[220:221], v[242:243] op_sel:[1,0]
	v_pk_mul_f32 v[240:241], v[220:221], v[240:241] op_sel:[1,0]
	v_pk_fma_f32 v[242:243], v[212:213], v[242:243], v[62:63]
	v_pk_fma_f32 v[240:241], v[214:215], v[240:241], v[60:61]
	v_pk_fma_f32 v[242:243], v[134:135], s[78:79], v[242:243] op_sel_hi:[1,0,1]
	v_pk_fma_f32 v[240:241], v[132:133], s[78:79], v[240:241] op_sel_hi:[1,0,1]
	global_store_dwordx4 v[202:203], v[240:243], off
	v_sub_f32_e32 v203, v245, v220
	v_sub_f32_e32 v202, v244, v220
	v_sub_f32_e32 v241, v247, v220
	v_sub_f32_e32 v240, v246, v220
	v_pk_mul_f32 v[202:203], v[220:221], v[202:203] op_sel:[1,0]
	v_pk_mul_f32 v[240:241], v[220:221], v[240:241] op_sel:[1,0]
	v_pk_fma_f32 v[202:203], v[208:209], v[202:203], v[56:57]
	v_pk_fma_f32 v[220:221], v[206:207], v[240:241], v[58:59]
	v_pk_fma_f32 v[240:241], v[128:129], s[78:79], v[202:203] op_sel_hi:[1,0,1]
	v_add_u32_e32 v202, 0x90, v194
	v_mov_b32_e32 v203, v159
	v_pk_fma_f32 v[242:243], v[130:131], s[78:79], v[220:221] op_sel_hi:[1,0,1]
	v_lshl_add_u64 v[202:203], v[202:203], 2, s[90:91]
	global_store_dwordx4 v[202:203], v[240:243], off
	v_sub_f32_e32 v203, v249, v218
	v_sub_f32_e32 v202, v248, v218
	v_sub_f32_e32 v221, v251, v218
	v_sub_f32_e32 v220, v250, v218
	v_pk_mul_f32 v[202:203], v[218:219], v[202:203] op_sel:[1,0]
	v_pk_mul_f32 v[220:221], v[218:219], v[220:221] op_sel:[1,0]
	v_pk_fma_f32 v[202:203], v[214:215], v[202:203], v[52:53]
	v_pk_fma_f32 v[220:221], v[212:213], v[220:221], v[54:55]
	v_pk_fma_f32 v[240:241], v[132:133], s[78:79], v[202:203] op_sel_hi:[1,0,1]
	v_add_u32_e32 v202, 0x8080, v194
	v_mov_b32_e32 v203, v159
	v_sub_f32_e32 v153, v153, v218
	v_sub_f32_e32 v152, v152, v218
	v_sub_f32_e32 v155, v155, v218
	v_sub_f32_e32 v154, v154, v218
	v_pk_fma_f32 v[242:243], v[134:135], s[78:79], v[220:221] op_sel_hi:[1,0,1]
	v_lshl_add_u64 v[202:203], v[202:203], 2, s[90:91]
	v_pk_mul_f32 v[154:155], v[218:219], v[154:155] op_sel:[1,0]
	v_pk_mul_f32 v[152:153], v[218:219], v[152:153] op_sel:[1,0]
	global_store_dwordx4 v[202:203], v[240:243], off
	v_pk_fma_f32 v[152:153], v[208:209], v[152:153], v[48:49]
	v_pk_fma_f32 v[154:155], v[206:207], v[154:155], v[50:51]
	v_add_u32_e32 v202, 0x8090, v194
	v_mov_b32_e32 v203, v159
	v_sub_f32_e32 v149, v149, v216
	v_sub_f32_e32 v148, v148, v216
	v_sub_f32_e32 v151, v151, v216
	v_sub_f32_e32 v150, v150, v216
	v_pk_fma_f32 v[154:155], v[130:131], s[78:79], v[154:155] op_sel_hi:[1,0,1]
	v_pk_fma_f32 v[152:153], v[128:129], s[78:79], v[152:153] op_sel_hi:[1,0,1]
	v_lshl_add_u64 v[202:203], v[202:203], 2, s[90:91]
	v_pk_mul_f32 v[150:151], v[216:217], v[150:151] op_sel:[1,0]
	v_pk_mul_f32 v[148:149], v[216:217], v[148:149] op_sel:[1,0]
	global_store_dwordx4 v[202:203], v[152:155], off
	v_pk_fma_f32 v[148:149], v[214:215], v[148:149], v[44:45]
	v_pk_fma_f32 v[150:151], v[212:213], v[150:151], v[46:47]
	v_add_u32_e32 v152, 0x10080, v194
	v_mov_b32_e32 v153, v159
	v_sub_f32_e32 v145, v145, v216
	v_sub_f32_e32 v144, v144, v216
	v_sub_f32_e32 v147, v147, v216
	v_sub_f32_e32 v146, v146, v216
	v_pk_fma_f32 v[150:151], v[134:135], s[78:79], v[150:151] op_sel_hi:[1,0,1]
	v_pk_fma_f32 v[148:149], v[132:133], s[78:79], v[148:149] op_sel_hi:[1,0,1]
	v_lshl_add_u64 v[152:153], v[152:153], 2, s[90:91]
	v_pk_mul_f32 v[146:147], v[216:217], v[146:147] op_sel:[1,0]
	v_pk_mul_f32 v[144:145], v[216:217], v[144:145] op_sel:[1,0]
	global_store_dwordx4 v[152:153], v[148:151], off
	v_pk_fma_f32 v[144:145], v[208:209], v[144:145], v[40:41]
	v_pk_fma_f32 v[146:147], v[206:207], v[146:147], v[42:43]
;     template <bool LN, int BJ, int LO, int HI> DI void batch(const f32x4 (&acc)[2][2][4][2], unsigned row0, unsigned col0, const f32x4 (&gv)[2], const f32x4 (&bv)[2]) const {
;         f32x4 r[HI - LO]; float mean[(HI - LO) / 2], rstd[(HI - LO) / 2];
; #pragma unroll
;         for (int i = LO; i < HI; ++i) { const int ai = i >> 3, m = (i >> 1) & 3, n = i & 1; const unsigned row = row0 + ai * HALF + m * 16;
;             if (n == 0) { mean[(i - LO) >> 1] = 0.f; rstd[(i - LO) >> 1] = 1.f;
;                 if (LN) { const float2 st = *(const float2*)(stats + row * 2u); mean[(i - LO) >> 1] = st.x; rstd[(i - LO) >> 1] = st.y; } }
;             r[i - LO] = *(const f32x4*)(src + (row * (unsigned)DM + col0 + BJ * HALF + n * 16)); }
; #pragma unroll
;         for (int i = LO; i < HI; ++i) { const int ai = i >> 3, m = (i >> 1) & 3, n = i & 1; const unsigned row = row0 + ai * HALF + m * 16;
;             *(f32x4*)(Y + (row * (unsigned)DM + col0 + BJ * HALF + n * 16)) = acc[ai][BJ][m][n] + ((r[i - LO] - mean[(i - LO) >> 1]) * rstd[(i - LO) >> 1]) * gv[n] + bv[n]; }
	v_add_u32_e32 v148, 0x10090, v194
	v_mov_b32_e32 v149, v159
	v_sub_f32_e32 v141, v141, v200
	v_sub_f32_e32 v140, v140, v200
	v_sub_f32_e32 v143, v143, v200
	v_sub_f32_e32 v142, v142, v200
	v_pk_fma_f32 v[146:147], v[130:131], s[78:79], v[146:147] op_sel_hi:[1,0,1]
	v_pk_fma_f32 v[144:145], v[128:129], s[78:79], v[144:145] op_sel_hi:[1,0,1]
	v_lshl_add_u64 v[148:149], v[148:149], 2, s[90:91]
	v_pk_mul_f32 v[142:143], v[200:201], v[142:143] op_sel:[1,0]
	v_pk_mul_f32 v[140:141], v[200:201], v[140:141] op_sel:[1,0]
	global_store_dwordx4 v[148:149], v[144:147], off
	v_pk_fma_f32 v[140:141], v[214:215], v[140:141], v[36:37]
	v_pk_fma_f32 v[142:143], v[212:213], v[142:143], v[38:39]
	v_add_u32_e32 v144, 0x18080, v194
	v_mov_b32_e32 v145, v159
	v_sub_f32_e32 v137, v137, v200
	v_sub_f32_e32 v136, v136, v200
	v_sub_f32_e32 v139, v139, v200
	v_sub_f32_e32 v138, v138, v200
	v_pk_fma_f32 v[142:143], v[134:135], s[78:79], v[142:143] op_sel_hi:[1,0,1]
	v_pk_fma_f32 v[140:141], v[132:133], s[78:79], v[140:141] op_sel_hi:[1,0,1]
	v_lshl_add_u64 v[144:145], v[144:145], 2, s[90:91]
	v_pk_mul_f32 v[138:139], v[200:201], v[138:139] op_sel:[1,0]
	v_pk_mul_f32 v[136:137], v[200:201], v[136:137] op_sel:[1,0]
	global_store_dwordx4 v[144:145], v[140:143], off
	v_pk_fma_f32 v[136:137], v[208:209], v[136:137], v[32:33]
	v_pk_fma_f32 v[138:139], v[206:207], v[138:139], v[34:35]
	v_add_u32_e32 v140, 0x18090, v194
	v_mov_b32_e32 v141, v159
	v_pk_fma_f32 v[138:139], v[130:131], s[78:79], v[138:139] op_sel_hi:[1,0,1]
	v_pk_fma_f32 v[136:137], v[128:129], s[78:79], v[136:137] op_sel_hi:[1,0,1]
	v_lshl_add_u64 v[140:141], v[140:141], 2, s[90:91]
	global_store_dwordx4 v[140:141], v[136:139], off
	s_nop 1
	v_add_u32_e32 v136, v233, v230
	v_mov_b32_e32 v137, v159
	v_lshl_add_u64 v[136:137], v[136:137], 2, s[88:89]
	global_load_dwordx2 v[220:221], v[196:197], off
	global_load_dwordx4 v[216:219], v[136:137], off
	v_add_u32_e32 v136, v233, v229
	v_mov_b32_e32 v137, v159
	v_lshl_add_u64 v[136:137], v[136:137], 2, s[88:89]
	global_load_dwordx4 v[240:243], v[136:137], off
	global_load_dwordx2 v[200:201], v[198:199], off
	v_add_u32_e32 v136, v234, v230
	v_mov_b32_e32 v137, v159
	v_lshl_add_u64 v[136:137], v[136:137], 2, s[88:89]
	global_load_dwordx4 v[244:247], v[136:137], off
	v_add_u32_e32 v136, v234, v229
	v_mov_b32_e32 v137, v159
	v_lshl_add_u64 v[136:137], v[136:137], 2, s[88:89]
	global_load_dwordx4 v[152:155], v[136:137], off
	global_load_dwordx2 v[198:199], v[204:205], off
	v_add_u32_e32 v136, v237, v230
	v_mov_b32_e32 v137, v159
	v_lshl_add_u64 v[136:137], v[136:137], 2, s[88:89]
	global_load_dwordx4 v[148:151], v[136:137], off
	v_add_u32_e32 v136, v237, v229
	v_mov_b32_e32 v137, v159
	v_lshl_add_u64 v[136:137], v[136:137], 2, s[88:89]
	global_load_dwordx4 v[144:147], v[136:137], off
	global_load_dwordx2 v[196:197], v[210:211], off
	v_add_u32_e32 v136, v238, v230
	v_mov_b32_e32 v137, v159
	v_lshl_add_u64 v[136:137], v[136:137], 2, s[88:89]
	global_load_dwordx4 v[140:143], v[136:137], off
	v_add_u32_e32 v136, v238, v229
	v_mov_b32_e32 v137, v159
	v_lshl_add_u64 v[136:137], v[136:137], 2, s[88:89]
	global_load_dwordx4 v[136:139], v[136:137], off
	v_add_u32_e32 v210, 0x40080, v194
	v_mov_b32_e32 v211, v159
	v_lshl_add_u64 v[210:211], v[210:211], 2, s[90:91]
	s_waitcnt vmcnt(0)
;     template <bool LN, int BJ, int LO, int HI> DI void batch(const f32x4 (&acc)[2][2][4][2], unsigned row0, unsigned col0, const f32x4 (&gv)[2], const f32x4 (&bv)[2]) const {
;         f32x4 r[HI - LO]; float mean[(HI - LO) / 2], rstd[(HI - LO) / 2];
; #pragma unroll
;         for (int i = LO; i < HI; ++i) { const int ai = i >> 3, m = (i >> 1) & 3, n = i & 1; const unsigned row = row0 + ai * HALF + m * 16;
;             if (n == 0) { mean[(i - LO) >> 1] = 0.f; rstd[(i - LO) >> 1] = 1.f;
;                 if (LN) { const float2 st = *(const float2*)(stats + row * 2u); mean[(i - LO) >> 1] = st.x; rstd[(i - LO) >> 1] = st.y; } }
;             r[i - LO] = *(const f32x4*)(src + (row * (unsigned)DM + col0 + BJ * HALF + n * 16)); }
; #pragma unroll
;         for (int i = LO; i < HI; ++i) { const int ai = i >> 3, m = (i >> 1) & 3, n = i & 1; const unsigned row = row0 + ai * HALF + m * 16;
;             *(f32x4*)(Y + (row * (unsigned)DM + col0 + BJ * HALF + n * 16)) = acc[ai][BJ][m][n] + ((r[i - LO] - mean[(i - LO) >> 1]) * rstd[(i - LO) >> 1]) * gv[n] + bv[n]; }
	v_sub_f32_e32 v203, v217, v220
	v_sub_f32_e32 v202, v216, v220
	v_sub_f32_e32 v205, v219, v220
	v_sub_f32_e32 v204, v218, v220
	v_pk_mul_f32 v[204:205], v[220:221], v[204:205] op_sel:[1,0]
	v_pk_mul_f32 v[202:203], v[220:221], v[202:203] op_sel:[1,0]
	v_pk_fma_f32 v[204:205], v[212:213], v[204:205], v[30:31]
	v_pk_fma_f32 v[202:203], v[214:215], v[202:203], v[28:29]
	v_pk_fma_f32 v[204:205], v[134:135], s[78:79], v[204:205] op_sel_hi:[1,0,1]
	v_pk_fma_f32 v[202:203], v[132:133], s[78:79], v[202:203] op_sel_hi:[1,0,1]
	global_store_dwordx4 v[210:211], v[202:205], off
	v_add_u32_e32 v210, 0x40090, v194
	v_mov_b32_e32 v211, v159
	v_sub_f32_e32 v203, v241, v220
	v_sub_f32_e32 v202, v240, v220
	v_sub_f32_e32 v205, v243, v220
	v_sub_f32_e32 v204, v242, v220
	v_pk_mul_f32 v[204:205], v[220:221], v[204:205] op_sel:[1,0]
	v_pk_mul_f32 v[202:203], v[220:221], v[202:203] op_sel:[1,0]
	v_pk_fma_f32 v[204:205], v[206:207], v[204:205], v[26:27]
	v_pk_fma_f32 v[202:203], v[208:209], v[202:203], v[24:25]
	v_pk_fma_f32 v[204:205], v[130:131], s[78:79], v[204:205] op_sel_hi:[1,0,1]
	v_pk_fma_f32 v[202:203], v[128:129], s[78:79], v[202:203] op_sel_hi:[1,0,1]
	v_lshl_add_u64 v[210:211], v[210:211], 2, s[90:91]
	global_store_dwordx4 v[210:211], v[202:205], off
	v_sub_f32_e32 v149, v149, v198
	v_sub_f32_e32 v148, v148, v198
	v_sub_f32_e32 v203, v245, v200
	v_sub_f32_e32 v202, v244, v200
	v_sub_f32_e32 v141, v141, v196
	v_sub_f32_e32 v140, v140, v196
	v_sub_f32_e32 v205, v247, v200
	v_sub_f32_e32 v204, v246, v200
	v_pk_mul_f32 v[202:203], v[200:201], v[202:203] op_sel:[1,0]
	v_sub_f32_e32 v151, v151, v198
	v_sub_f32_e32 v150, v150, v198
	v_pk_mul_f32 v[148:149], v[198:199], v[148:149] op_sel:[1,0]
	v_sub_f32_e32 v143, v143, v196
	v_sub_f32_e32 v142, v142, v196
	v_pk_mul_f32 v[140:141], v[196:197], v[140:141] op_sel:[1,0]
	v_pk_mul_f32 v[204:205], v[200:201], v[204:205] op_sel:[1,0]
	v_pk_fma_f32 v[202:203], v[214:215], v[202:203], v[20:21]
	v_sub_f32_e32 v153, v153, v200
	v_sub_f32_e32 v152, v152, v200
	v_sub_f32_e32 v155, v155, v200
	v_sub_f32_e32 v154, v154, v200
	v_pk_mul_f32 v[150:151], v[198:199], v[150:151] op_sel:[1,0]
	v_pk_fma_f32 v[148:149], v[214:215], v[148:149], v[12:13]
	v_pk_mul_f32 v[142:143], v[196:197], v[142:143] op_sel:[1,0]
	v_pk_fma_f32 v[140:141], v[214:215], v[140:141], v[4:5]
	v_pk_fma_f32 v[204:205], v[212:213], v[204:205], v[22:23]
	v_pk_fma_f32 v[202:203], v[132:133], s[78:79], v[202:203] op_sel_hi:[1,0,1]
	v_pk_mul_f32 v[154:155], v[200:201], v[154:155] op_sel:[1,0]
	v_pk_mul_f32 v[152:153], v[200:201], v[152:153] op_sel:[1,0]
	v_pk_fma_f32 v[150:151], v[212:213], v[150:151], v[14:15]
	v_pk_fma_f32 v[148:149], v[132:133], s[78:79], v[148:149] op_sel_hi:[1,0,1]
	v_pk_fma_f32 v[142:143], v[212:213], v[142:143], v[6:7]
	v_pk_fma_f32 v[132:133], v[132:133], s[78:79], v[140:141] op_sel_hi:[1,0,1]
	v_add_u32_e32 v140, 0x58080, v194
	v_mov_b32_e32 v141, v159
	v_pk_fma_f32 v[204:205], v[134:135], s[78:79], v[204:205] op_sel_hi:[1,0,1]
	v_pk_fma_f32 v[152:153], v[208:209], v[152:153], v[16:17]
	v_pk_fma_f32 v[154:155], v[206:207], v[154:155], v[18:19]
	v_add_u32_e32 v200, 0x48090, v194
	v_mov_b32_e32 v201, v159
	v_pk_fma_f32 v[150:151], v[134:135], s[78:79], v[150:151] op_sel_hi:[1,0,1]
	v_pk_fma_f32 v[134:135], v[134:135], s[78:79], v[142:143] op_sel_hi:[1,0,1]
	v_lshl_add_u64 v[140:141], v[140:141], 2, s[90:91]
	v_pk_fma_f32 v[154:155], v[130:131], s[78:79], v[154:155] op_sel_hi:[1,0,1]
	v_pk_fma_f32 v[152:153], v[128:129], s[78:79], v[152:153] op_sel_hi:[1,0,1]
	v_lshl_add_u64 v[200:201], v[200:201], 2, s[90:91]
	v_sub_f32_e32 v145, v145, v198
	v_sub_f32_e32 v144, v144, v198
	global_store_dwordx4 v[140:141], v[132:135], off
	global_store_dwordx4 v[200:201], v[152:155], off
	v_sub_f32_e32 v147, v147, v198
	v_sub_f32_e32 v133, v137, v196
	v_sub_f32_e32 v132, v136, v196
	v_add_u32_e32 v152, 0x50080, v194
	v_mov_b32_e32 v153, v159
	v_sub_f32_e32 v146, v146, v198
	v_pk_mul_f32 v[144:145], v[198:199], v[144:145] op_sel:[1,0]
	v_sub_f32_e32 v135, v139, v196
	v_sub_f32_e32 v134, v138, v196
	v_pk_mul_f32 v[132:133], v[196:197], v[132:133] op_sel:[1,0]
	v_lshl_add_u64 v[152:153], v[152:153], 2, s[90:91]
	v_pk_mul_f32 v[146:147], v[198:199], v[146:147] op_sel:[1,0]
	v_pk_fma_f32 v[144:145], v[208:209], v[144:145], v[8:9]
	v_pk_mul_f32 v[134:135], v[196:197], v[134:135] op_sel:[1,0]
	v_pk_fma_f32 v[132:133], v[208:209], v[132:133], v[0:1]
	v_add_u32_e32 v210, 0x48080, v194
	v_mov_b32_e32 v211, v159
	global_store_dwordx4 v[152:153], v[148:151], off
	v_pk_fma_f32 v[146:147], v[206:207], v[146:147], v[10:11]
	v_pk_fma_f32 v[144:145], v[128:129], s[78:79], v[144:145] op_sel_hi:[1,0,1]
	v_add_u32_e32 v148, 0x50090, v194
	v_mov_b32_e32 v149, v159
	v_pk_fma_f32 v[134:135], v[206:207], v[134:135], v[2:3]
	v_pk_fma_f32 v[128:129], v[128:129], s[78:79], v[132:133] op_sel_hi:[1,0,1]
	v_add_u32_e32 v132, 0x58090, v194
	v_mov_b32_e32 v133, v159
	v_lshl_add_u64 v[210:211], v[210:211], 2, s[90:91]
	v_pk_fma_f32 v[146:147], v[130:131], s[78:79], v[146:147] op_sel_hi:[1,0,1]
	v_lshl_add_u64 v[148:149], v[148:149], 2, s[90:91]
	v_pk_fma_f32 v[130:131], v[130:131], s[78:79], v[134:135] op_sel_hi:[1,0,1]
	v_lshl_add_u64 v[132:133], v[132:133], 2, s[90:91]
	global_store_dwordx4 v[210:211], v[202:205], off
	global_store_dwordx4 v[148:149], v[144:147], off
	global_store_dwordx4 v[132:133], v[128:131], off
	s_mov_b64 s[20:21], 0
	s_branch .LBB0_81

; #define PG8_STAGE(bufoff, gbase) do { _Pragma("unroll") for (int _i = 0; _i < 2; ++_i) \
;         __builtin_amdgcn_global_load_lds((const unsigned*)((const char*)(gbase) + voff[_i]), (LAS unsigned*)(lds + (bufoff) + ldsw + _i * 8192), 16, 0, 0); } while (0)
; #define PG8_LDA(dst, b, h) do { _Pragma("unroll") for (int m = 0; m < 4; ++m) _Pragma("unroll") for (int k = 0; k < 2; ++k) dst[m][k] = *(const LAS bf16x8*)(lds + PG8_SA(b, h) + aoff + m * 2048 + k * 1024); } while (0)
; #define PG8_LDB(dst, b, h) do { _Pragma("unroll") for (int n = 0; n < 2; ++n) _Pragma("unroll") for (int k = 0; k < 2; ++k) dst[n][k] = *(const LAS bf16x8*)(lds + PG8_SB(b, h) + boff + n * 2048 + k * 1024); } while (0)
; #define PG8_MMA(ai, bj, At, Bt) do { __builtin_amdgcn_s_setprio(1); _Pragma("unroll") for (int m = 0; m < 4; ++m) _Pragma("unroll") for (int n = 0; n < 2; ++n) _Pragma("unroll") for (int k = 0; k < 2; ++k) \
;         acc[ai][bj][m][n] = __builtin_amdgcn_mfma_f32_16x16x32_bf16(Bt[n][k], At[m][k], acc[ai][bj][m][n], 0, 0, 0); __builtin_amdgcn_s_setprio(0); } while (0)
; #define PG8_WAIT_V(n) asm volatile("s_waitcnt vmcnt(" #n ")" ::: "memory")
; #define PG8_WAIT_L(n) asm volatile("s_waitcnt lgkmcnt(" #n ")" ::: "memory")
; #define PG8_BAR __builtin_amdgcn_s_barrier()
; #define PG8_SCHED __builtin_amdgcn_sched_barrier(0)
; template <class Epi>
; DI void gemm_phase(LAS unsigned char* lds, const Gemm g, const StaticOrder& S, const Epi& E) {
;     ...
;             PG8_LDB(B0, 0, 0); PG8_SCHED; PG8_LDA(At, 0, 0); PG8_STAGE(PG8_SA(1, 1), a1 + hstep);
;             PG8_WAIT_L(8); PG8_BAR; PG8_WAIT_L(0); PG8_MMA(0, 0, At, B0); PG8_BAR; PG8_SCHED;
;             PG8_LDB(B1, 0, 1); PG8_STAGE(PG8_SB(0, 0), b2);
;             PG8_BAR; PG8_WAIT_L(0); PG8_MMA(0, 1, At, B1); PG8_BAR;
;             PG8_LDA(At, 0, 1); PG8_STAGE(PG8_SA(0, 0), a2);
;             PG8_BAR; PG8_WAIT_L(0); PG8_MMA(1, 0, At, B0); PG8_BAR; PG8_SCHED;
;             PG8_STAGE(PG8_SB(0, 1), b2 + hstep);
;             PG8_WAIT_V(6); PG8_BAR; PG8_MMA(1, 1, At, B1); PG8_BAR;
.LBB0_134:
	s_add_u32 s18, s16, 0x100
	s_addc_u32 s19, s17, 0
	s_add_i32 s39, 0, 0x10000
	ds_read_b128 v[96:99], v199
	ds_read_b128 v[100:103], v199 offset:1024
	ds_read_b128 v[136:139], v199 offset:2048
	ds_read_b128 v[148:151], v199 offset:3072
	s_cmpk_eq_i32 s33, 0x54
	s_cselect_b32 s23, s9, s19
	s_cselect_b32 s22, s8, s18
	s_cselect_b32 s21, s11, s5
	s_cselect_b32 s20, s10, s4
	v_lshl_add_u64 v[218:219], s[16:17], 0, v[144:145]
	s_add_i32 m0, s28, 0xc000
	ds_read_b128 v[152:155], v201
	ds_read_b128 v[186:189], v201 offset:1024
	ds_read_b128 v[190:193], v201 offset:2048
	ds_read_b128 v[194:197], v201 offset:3072
	ds_read_b128 v[202:205], v201 offset:4096
	ds_read_b128 v[206:209], v201 offset:5120
	ds_read_b128 v[210:213], v201 offset:6144
	ds_read_b128 v[214:217], v201 offset:7168
	global_load_lds_dwordx4 v[218:219], off
	v_lshl_add_u64 v[218:219], s[16:17], 0, v[146:147]
	s_add_i32 m0, s28, 0xe000
	s_nop 0
	global_load_lds_dwordx4 v[218:219], off
	s_waitcnt lgkmcnt(8)
	s_setprio 1
	s_barrier
	s_waitcnt lgkmcnt(0)
	v_mfma_f32_16x16x32_bf16 v[132:135], v[96:99], v[152:155], v[132:135]
	v_mfma_f32_16x16x32_bf16 v[128:131], v[136:139], v[152:155], v[128:131]
	v_mfma_f32_16x16x32_bf16 v[124:127], v[96:99], v[190:193], v[124:127]
	v_mfma_f32_16x16x32_bf16 v[120:123], v[136:139], v[190:193], v[120:123]
	v_mfma_f32_16x16x32_bf16 v[116:119], v[96:99], v[202:205], v[116:119]
	v_mfma_f32_16x16x32_bf16 v[112:115], v[136:139], v[202:205], v[112:115]
	v_mfma_f32_16x16x32_bf16 v[108:111], v[96:99], v[210:213], v[108:111]
	v_mfma_f32_16x16x32_bf16 v[104:107], v[136:139], v[210:213], v[104:107]
	v_mfma_f32_16x16x32_bf16 v[132:135], v[100:103], v[186:189], v[132:135]
	v_mfma_f32_16x16x32_bf16 v[128:131], v[148:151], v[186:189], v[128:131]
	v_mfma_f32_16x16x32_bf16 v[124:127], v[100:103], v[194:197], v[124:127]
	v_mfma_f32_16x16x32_bf16 v[120:123], v[148:151], v[194:197], v[120:123]
	v_mfma_f32_16x16x32_bf16 v[116:119], v[100:103], v[206:209], v[116:119]
	v_mfma_f32_16x16x32_bf16 v[112:115], v[148:151], v[206:209], v[112:115]
	v_mfma_f32_16x16x32_bf16 v[108:111], v[100:103], v[214:217], v[108:111]
	s_setprio 0
	v_mfma_f32_16x16x32_bf16 v[104:107], v[148:151], v[214:217], v[104:107]
	s_barrier
	s_add_i32 s40, 0, 0x14000
	s_add_i32 s16, s39, s27
	s_mov_b32 m0, s16
	ds_read_b128 v[226:229], v199 offset:16384
	ds_read_b128 v[230:233], v199 offset:17408
	ds_read_b128 v[234:237], v199 offset:18432
	ds_read_b128 v[238:241], v199 offset:19456
	global_load_lds_dwordx4 v142, s[20:21]
	s_add_i32 m0, s16, 0x2000
	s_nop 0
	global_load_lds_dwordx4 v140, s[20:21]
	s_waitcnt lgkmcnt(0)
	s_setprio 1
	s_barrier
	v_mfma_f32_16x16x32_bf16 v[60:63], v[226:229], v[152:155], v[60:63]
	v_mfma_f32_16x16x32_bf16 v[56:59], v[234:237], v[152:155], v[56:59]
	v_mfma_f32_16x16x32_bf16 v[52:55], v[226:229], v[190:193], v[52:55]
	v_mfma_f32_16x16x32_bf16 v[48:51], v[234:237], v[190:193], v[48:51]
	v_mfma_f32_16x16x32_bf16 v[44:47], v[226:229], v[202:205], v[44:47]
	v_mfma_f32_16x16x32_bf16 v[40:43], v[234:237], v[202:205], v[40:43]
	v_mfma_f32_16x16x32_bf16 v[36:39], v[226:229], v[210:213], v[36:39]
	v_mfma_f32_16x16x32_bf16 v[32:35], v[234:237], v[210:213], v[32:35]
	v_mfma_f32_16x16x32_bf16 v[60:63], v[230:233], v[186:189], v[60:63]
	s_mov_b32 m0, s28
	v_mfma_f32_16x16x32_bf16 v[56:59], v[238:241], v[186:189], v[56:59]
	v_lshl_add_u64 v[242:243], s[22:23], 0, v[142:143]
	v_mfma_f32_16x16x32_bf16 v[52:55], v[230:233], v[194:197], v[52:55]
	v_mfma_f32_16x16x32_bf16 v[48:51], v[238:241], v[194:197], v[48:51]
	v_mfma_f32_16x16x32_bf16 v[44:47], v[230:233], v[206:209], v[44:47]
	v_mfma_f32_16x16x32_bf16 v[40:43], v[238:241], v[206:209], v[40:43]
	v_mfma_f32_16x16x32_bf16 v[36:39], v[230:233], v[214:217], v[36:39]
	s_setprio 0
	v_mfma_f32_16x16x32_bf16 v[32:35], v[238:241], v[214:217], v[32:35]
	s_barrier
	ds_read_b128 v[152:155], v201 offset:16384
	ds_read_b128 v[186:189], v201 offset:17408
	ds_read_b128 v[190:193], v201 offset:18432
	ds_read_b128 v[194:197], v201 offset:19456
	ds_read_b128 v[202:205], v201 offset:20480
	ds_read_b128 v[206:209], v201 offset:21504
	ds_read_b128 v[210:213], v201 offset:22528
	ds_read_b128 v[214:217], v201 offset:23552
	global_load_lds_dwordx4 v[242:243], off
	s_mov_b64 s[100:101], s[22:23]
	s_mov_b32 m0, s29
	s_nop 0
	global_load_lds_dwordx4 v140, s[22:23]
	s_waitcnt lgkmcnt(0)
	s_setprio 1
	s_barrier
	v_mfma_f32_16x16x32_bf16 v[92:95], v[96:99], v[152:155], v[92:95]
	v_mfma_f32_16x16x32_bf16 v[88:91], v[136:139], v[152:155], v[88:91]
	v_mfma_f32_16x16x32_bf16 v[84:87], v[96:99], v[190:193], v[84:87]
	v_mfma_f32_16x16x32_bf16 v[80:83], v[136:139], v[190:193], v[80:83]
	v_mfma_f32_16x16x32_bf16 v[76:79], v[96:99], v[202:205], v[76:79]
	v_mfma_f32_16x16x32_bf16 v[72:75], v[136:139], v[202:205], v[72:75]
	v_mfma_f32_16x16x32_bf16 v[68:71], v[96:99], v[210:213], v[68:71]
	v_mfma_f32_16x16x32_bf16 v[64:67], v[136:139], v[210:213], v[64:67]
	v_mfma_f32_16x16x32_bf16 v[92:95], v[100:103], v[186:189], v[92:95]
	v_mfma_f32_16x16x32_bf16 v[88:91], v[148:151], v[186:189], v[88:91]
	v_mfma_f32_16x16x32_bf16 v[84:87], v[100:103], v[194:197], v[84:87]
	v_mfma_f32_16x16x32_bf16 v[80:83], v[148:151], v[194:197], v[80:83]
	v_mfma_f32_16x16x32_bf16 v[76:79], v[100:103], v[206:209], v[76:79]
	v_mfma_f32_16x16x32_bf16 v[72:75], v[148:151], v[206:209], v[72:75]
	v_mfma_f32_16x16x32_bf16 v[68:71], v[100:103], v[214:217], v[68:71]
	s_setprio 0
	v_mfma_f32_16x16x32_bf16 v[64:67], v[148:151], v[214:217], v[64:67]
	s_barrier
	s_add_u32 s16, s20, 0x160000
	s_addc_u32 s17, s21, 0
	s_add_i32 s39, s40, s27
	s_mov_b32 m0, s39
	s_nop 0
	global_load_lds_dwordx4 v142, s[16:17]
	s_add_i32 m0, s39, 0x2000
	s_nop 0
	global_load_lds_dwordx4 v140, s[16:17]
	s_waitcnt vmcnt(6)
	s_setprio 1
	s_barrier
; #define PG8_STAGE(bufoff, gbase) do { _Pragma("unroll") for (int _i = 0; _i < 2; ++_i) \
;         __builtin_amdgcn_global_load_lds((const unsigned*)((const char*)(gbase) + voff[_i]), (LAS unsigned*)(lds + (bufoff) + ldsw + _i * 8192), 16, 0, 0); } while (0)
; #define PG8_LDA(dst, b, h) do { _Pragma("unroll") for (int m = 0; m < 4; ++m) _Pragma("unroll") for (int k = 0; k < 2; ++k) dst[m][k] = *(const LAS bf16x8*)(lds + PG8_SA(b, h) + aoff + m * 2048 + k * 1024); } while (0)
; #define PG8_LDB(dst, b, h) do { _Pragma("unroll") for (int n = 0; n < 2; ++n) _Pragma("unroll") for (int k = 0; k < 2; ++k) dst[n][k] = *(const LAS bf16x8*)(lds + PG8_SB(b, h) + boff + n * 2048 + k * 1024); } while (0)
; #define PG8_MMA(ai, bj, At, Bt) do { __builtin_amdgcn_s_setprio(1); _Pragma("unroll") for (int m = 0; m < 4; ++m) _Pragma("unroll") for (int n = 0; n < 2; ++n) _Pragma("unroll") for (int k = 0; k < 2; ++k) \
;         acc[ai][bj][m][n] = __builtin_amdgcn_mfma_f32_16x16x32_bf16(Bt[n][k], At[m][k], acc[ai][bj][m][n], 0, 0, 0); __builtin_amdgcn_s_setprio(0); } while (0)
; #define PG8_WAIT_V(n) asm volatile("s_waitcnt vmcnt(" #n ")" ::: "memory")
; #define PG8_WAIT_L(n) asm volatile("s_waitcnt lgkmcnt(" #n ")" ::: "memory")
; #define PG8_BAR __builtin_amdgcn_s_barrier()
; #define PG8_SCHED __builtin_amdgcn_sched_barrier(0)
; template <class Epi>
; DI void gemm_phase(LAS unsigned char* lds, const Gemm g, const StaticOrder& S, const Epi& E) {
;     ...
;             PG8_WAIT_V(6); PG8_BAR; PG8_MMA(1, 1, At, B1); PG8_BAR;
;             PG8_LDB(B0, 1, 0); PG8_SCHED; PG8_LDA(At, 1, 0); PG8_STAGE(PG8_SA(0, 1), a2 + hstep);
;             PG8_WAIT_L(8); PG8_BAR; PG8_WAIT_L(0); PG8_MMA(0, 0, At, B0); PG8_BAR; PG8_SCHED;
;             PG8_LDB(B1, 1, 1); PG8_STAGE(PG8_SB(1, 0), b3);
;             PG8_BAR; PG8_WAIT_L(0); PG8_MMA(0, 1, At, B1); PG8_BAR;
;             PG8_LDA(At, 1, 1); PG8_STAGE(PG8_SA(1, 0), a3);
;             PG8_BAR; PG8_WAIT_L(0); PG8_MMA(1, 0, At, B0); PG8_BAR; PG8_SCHED;
	v_mfma_f32_16x16x32_bf16 v[28:31], v[226:229], v[152:155], v[28:31]
	v_mfma_f32_16x16x32_bf16 v[24:27], v[234:237], v[152:155], v[24:27]
	v_mfma_f32_16x16x32_bf16 v[20:23], v[226:229], v[190:193], v[20:23]
	v_mfma_f32_16x16x32_bf16 v[16:19], v[234:237], v[190:193], v[16:19]
	v_mfma_f32_16x16x32_bf16 v[12:15], v[226:229], v[202:205], v[12:15]
	v_mfma_f32_16x16x32_bf16 v[8:11], v[234:237], v[202:205], v[8:11]
	v_mfma_f32_16x16x32_bf16 v[4:7], v[226:229], v[210:213], v[4:7]
	v_mfma_f32_16x16x32_bf16 v[0:3], v[234:237], v[210:213], v[0:3]
	v_mfma_f32_16x16x32_bf16 v[28:31], v[230:233], v[186:189], v[28:31]
	s_add_i32 s39, 0, 0x18000
	v_mfma_f32_16x16x32_bf16 v[24:27], v[238:241], v[186:189], v[24:27]
	v_mfma_f32_16x16x32_bf16 v[20:23], v[230:233], v[194:197], v[20:23]
	v_mfma_f32_16x16x32_bf16 v[16:19], v[238:241], v[194:197], v[16:19]
	v_mfma_f32_16x16x32_bf16 v[12:15], v[230:233], v[206:209], v[12:15]
	v_mfma_f32_16x16x32_bf16 v[8:11], v[238:241], v[206:209], v[8:11]
	v_mfma_f32_16x16x32_bf16 v[4:7], v[230:233], v[214:217], v[4:7]
	s_setprio 0
	v_mfma_f32_16x16x32_bf16 v[0:3], v[238:241], v[214:217], v[0:3]
	s_barrier
	ds_read_b128 v[96:99], v199 offset:32768
	ds_read_b128 v[100:103], v199 offset:33792
	ds_read_b128 v[136:139], v199 offset:34816
	ds_read_b128 v[148:151], v199 offset:35840
	s_add_u32 s16, s22, 0x160000
	s_addc_u32 s17, s23, 0
	s_mov_b32 m0, s30
	ds_read_b128 v[152:155], v201 offset:32768
	ds_read_b128 v[186:189], v201 offset:33792
	ds_read_b128 v[190:193], v201 offset:34816
	ds_read_b128 v[194:197], v201 offset:35840
	ds_read_b128 v[202:205], v201 offset:36864
	ds_read_b128 v[206:209], v201 offset:37888
	ds_read_b128 v[210:213], v201 offset:38912
	ds_read_b128 v[214:217], v201 offset:39936
	global_load_lds_dwordx4 v142, s[16:17]
	s_mov_b32 m0, s31
	s_nop 0
	global_load_lds_dwordx4 v140, s[16:17]
	s_waitcnt lgkmcnt(8)
	s_setprio 1
	s_barrier
	s_waitcnt lgkmcnt(0)
	v_mfma_f32_16x16x32_bf16 v[132:135], v[96:99], v[152:155], v[132:135]
	v_mfma_f32_16x16x32_bf16 v[128:131], v[136:139], v[152:155], v[128:131]
	v_mfma_f32_16x16x32_bf16 v[124:127], v[96:99], v[190:193], v[124:127]
	v_mfma_f32_16x16x32_bf16 v[120:123], v[136:139], v[190:193], v[120:123]
	v_mfma_f32_16x16x32_bf16 v[116:119], v[96:99], v[202:205], v[116:119]
	v_mfma_f32_16x16x32_bf16 v[112:115], v[136:139], v[202:205], v[112:115]
	v_mfma_f32_16x16x32_bf16 v[108:111], v[96:99], v[210:213], v[108:111]
	v_mfma_f32_16x16x32_bf16 v[104:107], v[136:139], v[210:213], v[104:107]
	v_mfma_f32_16x16x32_bf16 v[132:135], v[100:103], v[186:189], v[132:135]
	v_mfma_f32_16x16x32_bf16 v[128:131], v[148:151], v[186:189], v[128:131]
	v_mfma_f32_16x16x32_bf16 v[124:127], v[100:103], v[194:197], v[124:127]
	v_mfma_f32_16x16x32_bf16 v[120:123], v[148:151], v[194:197], v[120:123]
	v_mfma_f32_16x16x32_bf16 v[116:119], v[100:103], v[206:209], v[116:119]
	v_mfma_f32_16x16x32_bf16 v[112:115], v[148:151], v[206:209], v[112:115]
	v_mfma_f32_16x16x32_bf16 v[108:111], v[100:103], v[214:217], v[108:111]
	s_setprio 0
	v_mfma_f32_16x16x32_bf16 v[104:107], v[148:151], v[214:217], v[104:107]
	s_barrier
	s_add_i32 s22, 0, 0x1c000
	s_add_i32 s16, s39, s27
	s_add_i32 m0, s16, 0xffffff80
	ds_read_b128 v[226:229], v199 offset:49152
	ds_read_b128 v[230:233], v199 offset:50176
	ds_read_b128 v[234:237], v199 offset:51200
	ds_read_b128 v[238:241], v199 offset:52224
	global_load_lds_dwordx4 v142, s[20:21] offset:128
	s_add_i32 m0, s16, 0x1f80
	s_nop 0
	global_load_lds_dwordx4 v140, s[20:21] offset:128
	s_waitcnt lgkmcnt(0)
	s_setprio 1
	s_barrier
	v_mfma_f32_16x16x32_bf16 v[60:63], v[226:229], v[152:155], v[60:63]
	v_mfma_f32_16x16x32_bf16 v[56:59], v[234:237], v[152:155], v[56:59]
	v_mfma_f32_16x16x32_bf16 v[52:55], v[226:229], v[190:193], v[52:55]
	v_mfma_f32_16x16x32_bf16 v[48:51], v[234:237], v[190:193], v[48:51]
	v_mfma_f32_16x16x32_bf16 v[44:47], v[226:229], v[202:205], v[44:47]
	v_mfma_f32_16x16x32_bf16 v[40:43], v[234:237], v[202:205], v[40:43]
	v_mfma_f32_16x16x32_bf16 v[36:39], v[226:229], v[210:213], v[36:39]
	v_mfma_f32_16x16x32_bf16 v[32:35], v[234:237], v[210:213], v[32:35]
	v_mfma_f32_16x16x32_bf16 v[60:63], v[230:233], v[186:189], v[60:63]
	s_mov_b32 m0, s34
	v_mfma_f32_16x16x32_bf16 v[56:59], v[238:241], v[186:189], v[56:59]
	v_lshl_add_u64 v[218:219], v[242:243], 0, s[94:95]
	v_mfma_f32_16x16x32_bf16 v[52:55], v[230:233], v[194:197], v[52:55]
	v_mfma_f32_16x16x32_bf16 v[48:51], v[238:241], v[194:197], v[48:51]
	v_mfma_f32_16x16x32_bf16 v[44:47], v[230:233], v[206:209], v[44:47]
	v_mfma_f32_16x16x32_bf16 v[40:43], v[238:241], v[206:209], v[40:43]
	v_mfma_f32_16x16x32_bf16 v[36:39], v[230:233], v[214:217], v[36:39]
	s_setprio 0
	v_mfma_f32_16x16x32_bf16 v[32:35], v[238:241], v[214:217], v[32:35]
	s_barrier
	ds_read_b128 v[152:155], v201 offset:49152
	ds_read_b128 v[186:189], v201 offset:50176
	ds_read_b128 v[190:193], v201 offset:51200
	ds_read_b128 v[194:197], v201 offset:52224
	ds_read_b128 v[202:205], v201 offset:53248
	ds_read_b128 v[206:209], v201 offset:54272
	ds_read_b128 v[210:213], v201 offset:55296
	ds_read_b128 v[214:217], v201 offset:56320
	global_load_lds_dwordx4 v[218:219], off
	s_add_i32 m0, s35, 0xffffff80
	s_nop 0
	global_load_lds_dwordx4 v140, s[100:101] offset:128
	s_waitcnt lgkmcnt(0)
	s_setprio 1
	s_barrier
; #define PG8_STAGE(bufoff, gbase) do { _Pragma("unroll") for (int _i = 0; _i < 2; ++_i) \
;         __builtin_amdgcn_global_load_lds((const unsigned*)((const char*)(gbase) + voff[_i]), (LAS unsigned*)(lds + (bufoff) + ldsw + _i * 8192), 16, 0, 0); } while (0)
; #define PG8_MMA(ai, bj, At, Bt) do { __builtin_amdgcn_s_setprio(1); _Pragma("unroll") for (int m = 0; m < 4; ++m) _Pragma("unroll") for (int n = 0; n < 2; ++n) _Pragma("unroll") for (int k = 0; k < 2; ++k) \
;         acc[ai][bj][m][n] = __builtin_amdgcn_mfma_f32_16x16x32_bf16(Bt[n][k], At[m][k], acc[ai][bj][m][n], 0, 0, 0); __builtin_amdgcn_s_setprio(0); } while (0)
; #define PG8_WAIT_V(n) asm volatile("s_waitcnt vmcnt(" #n ")" ::: "memory")
; #define PG8_BAR __builtin_amdgcn_s_barrier()
; template <class Epi>
; DI void gemm_phase(LAS unsigned char* lds, const Gemm g, const StaticOrder& S, const Epi& E) {
;     ...
;             PG8_STAGE(PG8_SB(1, 1), b3 + hstep);
;             PG8_WAIT_V(6); PG8_BAR; PG8_MMA(1, 1, At, B1); PG8_BAR;
;     template <bool LN, int BJ> DI void load_gb(unsigned col0, f32x4 (&gv)[2], f32x4 (&bv)[2]) const {
; #pragma unroll
;         for (int n = 0; n < 2; ++n) {
;             if (LN) { gv[n] = *(const f32x4*)(gam + col0 + BJ * HALF + n * 16) * ALPHA; bv[n] = *(const f32x4*)(bet + col0 + BJ * HALF + n * 16) * ALPHA; }
;             else { gv[n] = (f32x4){ALPHA, ALPHA, ALPHA, ALPHA}; bv[n] = (f32x4){0.f, 0.f, 0.f, 0.f}; }
;         }
;     }
;     template <bool LN> DI void run(const f32x4 (&acc)[2][2][4][2], const Unit& u, int wr, int wc, int fr, int fq) const {
;         const unsigned row0 = u.pm * BM + wr * 64 + fr, col0 = u.pn * BM + wc * 32 + 4 * fq;
;         f32x4 gv[2], bv[2];
;         load_gb<LN, 0>(col0, gv, bv);
;         batch<LN, 0, 0, 4>(acc, row0, col0, gv, bv);
;         batch<LN, 0, 4, 8>(acc, row0, col0, gv, bv);
;         batch<LN, 0, 8, 12>(acc, row0, col0, gv, bv);
;         batch<LN, 0, 12, 16>(acc, row0, col0, gv, bv);
	v_mfma_f32_16x16x32_bf16 v[92:95], v[96:99], v[152:155], v[92:95]
	v_mfma_f32_16x16x32_bf16 v[88:91], v[136:139], v[152:155], v[88:91]
	v_mfma_f32_16x16x32_bf16 v[84:87], v[96:99], v[190:193], v[84:87]
	v_mfma_f32_16x16x32_bf16 v[80:83], v[136:139], v[190:193], v[80:83]
	v_mfma_f32_16x16x32_bf16 v[76:79], v[96:99], v[202:205], v[76:79]
	v_mfma_f32_16x16x32_bf16 v[72:75], v[136:139], v[202:205], v[72:75]
	v_mfma_f32_16x16x32_bf16 v[68:71], v[96:99], v[210:213], v[68:71]
	v_mfma_f32_16x16x32_bf16 v[64:67], v[136:139], v[210:213], v[64:67]
	v_mfma_f32_16x16x32_bf16 v[92:95], v[100:103], v[186:189], v[92:95]
	v_mfma_f32_16x16x32_bf16 v[88:91], v[148:151], v[186:189], v[88:91]
	v_mfma_f32_16x16x32_bf16 v[84:87], v[100:103], v[194:197], v[84:87]
	v_mfma_f32_16x16x32_bf16 v[80:83], v[148:151], v[194:197], v[80:83]
	v_mfma_f32_16x16x32_bf16 v[76:79], v[100:103], v[206:209], v[76:79]
	v_mfma_f32_16x16x32_bf16 v[72:75], v[148:151], v[206:209], v[72:75]
	v_mfma_f32_16x16x32_bf16 v[68:71], v[100:103], v[214:217], v[68:71]
	s_setprio 0
	v_mfma_f32_16x16x32_bf16 v[64:67], v[148:151], v[214:217], v[64:67]
	s_barrier
	s_add_u32 s16, s20, 0x160080
	s_addc_u32 s17, s21, 0
	s_add_i32 s20, s22, s27
	s_mov_b32 m0, s20
	s_nop 0
	global_load_lds_dwordx4 v142, s[16:17]
	s_add_i32 m0, s20, 0x2000
	s_nop 0
	global_load_lds_dwordx4 v140, s[16:17]
	s_waitcnt vmcnt(6)
	s_setprio 1
	s_barrier
	v_mfma_f32_16x16x32_bf16 v[28:31], v[226:229], v[152:155], v[28:31]
	v_mfma_f32_16x16x32_bf16 v[24:27], v[234:237], v[152:155], v[24:27]
	v_mfma_f32_16x16x32_bf16 v[20:23], v[226:229], v[190:193], v[20:23]
	v_mfma_f32_16x16x32_bf16 v[16:19], v[234:237], v[190:193], v[16:19]
	v_mfma_f32_16x16x32_bf16 v[12:15], v[226:229], v[202:205], v[12:15]
	v_mfma_f32_16x16x32_bf16 v[8:11], v[234:237], v[202:205], v[8:11]
	v_mfma_f32_16x16x32_bf16 v[4:7], v[226:229], v[210:213], v[4:7]
	v_mfma_f32_16x16x32_bf16 v[0:3], v[234:237], v[210:213], v[0:3]
	v_mfma_f32_16x16x32_bf16 v[28:31], v[230:233], v[186:189], v[28:31]
	s_add_i32 s33, s33, 2
	v_mfma_f32_16x16x32_bf16 v[24:27], v[238:241], v[186:189], v[24:27]
	s_add_u32 s4, s4, 0x100
	v_mfma_f32_16x16x32_bf16 v[20:23], v[230:233], v[194:197], v[20:23]
	s_addc_u32 s5, s5, 0
	v_mfma_f32_16x16x32_bf16 v[16:19], v[238:241], v[194:197], v[16:19]
	s_cmpk_gt_u32 s33, 0x55
	v_mfma_f32_16x16x32_bf16 v[12:15], v[230:233], v[206:209], v[12:15]
	s_mov_b64 s[16:17], s[18:19]
	v_mfma_f32_16x16x32_bf16 v[8:11], v[238:241], v[206:209], v[8:11]
	v_mfma_f32_16x16x32_bf16 v[4:7], v[230:233], v[214:217], v[4:7]
	s_setprio 0
	v_mfma_f32_16x16x32_bf16 v[0:3], v[238:241], v[214:217], v[0:3]
	s_barrier
	s_cbranch_scc0 .LBB0_134
	v_lshl_or_b32 v158, s2, 8, v200
	v_lshlrev_b64 v[100:101], 2, v[158:159]
	v_lshl_add_u64 v[150:151], s[12:13], 0, v[100:101]
	global_load_dwordx4 v[96:99], v[150:151], off
	v_lshl_add_u64 v[152:153], s[14:15], 0, v[100:101]
	v_lshl_add_u32 v203, s3, 8, v198
	v_lshlrev_b32_e32 v202, 11, v203
	v_add_u32_e32 v148, v202, v158
	v_mov_b32_e32 v149, v159
	v_lshlrev_b32_e32 v136, 1, v203
	v_mov_b32_e32 v137, v159
	v_lshlrev_b64 v[220:221], 2, v[148:149]
	v_lshl_add_u64 v[154:155], v[136:137], 2, s[96:97]
	v_lshl_add_u64 v[136:137], s[90:91], 0, v[220:221]
	v_or_b32_e32 v204, 16, v158
	v_or_b32_e32 v138, 16, v203
	v_lshlrev_b32_e32 v149, 11, v138
	s_waitcnt vmcnt(0)
	v_pk_mul_f32 v[192:193], v[98:99], s[78:79] op_sel_hi:[1,0]
	v_pk_mul_f32 v[194:195], v[96:97], s[78:79] op_sel_hi:[1,0]
	global_load_dwordx4 v[100:103], v[152:153], off
	global_load_dwordx4 v[96:99], v[150:151], off offset:64
	global_load_dwordx2 v[218:219], v[154:155], off
	global_load_dwordx4 v[206:209], v[136:137], off
	v_add_u32_e32 v136, v202, v204
	v_mov_b32_e32 v137, v159
	v_lshl_add_u64 v[136:137], v[136:137], 2, s[90:91]
	global_load_dwordx4 v[210:213], v[136:137], off
	v_lshlrev_b32_e32 v136, 1, v138
	v_mov_b32_e32 v137, v159
	v_lshl_add_u64 v[186:187], v[136:137], 2, s[96:97]
	v_add_u32_e32 v136, v149, v158
	v_lshl_add_u64 v[136:137], v[136:137], 2, s[90:91]
	global_load_dwordx2 v[196:197], v[186:187], off
	global_load_dwordx4 v[214:217], v[136:137], off
	v_add_u32_e32 v136, v149, v204
	v_mov_b32_e32 v137, v159
	v_lshl_add_u64 v[136:137], v[136:137], 2, s[90:91]
	global_load_dwordx4 v[136:139], v[136:137], off
	s_waitcnt vmcnt(0)
	v_pk_mul_f32 v[188:189], v[98:99], s[78:79] op_sel_hi:[1,0]
	v_pk_mul_f32 v[190:191], v[96:97], s[78:79] op_sel_hi:[1,0]
	global_load_dwordx4 v[96:99], v[152:153], off offset:64
	v_sub_f32_e32 v207, v207, v218
	v_sub_f32_e32 v206, v206, v218
	v_sub_f32_e32 v209, v209, v218
	v_sub_f32_e32 v208, v208, v218
	v_pk_mul_f32 v[208:209], v[218:219], v[208:209] op_sel:[1,0]
	v_pk_mul_f32 v[206:207], v[218:219], v[206:207] op_sel:[1,0]
	v_pk_fma_f32 v[134:135], v[192:193], v[208:209], v[134:135]
	v_pk_fma_f32 v[132:133], v[194:195], v[206:207], v[132:133]
	v_pk_fma_f32 v[134:135], v[102:103], s[78:79], v[134:135] op_sel_hi:[1,0,1]
	v_pk_fma_f32 v[132:133], v[100:101], s[78:79], v[132:133] op_sel_hi:[1,0,1]
	v_lshl_add_u64 v[206:207], s[88:89], 0, v[220:221]
	global_store_dwordx4 v[206:207], v[132:135], off
	s_nop 1
	v_sub_f32_e32 v133, v211, v218
	v_sub_f32_e32 v132, v210, v218
	v_sub_f32_e32 v135, v213, v218
	v_sub_f32_e32 v134, v212, v218
	v_pk_mul_f32 v[134:135], v[218:219], v[134:135] op_sel:[1,0]
	v_pk_mul_f32 v[132:133], v[218:219], v[132:133] op_sel:[1,0]
	v_pk_fma_f32 v[130:131], v[188:189], v[134:135], v[130:131]
	v_pk_fma_f32 v[128:129], v[190:191], v[132:133], v[128:129]
	v_or_b32_e32 v132, 16, v148
	v_mov_b32_e32 v133, v159
	v_lshl_add_u64 v[132:133], v[132:133], 2, s[88:89]
	s_waitcnt vmcnt(0)
;     template <bool LN, int BJ, int LO, int HI> DI void batch(const f32x4 (&acc)[2][2][4][2], unsigned row0, unsigned col0, const f32x4 (&gv)[2], const f32x4 (&bv)[2]) const {
;         f32x4 r[HI - LO]; float mean[(HI - LO) / 2], rstd[(HI - LO) / 2];
; #pragma unroll
;         for (int i = LO; i < HI; ++i) { const int ai = i >> 3, m = (i >> 1) & 3, n = i & 1; const unsigned row = row0 + ai * HALF + m * 16;
;             if (n == 0) { mean[(i - LO) >> 1] = 0.f; rstd[(i - LO) >> 1] = 1.f;
;                 if (LN) { const float2 st = *(const float2*)(stats + row * 2u); mean[(i - LO) >> 1] = st.x; rstd[(i - LO) >> 1] = st.y; } }
;             r[i - LO] = *(const f32x4*)(src + (row * (unsigned)DM + col0 + BJ * HALF + n * 16)); }
; #pragma unroll
;         for (int i = LO; i < HI; ++i) { const int ai = i >> 3, m = (i >> 1) & 3, n = i & 1; const unsigned row = row0 + ai * HALF + m * 16;
;             *(f32x4*)(Y + (row * (unsigned)DM + col0 + BJ * HALF + n * 16)) = acc[ai][BJ][m][n] + ((r[i - LO] - mean[(i - LO) >> 1]) * rstd[(i - LO) >> 1]) * gv[n] + bv[n]; }
	v_pk_fma_f32 v[130:131], v[98:99], s[78:79], v[130:131] op_sel_hi:[1,0,1]
	v_pk_fma_f32 v[128:129], v[96:97], s[78:79], v[128:129] op_sel_hi:[1,0,1]
	global_store_dwordx4 v[132:133], v[128:131], off
	s_nop 1
	v_sub_f32_e32 v129, v215, v196
	v_sub_f32_e32 v128, v214, v196
	v_sub_f32_e32 v131, v217, v196
	v_sub_f32_e32 v130, v216, v196
	v_pk_mul_f32 v[130:131], v[196:197], v[130:131] op_sel:[1,0]
	v_pk_mul_f32 v[128:129], v[196:197], v[128:129] op_sel:[1,0]
	v_pk_fma_f32 v[126:127], v[192:193], v[130:131], v[126:127]
	v_pk_fma_f32 v[124:125], v[194:195], v[128:129], v[124:125]
	v_add_u32_e32 v128, 0x8000, v148
	v_mov_b32_e32 v129, v159
	v_pk_fma_f32 v[126:127], v[102:103], s[78:79], v[126:127] op_sel_hi:[1,0,1]
	v_pk_fma_f32 v[124:125], v[100:101], s[78:79], v[124:125] op_sel_hi:[1,0,1]
	v_lshl_add_u64 v[128:129], v[128:129], 2, s[88:89]
	global_store_dwordx4 v[128:129], v[124:127], off
	s_nop 1
	v_sub_f32_e32 v125, v137, v196
	v_sub_f32_e32 v124, v136, v196
	v_sub_f32_e32 v127, v139, v196
	v_sub_f32_e32 v126, v138, v196
	v_pk_mul_f32 v[126:127], v[196:197], v[126:127] op_sel:[1,0]
	v_pk_mul_f32 v[124:125], v[196:197], v[124:125] op_sel:[1,0]
	v_pk_fma_f32 v[122:123], v[188:189], v[126:127], v[122:123]
	v_pk_fma_f32 v[120:121], v[190:191], v[124:125], v[120:121]
	v_add_u32_e32 v124, 0x8010, v148
	v_mov_b32_e32 v125, v159
	v_pk_fma_f32 v[122:123], v[98:99], s[78:79], v[122:123] op_sel_hi:[1,0,1]
	v_pk_fma_f32 v[120:121], v[96:97], s[78:79], v[120:121] op_sel_hi:[1,0,1]
	v_lshl_add_u64 v[124:125], v[124:125], 2, s[88:89]
	global_store_dwordx4 v[124:125], v[120:123], off
	s_nop 1
	v_or_b32_e32 v122, 32, v203
	v_lshlrev_b32_e32 v124, 11, v122
	v_lshlrev_b32_e32 v120, 1, v122
	v_mov_b32_e32 v121, v159
	v_add_u32_e32 v122, v124, v158
	v_mov_b32_e32 v123, v159
	v_lshl_add_u64 v[120:121], v[120:121], 2, s[96:97]
	v_lshl_add_u64 v[122:123], v[122:123], 2, s[90:91]
	global_load_dwordx2 v[138:139], v[120:121], off
	global_load_dwordx4 v[126:129], v[122:123], off
	v_add_u32_e32 v122, v124, v204
	v_mov_b32_e32 v123, v159
	v_lshl_add_u64 v[122:123], v[122:123], 2, s[90:91]
	global_load_dwordx4 v[130:133], v[122:123], off
	v_or_b32_e32 v125, 48, v203
	v_lshlrev_b32_e32 v122, 1, v125
	v_lshlrev_b32_e32 v125, 11, v125
	v_mov_b32_e32 v123, v159
	v_add_u32_e32 v134, v125, v158
	v_mov_b32_e32 v135, v159
	v_lshl_add_u64 v[122:123], v[122:123], 2, s[96:97]
	v_lshl_add_u64 v[134:135], v[134:135], 2, s[90:91]
	global_load_dwordx2 v[196:197], v[122:123], off
	v_add_u32_e32 v206, v125, v204
	global_load_dwordx4 v[134:137], v[134:135], off
	v_mov_b32_e32 v207, v159
	v_lshl_add_u64 v[206:207], v[206:207], 2, s[90:91]
	global_load_dwordx4 v[206:209], v[206:207], off
	s_waitcnt vmcnt(0)
	v_sub_f32_e32 v127, v127, v138
	v_sub_f32_e32 v126, v126, v138
	v_sub_f32_e32 v129, v129, v138
	v_sub_f32_e32 v128, v128, v138
	v_pk_mul_f32 v[128:129], v[138:139], v[128:129] op_sel:[1,0]
	v_pk_mul_f32 v[126:127], v[138:139], v[126:127] op_sel:[1,0]
	v_pk_fma_f32 v[118:119], v[192:193], v[128:129], v[118:119]
	v_pk_fma_f32 v[116:117], v[194:195], v[126:127], v[116:117]
	v_add_u32_e32 v126, 0x10000, v148
	v_mov_b32_e32 v127, v159
	v_pk_fma_f32 v[118:119], v[102:103], s[78:79], v[118:119] op_sel_hi:[1,0,1]
	v_pk_fma_f32 v[116:117], v[100:101], s[78:79], v[116:117] op_sel_hi:[1,0,1]
	v_lshl_add_u64 v[126:127], v[126:127], 2, s[88:89]
	global_store_dwordx4 v[126:127], v[116:119], off
	s_nop 1
	v_sub_f32_e32 v117, v131, v138
	v_sub_f32_e32 v116, v130, v138
	v_sub_f32_e32 v119, v133, v138
	v_sub_f32_e32 v118, v132, v138
	v_pk_mul_f32 v[118:119], v[138:139], v[118:119] op_sel:[1,0]
	v_pk_mul_f32 v[116:117], v[138:139], v[116:117] op_sel:[1,0]
	v_pk_fma_f32 v[114:115], v[188:189], v[118:119], v[114:115]
	v_pk_fma_f32 v[112:113], v[190:191], v[116:117], v[112:113]
	v_add_u32_e32 v116, 0x10010, v148
	v_mov_b32_e32 v117, v159
	v_pk_fma_f32 v[114:115], v[98:99], s[78:79], v[114:115] op_sel_hi:[1,0,1]
	v_pk_fma_f32 v[112:113], v[96:97], s[78:79], v[112:113] op_sel_hi:[1,0,1]
	v_lshl_add_u64 v[116:117], v[116:117], 2, s[88:89]
	global_store_dwordx4 v[116:117], v[112:115], off
	s_nop 1
	v_sub_f32_e32 v113, v135, v196
	v_sub_f32_e32 v112, v134, v196
	v_sub_f32_e32 v115, v137, v196
	v_sub_f32_e32 v114, v136, v196
	v_pk_mul_f32 v[114:115], v[196:197], v[114:115] op_sel:[1,0]
	v_pk_mul_f32 v[112:113], v[196:197], v[112:113] op_sel:[1,0]
	v_pk_fma_f32 v[110:111], v[192:193], v[114:115], v[110:111]
	v_pk_fma_f32 v[108:109], v[194:195], v[112:113], v[108:109]
	v_add_u32_e32 v112, 0x18000, v148
	v_mov_b32_e32 v113, v159
	v_pk_fma_f32 v[110:111], v[102:103], s[78:79], v[110:111] op_sel_hi:[1,0,1]
	v_pk_fma_f32 v[108:109], v[100:101], s[78:79], v[108:109] op_sel_hi:[1,0,1]
	v_lshl_add_u64 v[112:113], v[112:113], 2, s[88:89]
	global_store_dwordx4 v[112:113], v[108:111], off
	s_nop 1
	v_sub_f32_e32 v109, v207, v196
	v_sub_f32_e32 v108, v206, v196
	v_sub_f32_e32 v111, v209, v196
	v_sub_f32_e32 v110, v208, v196
	v_pk_mul_f32 v[110:111], v[196:197], v[110:111] op_sel:[1,0]
	v_pk_mul_f32 v[108:109], v[196:197], v[108:109] op_sel:[1,0]
	v_pk_fma_f32 v[106:107], v[188:189], v[110:111], v[106:107]
	v_pk_fma_f32 v[104:105], v[190:191], v[108:109], v[104:105]
	v_add_u32_e32 v108, 0x18010, v148
	v_mov_b32_e32 v109, v159
	v_pk_fma_f32 v[106:107], v[98:99], s[78:79], v[106:107] op_sel_hi:[1,0,1]
	v_pk_fma_f32 v[104:105], v[96:97], s[78:79], v[104:105] op_sel_hi:[1,0,1]
	v_lshl_add_u64 v[108:109], v[108:109], 2, s[88:89]
	global_store_dwordx4 v[108:109], v[104:107], off
	s_nop 1
	v_add_u32_e32 v106, 0x80, v203
	v_lshlrev_b32_e32 v114, 11, v106
	v_lshlrev_b32_e32 v104, 1, v106
	v_mov_b32_e32 v105, v159
	v_add_u32_e32 v106, v114, v158
	v_mov_b32_e32 v107, v159
	v_lshl_add_u64 v[104:105], v[104:105], 2, s[96:97]
	v_lshl_add_u64 v[106:107], v[106:107], 2, s[90:91]
	global_load_dwordx2 v[112:113], v[104:105], off
	global_load_dwordx4 v[108:111], v[106:107], off
	v_add_u32_e32 v106, v114, v204
	v_mov_b32_e32 v107, v159
	v_lshl_add_u64 v[106:107], v[106:107], 2, s[90:91]
	global_load_dwordx4 v[116:119], v[106:107], off
	v_add_u32_e32 v115, 0x90, v203
	v_lshlrev_b32_e32 v106, 1, v115
	v_lshlrev_b32_e32 v115, 11, v115
	v_mov_b32_e32 v107, v159
	v_add_u32_e32 v126, v115, v158
	v_mov_b32_e32 v127, v159
	v_lshl_add_u64 v[106:107], v[106:107], 2, s[96:97]
	v_lshl_add_u64 v[126:127], v[126:127], 2, s[90:91]
	global_load_dwordx2 v[134:135], v[106:107], off
	v_add_u32_e32 v130, v115, v204
	global_load_dwordx4 v[126:129], v[126:127], off
	v_mov_b32_e32 v131, v159
	v_lshl_add_u64 v[130:131], v[130:131], 2, s[90:91]
	global_load_dwordx4 v[130:133], v[130:131], off
	s_waitcnt vmcnt(0)
;     template <bool LN, int BJ, int LO, int HI> DI void batch(const f32x4 (&acc)[2][2][4][2], unsigned row0, unsigned col0, const f32x4 (&gv)[2], const f32x4 (&bv)[2]) const {
;         f32x4 r[HI - LO]; float mean[(HI - LO) / 2], rstd[(HI - LO) / 2];
; #pragma unroll
;         for (int i = LO; i < HI; ++i) { const int ai = i >> 3, m = (i >> 1) & 3, n = i & 1; const unsigned row = row0 + ai * HALF + m * 16;
;             if (n == 0) { mean[(i - LO) >> 1] = 0.f; rstd[(i - LO) >> 1] = 1.f;
;                 if (LN) { const float2 st = *(const float2*)(stats + row * 2u); mean[(i - LO) >> 1] = st.x; rstd[(i - LO) >> 1] = st.y; } }
;             r[i - LO] = *(const f32x4*)(src + (row * (unsigned)DM + col0 + BJ * HALF + n * 16)); }
; #pragma unroll
;         for (int i = LO; i < HI; ++i) { const int ai = i >> 3, m = (i >> 1) & 3, n = i & 1; const unsigned row = row0 + ai * HALF + m * 16;
;             *(f32x4*)(Y + (row * (unsigned)DM + col0 + BJ * HALF + n * 16)) = acc[ai][BJ][m][n] + ((r[i - LO] - mean[(i - LO) >> 1]) * rstd[(i - LO) >> 1]) * gv[n] + bv[n]; }
;     template <bool LN, int BJ> DI void load_gb(unsigned col0, f32x4 (&gv)[2], f32x4 (&bv)[2]) const {
; #pragma unroll
;         for (int n = 0; n < 2; ++n) {
;             if (LN) { gv[n] = *(const f32x4*)(gam + col0 + BJ * HALF + n * 16) * ALPHA; bv[n] = *(const f32x4*)(bet + col0 + BJ * HALF + n * 16) * ALPHA; }
;             else { gv[n] = (f32x4){ALPHA, ALPHA, ALPHA, ALPHA}; bv[n] = (f32x4){0.f, 0.f, 0.f, 0.f}; }
;         }
;     }
;     template <bool LN> DI void run(const f32x4 (&acc)[2][2][4][2], const Unit& u, int wr, int wc, int fr, int fq) const {
;         const unsigned row0 = u.pm * BM + wr * 64 + fr, col0 = u.pn * BM + wc * 32 + 4 * fq;
;         f32x4 gv[2], bv[2];
;         load_gb<LN, 0>(col0, gv, bv);
;         batch<LN, 0, 0, 4>(acc, row0, col0, gv, bv);
;         batch<LN, 0, 4, 8>(acc, row0, col0, gv, bv);
;         batch<LN, 0, 8, 12>(acc, row0, col0, gv, bv);
;         batch<LN, 0, 12, 16>(acc, row0, col0, gv, bv);
;         load_gb<LN, 1>(col0, gv, bv);
	v_sub_f32_e32 v109, v109, v112
	v_sub_f32_e32 v108, v108, v112
	v_sub_f32_e32 v111, v111, v112
	v_sub_f32_e32 v110, v110, v112
	v_pk_mul_f32 v[110:111], v[112:113], v[110:111] op_sel:[1,0]
	v_pk_mul_f32 v[108:109], v[112:113], v[108:109] op_sel:[1,0]
	v_pk_fma_f32 v[94:95], v[192:193], v[110:111], v[94:95]
	v_pk_fma_f32 v[92:93], v[194:195], v[108:109], v[92:93]
	v_add_u32_e32 v108, 0x40000, v148
	v_mov_b32_e32 v109, v159
	v_pk_fma_f32 v[94:95], v[102:103], s[78:79], v[94:95] op_sel_hi:[1,0,1]
	v_pk_fma_f32 v[92:93], v[100:101], s[78:79], v[92:93] op_sel_hi:[1,0,1]
	v_lshl_add_u64 v[108:109], v[108:109], 2, s[88:89]
	global_store_dwordx4 v[108:109], v[92:95], off
	s_nop 1
	v_sub_f32_e32 v93, v117, v112
	v_sub_f32_e32 v92, v116, v112
	v_sub_f32_e32 v95, v119, v112
	v_sub_f32_e32 v94, v118, v112
	v_pk_mul_f32 v[94:95], v[112:113], v[94:95] op_sel:[1,0]
	v_pk_mul_f32 v[92:93], v[112:113], v[92:93] op_sel:[1,0]
	v_pk_fma_f32 v[90:91], v[188:189], v[94:95], v[90:91]
	v_pk_fma_f32 v[88:89], v[190:191], v[92:93], v[88:89]
	v_add_u32_e32 v92, 0x40010, v148
	v_mov_b32_e32 v93, v159
	v_pk_fma_f32 v[90:91], v[98:99], s[78:79], v[90:91] op_sel_hi:[1,0,1]
	v_pk_fma_f32 v[88:89], v[96:97], s[78:79], v[88:89] op_sel_hi:[1,0,1]
	v_lshl_add_u64 v[92:93], v[92:93], 2, s[88:89]
	global_store_dwordx4 v[92:93], v[88:91], off
	s_nop 1
	v_sub_f32_e32 v89, v127, v134
	v_sub_f32_e32 v88, v126, v134
	v_sub_f32_e32 v91, v129, v134
	v_sub_f32_e32 v90, v128, v134
	v_pk_mul_f32 v[90:91], v[134:135], v[90:91] op_sel:[1,0]
	v_pk_mul_f32 v[88:89], v[134:135], v[88:89] op_sel:[1,0]
	v_pk_fma_f32 v[86:87], v[192:193], v[90:91], v[86:87]
	v_pk_fma_f32 v[84:85], v[194:195], v[88:89], v[84:85]
	v_add_u32_e32 v88, 0x48000, v148
	v_mov_b32_e32 v89, v159
	v_pk_fma_f32 v[86:87], v[102:103], s[78:79], v[86:87] op_sel_hi:[1,0,1]
	v_pk_fma_f32 v[84:85], v[100:101], s[78:79], v[84:85] op_sel_hi:[1,0,1]
	v_lshl_add_u64 v[88:89], v[88:89], 2, s[88:89]
	global_store_dwordx4 v[88:89], v[84:87], off
	s_nop 1
	v_sub_f32_e32 v85, v131, v134
	v_sub_f32_e32 v84, v130, v134
	v_sub_f32_e32 v87, v133, v134
	v_sub_f32_e32 v86, v132, v134
	v_pk_mul_f32 v[86:87], v[134:135], v[86:87] op_sel:[1,0]
	v_pk_mul_f32 v[84:85], v[134:135], v[84:85] op_sel:[1,0]
	v_pk_fma_f32 v[82:83], v[188:189], v[86:87], v[82:83]
	v_pk_fma_f32 v[80:81], v[190:191], v[84:85], v[80:81]
	v_add_u32_e32 v84, 0x48010, v148
	v_mov_b32_e32 v85, v159
	v_pk_fma_f32 v[82:83], v[98:99], s[78:79], v[82:83] op_sel_hi:[1,0,1]
	v_pk_fma_f32 v[80:81], v[96:97], s[78:79], v[80:81] op_sel_hi:[1,0,1]
	v_lshl_add_u64 v[84:85], v[84:85], 2, s[88:89]
	global_store_dwordx4 v[84:85], v[80:83], off
	s_nop 1
	v_add_u32_e32 v82, 0xa0, v203
	v_lshlrev_b32_e32 v80, 1, v82
	v_mov_b32_e32 v81, v159
	v_lshlrev_b32_e32 v116, 11, v82
	v_lshl_add_u64 v[108:109], v[80:81], 2, s[96:97]
	v_add_u32_e32 v80, v116, v158
	v_lshl_add_u64 v[80:81], v[80:81], 2, s[90:91]
	global_load_dwordx2 v[112:113], v[108:109], off
	v_add_u32_e32 v84, v116, v204
	global_load_dwordx4 v[80:83], v[80:81], off
	v_mov_b32_e32 v85, v159
	v_lshl_add_u64 v[84:85], v[84:85], 2, s[90:91]
	global_load_dwordx4 v[84:87], v[84:85], off
	v_add_u32_e32 v90, 0xb0, v203
	v_lshlrev_b32_e32 v88, 1, v90
	v_mov_b32_e32 v89, v159
	v_lshlrev_b32_e32 v117, 11, v90
	v_lshl_add_u64 v[110:111], v[88:89], 2, s[96:97]
	v_add_u32_e32 v88, v117, v158
	v_lshl_add_u64 v[88:89], v[88:89], 2, s[90:91]
	global_load_dwordx2 v[118:119], v[110:111], off
	v_add_u32_e32 v92, v117, v204
	global_load_dwordx4 v[88:91], v[88:89], off
	v_mov_b32_e32 v93, v159
	v_lshl_add_u64 v[92:93], v[92:93], 2, s[90:91]
	global_load_dwordx4 v[92:95], v[92:93], off
	s_waitcnt vmcnt(0)
	v_sub_f32_e32 v81, v81, v112
	v_sub_f32_e32 v80, v80, v112
	v_sub_f32_e32 v83, v83, v112
	v_sub_f32_e32 v82, v82, v112
	v_pk_mul_f32 v[82:83], v[112:113], v[82:83] op_sel:[1,0]
	v_pk_mul_f32 v[80:81], v[112:113], v[80:81] op_sel:[1,0]
	v_pk_fma_f32 v[78:79], v[192:193], v[82:83], v[78:79]
	v_pk_fma_f32 v[76:77], v[194:195], v[80:81], v[76:77]
	v_add_u32_e32 v80, 0x50000, v148
	v_mov_b32_e32 v81, v159
	v_pk_fma_f32 v[78:79], v[102:103], s[78:79], v[78:79] op_sel_hi:[1,0,1]
	v_pk_fma_f32 v[76:77], v[100:101], s[78:79], v[76:77] op_sel_hi:[1,0,1]
	v_lshl_add_u64 v[80:81], v[80:81], 2, s[88:89]
	global_store_dwordx4 v[80:81], v[76:79], off
	s_nop 1
	v_sub_f32_e32 v77, v85, v112
	v_sub_f32_e32 v76, v84, v112
	v_sub_f32_e32 v79, v87, v112
	v_sub_f32_e32 v78, v86, v112
	v_pk_mul_f32 v[78:79], v[112:113], v[78:79] op_sel:[1,0]
	v_pk_mul_f32 v[76:77], v[112:113], v[76:77] op_sel:[1,0]
	v_pk_fma_f32 v[74:75], v[188:189], v[78:79], v[74:75]
	v_pk_fma_f32 v[72:73], v[190:191], v[76:77], v[72:73]
	v_add_u32_e32 v76, 0x50010, v148
	v_mov_b32_e32 v77, v159
	v_pk_fma_f32 v[74:75], v[98:99], s[78:79], v[74:75] op_sel_hi:[1,0,1]
	v_pk_fma_f32 v[72:73], v[96:97], s[78:79], v[72:73] op_sel_hi:[1,0,1]
	v_lshl_add_u64 v[76:77], v[76:77], 2, s[88:89]
	global_store_dwordx4 v[76:77], v[72:75], off
	s_nop 1
	v_sub_f32_e32 v73, v89, v118
	v_sub_f32_e32 v72, v88, v118
	v_sub_f32_e32 v75, v91, v118
	v_sub_f32_e32 v74, v90, v118
	v_pk_mul_f32 v[74:75], v[118:119], v[74:75] op_sel:[1,0]
	v_pk_mul_f32 v[72:73], v[118:119], v[72:73] op_sel:[1,0]
	v_pk_fma_f32 v[70:71], v[192:193], v[74:75], v[70:71]
	v_pk_fma_f32 v[68:69], v[194:195], v[72:73], v[68:69]
	v_add_u32_e32 v72, 0x58000, v148
	v_mov_b32_e32 v73, v159
	v_pk_fma_f32 v[70:71], v[102:103], s[78:79], v[70:71] op_sel_hi:[1,0,1]
	v_pk_fma_f32 v[68:69], v[100:101], s[78:79], v[68:69] op_sel_hi:[1,0,1]
	v_lshl_add_u64 v[72:73], v[72:73], 2, s[88:89]
	global_store_dwordx4 v[72:73], v[68:71], off
	s_nop 1
	v_sub_f32_e32 v69, v93, v118
	v_sub_f32_e32 v68, v92, v118
	v_sub_f32_e32 v71, v95, v118
	v_sub_f32_e32 v70, v94, v118
	v_pk_mul_f32 v[70:71], v[118:119], v[70:71] op_sel:[1,0]
	v_pk_mul_f32 v[68:69], v[118:119], v[68:69] op_sel:[1,0]
	v_pk_fma_f32 v[66:67], v[188:189], v[70:71], v[66:67]
	v_pk_fma_f32 v[64:65], v[190:191], v[68:69], v[64:65]
	v_add_u32_e32 v68, 0x58010, v148
	v_mov_b32_e32 v69, v159
	v_pk_fma_f32 v[66:67], v[98:99], s[78:79], v[66:67] op_sel_hi:[1,0,1]
	v_pk_fma_f32 v[64:65], v[96:97], s[78:79], v[64:65] op_sel_hi:[1,0,1]
	v_lshl_add_u64 v[68:69], v[68:69], 2, s[88:89]
	global_store_dwordx4 v[68:69], v[64:67], off
	global_load_dwordx4 v[64:67], v[150:151], off offset:512
	v_or_b32_e32 v119, 0x80, v158
	v_add_u32_e32 v72, v202, v119
	v_mov_b32_e32 v73, v159
	v_lshl_add_u64 v[72:73], v[72:73], 2, s[90:91]
	v_or_b32_e32 v118, 0x90, v158
	v_add_u32_e32 v158, v202, v118
	s_waitcnt vmcnt(0)
;     template <bool LN, int BJ, int LO, int HI> DI void batch(const f32x4 (&acc)[2][2][4][2], unsigned row0, unsigned col0, const f32x4 (&gv)[2], const f32x4 (&bv)[2]) const {
;         f32x4 r[HI - LO]; float mean[(HI - LO) / 2], rstd[(HI - LO) / 2];
; #pragma unroll
;         for (int i = LO; i < HI; ++i) { const int ai = i >> 3, m = (i >> 1) & 3, n = i & 1; const unsigned row = row0 + ai * HALF + m * 16;
;             if (n == 0) { mean[(i - LO) >> 1] = 0.f; rstd[(i - LO) >> 1] = 1.f;
;                 if (LN) { const float2 st = *(const float2*)(stats + row * 2u); mean[(i - LO) >> 1] = st.x; rstd[(i - LO) >> 1] = st.y; } }
;             r[i - LO] = *(const f32x4*)(src + (row * (unsigned)DM + col0 + BJ * HALF + n * 16)); }
; #pragma unroll
;         for (int i = LO; i < HI; ++i) { const int ai = i >> 3, m = (i >> 1) & 3, n = i & 1; const unsigned row = row0 + ai * HALF + m * 16;
;             *(f32x4*)(Y + (row * (unsigned)DM + col0 + BJ * HALF + n * 16)) = acc[ai][BJ][m][n] + ((r[i - LO] - mean[(i - LO) >> 1]) * rstd[(i - LO) >> 1]) * gv[n] + bv[n]; }
;     template <bool LN> DI void run(const f32x4 (&acc)[2][2][4][2], const Unit& u, int wr, int wc, int fr, int fq) const {
;     ...
;         load_gb<LN, 1>(col0, gv, bv);
;         batch<LN, 1, 0, 8>(acc, row0, col0, gv, bv);
	v_pk_mul_f32 v[96:97], v[66:67], s[78:79] op_sel_hi:[1,0]
	v_pk_mul_f32 v[98:99], v[64:65], s[78:79] op_sel_hi:[1,0]
	global_load_dwordx4 v[68:71], v[152:153], off offset:512
	global_load_dwordx4 v[64:67], v[150:151], off offset:576
	global_load_dwordx2 v[138:139], v[154:155], off
	global_load_dwordx4 v[126:129], v[72:73], off
	v_lshl_add_u64 v[72:73], v[158:159], 2, s[90:91]
	v_add_u32_e32 v158, v149, v119
	s_waitcnt vmcnt(0)
	v_pk_mul_f32 v[92:93], v[66:67], s[78:79] op_sel_hi:[1,0]
	v_pk_mul_f32 v[94:95], v[64:65], s[78:79] op_sel_hi:[1,0]
	global_load_dwordx4 v[64:67], v[152:153], off offset:576
	global_load_dwordx4 v[130:133], v[72:73], off
	global_load_dwordx2 v[112:113], v[186:187], off
	v_lshl_add_u64 v[72:73], v[158:159], 2, s[90:91]
	global_load_dwordx4 v[134:137], v[72:73], off
	v_add_u32_e32 v158, v149, v118
	v_lshl_add_u64 v[72:73], v[158:159], 2, s[90:91]
	global_load_dwordx4 v[88:91], v[72:73], off
	global_load_dwordx2 v[102:103], v[120:121], off
	v_add_u32_e32 v158, v124, v119
	v_lshl_add_u64 v[72:73], v[158:159], 2, s[90:91]
	global_load_dwordx4 v[84:87], v[72:73], off
	v_add_u32_e32 v158, v124, v118
	v_lshl_add_u64 v[72:73], v[158:159], 2, s[90:91]
	global_load_dwordx4 v[80:83], v[72:73], off
	global_load_dwordx2 v[100:101], v[122:123], off
	v_add_u32_e32 v158, v125, v119
	v_lshl_add_u64 v[72:73], v[158:159], 2, s[90:91]
	global_load_dwordx4 v[76:79], v[72:73], off
	v_add_u32_e32 v158, v125, v118
	v_lshl_add_u64 v[72:73], v[158:159], 2, s[90:91]
	global_load_dwordx4 v[72:75], v[72:73], off
	v_sub_f32_e32 v121, v127, v138
	v_sub_f32_e32 v120, v126, v138
	v_sub_f32_e32 v123, v129, v138
	v_sub_f32_e32 v122, v128, v138
	v_pk_mul_f32 v[122:123], v[138:139], v[122:123] op_sel:[1,0]
	v_pk_mul_f32 v[120:121], v[138:139], v[120:121] op_sel:[1,0]
	v_or_b32_e32 v158, 0x80, v148
	v_pk_fma_f32 v[60:61], v[98:99], v[120:121], v[60:61]
	v_pk_fma_f32 v[62:63], v[96:97], v[122:123], v[62:63]
	v_pk_fma_f32 v[60:61], v[68:69], s[78:79], v[60:61] op_sel_hi:[1,0,1]
	v_pk_fma_f32 v[62:63], v[70:71], s[78:79], v[62:63] op_sel_hi:[1,0,1]
	v_lshl_add_u64 v[120:121], v[158:159], 2, s[88:89]
	global_store_dwordx4 v[120:121], v[60:63], off
	v_or_b32_e32 v158, 0x90, v148
	s_waitcnt vmcnt(0)
	v_sub_f32_e32 v61, v131, v138
	v_sub_f32_e32 v60, v130, v138
	v_sub_f32_e32 v63, v133, v138
	v_sub_f32_e32 v62, v132, v138
	v_pk_mul_f32 v[62:63], v[138:139], v[62:63] op_sel:[1,0]
	v_pk_mul_f32 v[60:61], v[138:139], v[60:61] op_sel:[1,0]
	v_pk_fma_f32 v[58:59], v[92:93], v[62:63], v[58:59]
	v_pk_fma_f32 v[56:57], v[94:95], v[60:61], v[56:57]
	v_pk_fma_f32 v[58:59], v[66:67], s[78:79], v[58:59] op_sel_hi:[1,0,1]
	v_pk_fma_f32 v[56:57], v[64:65], s[78:79], v[56:57] op_sel_hi:[1,0,1]
	v_lshl_add_u64 v[60:61], v[158:159], 2, s[88:89]
	global_store_dwordx4 v[60:61], v[56:59], off
	v_add_u32_e32 v158, 0x8080, v148
	s_nop 0
	v_sub_f32_e32 v57, v135, v112
	v_sub_f32_e32 v56, v134, v112
	v_sub_f32_e32 v59, v137, v112
	v_sub_f32_e32 v58, v136, v112
	v_pk_mul_f32 v[58:59], v[112:113], v[58:59] op_sel:[1,0]
	v_pk_mul_f32 v[56:57], v[112:113], v[56:57] op_sel:[1,0]
	v_pk_fma_f32 v[54:55], v[96:97], v[58:59], v[54:55]
	v_pk_fma_f32 v[52:53], v[98:99], v[56:57], v[52:53]
	v_pk_fma_f32 v[54:55], v[70:71], s[78:79], v[54:55] op_sel_hi:[1,0,1]
	v_pk_fma_f32 v[52:53], v[68:69], s[78:79], v[52:53] op_sel_hi:[1,0,1]
	v_lshl_add_u64 v[56:57], v[158:159], 2, s[88:89]
	global_store_dwordx4 v[56:57], v[52:55], off
	v_add_u32_e32 v158, 0x8090, v148
	s_nop 0
	v_sub_f32_e32 v53, v89, v112
	v_sub_f32_e32 v52, v88, v112
	v_sub_f32_e32 v55, v91, v112
	v_sub_f32_e32 v54, v90, v112
	v_pk_mul_f32 v[54:55], v[112:113], v[54:55] op_sel:[1,0]
	v_pk_mul_f32 v[52:53], v[112:113], v[52:53] op_sel:[1,0]
	v_pk_fma_f32 v[50:51], v[92:93], v[54:55], v[50:51]
	v_pk_fma_f32 v[48:49], v[94:95], v[52:53], v[48:49]
	v_pk_fma_f32 v[50:51], v[66:67], s[78:79], v[50:51] op_sel_hi:[1,0,1]
	v_pk_fma_f32 v[48:49], v[64:65], s[78:79], v[48:49] op_sel_hi:[1,0,1]
	v_lshl_add_u64 v[52:53], v[158:159], 2, s[88:89]
	global_store_dwordx4 v[52:53], v[48:51], off
	v_add_u32_e32 v158, 0x10080, v148
	s_nop 0
	v_sub_f32_e32 v49, v85, v102
	v_sub_f32_e32 v48, v84, v102
	v_sub_f32_e32 v51, v87, v102
	v_sub_f32_e32 v50, v86, v102
	v_pk_mul_f32 v[50:51], v[102:103], v[50:51] op_sel:[1,0]
	v_pk_mul_f32 v[48:49], v[102:103], v[48:49] op_sel:[1,0]
	v_pk_fma_f32 v[46:47], v[96:97], v[50:51], v[46:47]
	v_pk_fma_f32 v[44:45], v[98:99], v[48:49], v[44:45]
	v_pk_fma_f32 v[46:47], v[70:71], s[78:79], v[46:47] op_sel_hi:[1,0,1]
	v_pk_fma_f32 v[44:45], v[68:69], s[78:79], v[44:45] op_sel_hi:[1,0,1]
	v_lshl_add_u64 v[48:49], v[158:159], 2, s[88:89]
	global_store_dwordx4 v[48:49], v[44:47], off
	v_add_u32_e32 v158, 0x10090, v148
	s_nop 0
	v_sub_f32_e32 v45, v81, v102
	v_sub_f32_e32 v44, v80, v102
	v_sub_f32_e32 v47, v83, v102
	v_sub_f32_e32 v46, v82, v102
	v_pk_mul_f32 v[46:47], v[102:103], v[46:47] op_sel:[1,0]
	v_pk_mul_f32 v[44:45], v[102:103], v[44:45] op_sel:[1,0]
	v_pk_fma_f32 v[42:43], v[92:93], v[46:47], v[42:43]
	v_pk_fma_f32 v[40:41], v[94:95], v[44:45], v[40:41]
	v_pk_fma_f32 v[42:43], v[66:67], s[78:79], v[42:43] op_sel_hi:[1,0,1]
	v_pk_fma_f32 v[40:41], v[64:65], s[78:79], v[40:41] op_sel_hi:[1,0,1]
	v_lshl_add_u64 v[44:45], v[158:159], 2, s[88:89]
	global_store_dwordx4 v[44:45], v[40:43], off
	v_add_u32_e32 v158, 0x18080, v148
	s_nop 0
	v_sub_f32_e32 v41, v77, v100
	v_sub_f32_e32 v40, v76, v100
	v_sub_f32_e32 v43, v79, v100
	v_sub_f32_e32 v42, v78, v100
	v_pk_mul_f32 v[42:43], v[100:101], v[42:43] op_sel:[1,0]
	v_pk_mul_f32 v[40:41], v[100:101], v[40:41] op_sel:[1,0]
	v_pk_fma_f32 v[38:39], v[96:97], v[42:43], v[38:39]
;     template <bool LN, int BJ, int LO, int HI> DI void batch(const f32x4 (&acc)[2][2][4][2], unsigned row0, unsigned col0, const f32x4 (&gv)[2], const f32x4 (&bv)[2]) const {
;         f32x4 r[HI - LO]; float mean[(HI - LO) / 2], rstd[(HI - LO) / 2];
; #pragma unroll
;         for (int i = LO; i < HI; ++i) { const int ai = i >> 3, m = (i >> 1) & 3, n = i & 1; const unsigned row = row0 + ai * HALF + m * 16;
;             if (n == 0) { mean[(i - LO) >> 1] = 0.f; rstd[(i - LO) >> 1] = 1.f;
;                 if (LN) { const float2 st = *(const float2*)(stats + row * 2u); mean[(i - LO) >> 1] = st.x; rstd[(i - LO) >> 1] = st.y; } }
;             r[i - LO] = *(const f32x4*)(src + (row * (unsigned)DM + col0 + BJ * HALF + n * 16)); }
; #pragma unroll
;         for (int i = LO; i < HI; ++i) { const int ai = i >> 3, m = (i >> 1) & 3, n = i & 1; const unsigned row = row0 + ai * HALF + m * 16;
;             *(f32x4*)(Y + (row * (unsigned)DM + col0 + BJ * HALF + n * 16)) = acc[ai][BJ][m][n] + ((r[i - LO] - mean[(i - LO) >> 1]) * rstd[(i - LO) >> 1]) * gv[n] + bv[n]; }
	v_pk_fma_f32 v[36:37], v[98:99], v[40:41], v[36:37]
	v_pk_fma_f32 v[38:39], v[70:71], s[78:79], v[38:39] op_sel_hi:[1,0,1]
	v_pk_fma_f32 v[36:37], v[68:69], s[78:79], v[36:37] op_sel_hi:[1,0,1]
	v_lshl_add_u64 v[40:41], v[158:159], 2, s[88:89]
	global_store_dwordx4 v[40:41], v[36:39], off
	v_add_u32_e32 v158, 0x18090, v148
	s_nop 0
	v_sub_f32_e32 v37, v73, v100
	v_sub_f32_e32 v36, v72, v100
	v_sub_f32_e32 v39, v75, v100
	v_sub_f32_e32 v38, v74, v100
	v_pk_mul_f32 v[38:39], v[100:101], v[38:39] op_sel:[1,0]
	v_pk_mul_f32 v[36:37], v[100:101], v[36:37] op_sel:[1,0]
	v_pk_fma_f32 v[34:35], v[92:93], v[38:39], v[34:35]
	v_pk_fma_f32 v[32:33], v[94:95], v[36:37], v[32:33]
	v_pk_fma_f32 v[34:35], v[66:67], s[78:79], v[34:35] op_sel_hi:[1,0,1]
	v_pk_fma_f32 v[32:33], v[64:65], s[78:79], v[32:33] op_sel_hi:[1,0,1]
	v_lshl_add_u64 v[36:37], v[158:159], 2, s[88:89]
	global_store_dwordx4 v[36:37], v[32:35], off
	v_add_u32_e32 v158, v114, v119
	s_nop 0
	v_lshl_add_u64 v[32:33], v[158:159], 2, s[90:91]
	global_load_dwordx2 v[62:63], v[104:105], off
	global_load_dwordx4 v[54:57], v[32:33], off
	v_add_u32_e32 v158, v114, v118
	v_lshl_add_u64 v[32:33], v[158:159], 2, s[90:91]
	global_load_dwordx4 v[58:61], v[32:33], off
	global_load_dwordx2 v[52:53], v[106:107], off
	v_add_u32_e32 v158, v115, v119
	v_lshl_add_u64 v[32:33], v[158:159], 2, s[90:91]
	global_load_dwordx4 v[72:75], v[32:33], off
	v_add_u32_e32 v158, v115, v118
	v_lshl_add_u64 v[32:33], v[158:159], 2, s[90:91]
	global_load_dwordx4 v[76:79], v[32:33], off
	global_load_dwordx2 v[50:51], v[108:109], off
	v_add_u32_e32 v158, v116, v119
	v_lshl_add_u64 v[32:33], v[158:159], 2, s[90:91]
	global_load_dwordx4 v[44:47], v[32:33], off
	v_add_u32_e32 v158, v116, v118
	v_lshl_add_u64 v[32:33], v[158:159], 2, s[90:91]
	global_load_dwordx4 v[40:43], v[32:33], off
	global_load_dwordx2 v[48:49], v[110:111], off
	v_add_u32_e32 v158, v117, v119
	v_lshl_add_u64 v[32:33], v[158:159], 2, s[90:91]
	global_load_dwordx4 v[36:39], v[32:33], off
	v_add_u32_e32 v158, v117, v118
	v_lshl_add_u64 v[32:33], v[158:159], 2, s[90:91]
	global_load_dwordx4 v[32:35], v[32:33], off
	v_add_u32_e32 v158, 0x40080, v148
	s_waitcnt vmcnt(0)
; #define PG8_WAIT_V(n) asm volatile("s_waitcnt vmcnt(" #n ")" ::: "memory")
; #define PG8_BAR __builtin_amdgcn_s_barrier()
; template <class Epi>
; DI void gemm_phase(LAS unsigned char* lds, const Gemm g, const StaticOrder& S, const Epi& E) {
;     ...
;         E(acc, cur, wr, wc, fr, fq);
;         if (!has_next) break;
; #pragma unroll
;         for (int a = 0; a < 2; ++a)
; #pragma unroll
;             for (int b = 0; b < 2; ++b)
; #pragma unroll
;                 for (int m = 0; m < 4; ++m)
; #pragma unroll
;                     for (int n = 0; n < 2; ++n) acc[a][b][m][n] = (f32x4){0.f, 0.f, 0.f, 0.f};
;         cur = nxt; cA = nA; cB = nB; ++ui;
;     }
;     PG8_WAIT_V(0);
;     if (wr == 0) PG8_BAR;
;     PG8_BAR;
;     template <bool LN, int BJ, int LO, int HI> DI void batch(const f32x4 (&acc)[2][2][4][2], unsigned row0, unsigned col0, const f32x4 (&gv)[2], const f32x4 (&bv)[2]) const {
;     ...
;         for (int i = LO; i < HI; ++i) { const int ai = i >> 3, m = (i >> 1) & 3, n = i & 1; const unsigned row = row0 + ai * HALF + m * 16;
;             if (n == 0) { mean[(i - LO) >> 1] = 0.f; rstd[(i - LO) >> 1] = 1.f;
;                 if (LN) { const float2 st = *(const float2*)(stats + row * 2u); mean[(i - LO) >> 1] = st.x; rstd[(i - LO) >> 1] = st.y; } }
;             r[i - LO] = *(const f32x4*)(src + (row * (unsigned)DM + col0 + BJ * HALF + n * 16)); }
; #pragma unroll
;         for (int i = LO; i < HI; ++i) { const int ai = i >> 3, m = (i >> 1) & 3, n = i & 1; const unsigned row = row0 + ai * HALF + m * 16;
;             *(f32x4*)(Y + (row * (unsigned)DM + col0 + BJ * HALF + n * 16)) = acc[ai][BJ][m][n] + ((r[i - LO] - mean[(i - LO) >> 1]) * rstd[(i - LO) >> 1]) * gv[n] + bv[n]; }
;         __builtin_amdgcn_sched_barrier(0);
;     }
	v_sub_f32_e32 v55, v55, v62
	v_sub_f32_e32 v54, v54, v62
	v_sub_f32_e32 v57, v57, v62
	v_sub_f32_e32 v56, v56, v62
	v_pk_mul_f32 v[56:57], v[62:63], v[56:57] op_sel:[1,0]
	v_pk_mul_f32 v[54:55], v[62:63], v[54:55] op_sel:[1,0]
	v_pk_fma_f32 v[30:31], v[96:97], v[56:57], v[30:31]
	v_pk_fma_f32 v[28:29], v[98:99], v[54:55], v[28:29]
	v_pk_fma_f32 v[30:31], v[70:71], s[78:79], v[30:31] op_sel_hi:[1,0,1]
	v_pk_fma_f32 v[28:29], v[68:69], s[78:79], v[28:29] op_sel_hi:[1,0,1]
	v_lshl_add_u64 v[54:55], v[158:159], 2, s[88:89]
	global_store_dwordx4 v[54:55], v[28:31], off
	v_add_u32_e32 v158, 0x40090, v148
	s_nop 0
	v_sub_f32_e32 v29, v59, v62
	v_sub_f32_e32 v28, v58, v62
	v_sub_f32_e32 v31, v61, v62
	v_sub_f32_e32 v30, v60, v62
	v_pk_mul_f32 v[30:31], v[62:63], v[30:31] op_sel:[1,0]
	v_pk_mul_f32 v[28:29], v[62:63], v[28:29] op_sel:[1,0]
	v_pk_fma_f32 v[26:27], v[92:93], v[30:31], v[26:27]
	v_pk_fma_f32 v[24:25], v[94:95], v[28:29], v[24:25]
	v_pk_fma_f32 v[26:27], v[66:67], s[78:79], v[26:27] op_sel_hi:[1,0,1]
	v_pk_fma_f32 v[24:25], v[64:65], s[78:79], v[24:25] op_sel_hi:[1,0,1]
	v_lshl_add_u64 v[28:29], v[158:159], 2, s[88:89]
	global_store_dwordx4 v[28:29], v[24:27], off
	v_add_u32_e32 v158, 0x48080, v148
	s_nop 0
	v_sub_f32_e32 v25, v73, v52
	v_sub_f32_e32 v24, v72, v52
	v_sub_f32_e32 v27, v75, v52
	v_sub_f32_e32 v26, v74, v52
	v_pk_mul_f32 v[26:27], v[52:53], v[26:27] op_sel:[1,0]
	v_pk_mul_f32 v[24:25], v[52:53], v[24:25] op_sel:[1,0]
	v_pk_fma_f32 v[22:23], v[96:97], v[26:27], v[22:23]
	v_pk_fma_f32 v[20:21], v[98:99], v[24:25], v[20:21]
	v_pk_fma_f32 v[22:23], v[70:71], s[78:79], v[22:23] op_sel_hi:[1,0,1]
	v_pk_fma_f32 v[20:21], v[68:69], s[78:79], v[20:21] op_sel_hi:[1,0,1]
	v_lshl_add_u64 v[24:25], v[158:159], 2, s[88:89]
	global_store_dwordx4 v[24:25], v[20:23], off
	v_add_u32_e32 v158, 0x48090, v148
	s_nop 0
	v_sub_f32_e32 v21, v77, v52
	v_sub_f32_e32 v20, v76, v52
	v_sub_f32_e32 v23, v79, v52
	v_sub_f32_e32 v22, v78, v52
	v_pk_mul_f32 v[22:23], v[52:53], v[22:23] op_sel:[1,0]
	v_pk_mul_f32 v[20:21], v[52:53], v[20:21] op_sel:[1,0]
	v_pk_fma_f32 v[18:19], v[92:93], v[22:23], v[18:19]
	v_pk_fma_f32 v[16:17], v[94:95], v[20:21], v[16:17]
	v_pk_fma_f32 v[18:19], v[66:67], s[78:79], v[18:19] op_sel_hi:[1,0,1]
	v_pk_fma_f32 v[16:17], v[64:65], s[78:79], v[16:17] op_sel_hi:[1,0,1]
	v_lshl_add_u64 v[20:21], v[158:159], 2, s[88:89]
	global_store_dwordx4 v[20:21], v[16:19], off
	v_add_u32_e32 v158, 0x50080, v148
	s_nop 0
	v_sub_f32_e32 v17, v45, v50
	v_sub_f32_e32 v16, v44, v50
	v_sub_f32_e32 v19, v47, v50
	v_sub_f32_e32 v18, v46, v50
	v_pk_mul_f32 v[18:19], v[50:51], v[18:19] op_sel:[1,0]
	v_pk_mul_f32 v[16:17], v[50:51], v[16:17] op_sel:[1,0]
	v_pk_fma_f32 v[14:15], v[96:97], v[18:19], v[14:15]
	v_pk_fma_f32 v[12:13], v[98:99], v[16:17], v[12:13]
	v_pk_fma_f32 v[14:15], v[70:71], s[78:79], v[14:15] op_sel_hi:[1,0,1]
	v_pk_fma_f32 v[12:13], v[68:69], s[78:79], v[12:13] op_sel_hi:[1,0,1]
	v_lshl_add_u64 v[16:17], v[158:159], 2, s[88:89]
	global_store_dwordx4 v[16:17], v[12:15], off
	v_add_u32_e32 v158, 0x50090, v148
	s_nop 0
	v_sub_f32_e32 v13, v41, v50
	v_sub_f32_e32 v12, v40, v50
	v_sub_f32_e32 v15, v43, v50
	v_sub_f32_e32 v14, v42, v50
	v_pk_mul_f32 v[14:15], v[50:51], v[14:15] op_sel:[1,0]
	v_pk_mul_f32 v[12:13], v[50:51], v[12:13] op_sel:[1,0]
	v_pk_fma_f32 v[10:11], v[92:93], v[14:15], v[10:11]
	v_pk_fma_f32 v[8:9], v[94:95], v[12:13], v[8:9]
	v_pk_fma_f32 v[10:11], v[66:67], s[78:79], v[10:11] op_sel_hi:[1,0,1]
	v_pk_fma_f32 v[8:9], v[64:65], s[78:79], v[8:9] op_sel_hi:[1,0,1]
	v_lshl_add_u64 v[12:13], v[158:159], 2, s[88:89]
	global_store_dwordx4 v[12:13], v[8:11], off
	v_add_u32_e32 v158, 0x58080, v148
	s_nop 0
	v_sub_f32_e32 v9, v37, v48
	v_sub_f32_e32 v8, v36, v48
	v_sub_f32_e32 v11, v39, v48
	v_sub_f32_e32 v10, v38, v48
	v_pk_mul_f32 v[10:11], v[48:49], v[10:11] op_sel:[1,0]
	v_pk_mul_f32 v[8:9], v[48:49], v[8:9] op_sel:[1,0]
	v_pk_fma_f32 v[6:7], v[96:97], v[10:11], v[6:7]
	v_pk_fma_f32 v[4:5], v[98:99], v[8:9], v[4:5]
	v_pk_fma_f32 v[6:7], v[70:71], s[78:79], v[6:7] op_sel_hi:[1,0,1]
	v_pk_fma_f32 v[4:5], v[68:69], s[78:79], v[4:5] op_sel_hi:[1,0,1]
	v_lshl_add_u64 v[8:9], v[158:159], 2, s[88:89]
	global_store_dwordx4 v[8:9], v[4:7], off
	v_add_u32_e32 v158, 0x58090, v148
	s_nop 0
	v_sub_f32_e32 v5, v33, v48
	v_sub_f32_e32 v4, v32, v48
	v_sub_f32_e32 v7, v35, v48
	v_sub_f32_e32 v6, v34, v48
	v_pk_mul_f32 v[6:7], v[48:49], v[6:7] op_sel:[1,0]
	v_pk_mul_f32 v[4:5], v[48:49], v[4:5] op_sel:[1,0]
	v_pk_fma_f32 v[2:3], v[92:93], v[6:7], v[2:3]
	v_pk_fma_f32 v[0:1], v[94:95], v[4:5], v[0:1]
	v_pk_fma_f32 v[2:3], v[66:67], s[78:79], v[2:3] op_sel_hi:[1,0,1]
	v_pk_fma_f32 v[0:1], v[64:65], s[78:79], v[0:1] op_sel_hi:[1,0,1]
	v_lshl_add_u64 v[4:5], v[158:159], 2, s[88:89]
	global_store_dwordx4 v[4:5], v[0:3], off
	s_and_b64 vcc, exec, s[6:7]
	s_mov_b32 s2, s37
	s_mov_b32 s3, s38
	s_mov_b64 s[18:19], s[10:11]
	s_mov_b64 s[16:17], s[8:9]
	v_readlane_b32 s33, v255, 39
	s_cbranch_vccz .LBB0_123
	s_waitcnt vmcnt(0)
	s_cmpk_gt_u32 s24, 0xff
	s_cbranch_scc1 .LBB0_138
	s_barrier

; #define PG8_STAGE(bufoff, gbase) do { _Pragma("unroll") for (int _i = 0; _i < 2; ++_i) \
;         __builtin_amdgcn_global_load_lds((const unsigned*)((const char*)(gbase) + voff[_i]), (LAS unsigned*)(lds + (bufoff) + ldsw + _i * 8192), 16, 0, 0); } while (0)
; #define PG8_LDA(dst, b, h) do { _Pragma("unroll") for (int m = 0; m < 4; ++m) _Pragma("unroll") for (int k = 0; k < 2; ++k) dst[m][k] = *(const LAS bf16x8*)(lds + PG8_SA(b, h) + aoff + m * 2048 + k * 1024); } while (0)
; #define PG8_LDB(dst, b, h) do { _Pragma("unroll") for (int n = 0; n < 2; ++n) _Pragma("unroll") for (int k = 0; k < 2; ++k) dst[n][k] = *(const LAS bf16x8*)(lds + PG8_SB(b, h) + boff + n * 2048 + k * 1024); } while (0)
; template <class Epi>
; DI void gemm_phase(LAS unsigned char* lds, const Gemm g, const StaticOrder& S, const Epi& E) {
;     ...
;         for (int t = 0; t < nt; t += 2) {
;             const bool last = (t == nt - 2);
;             const char* a1 = cA + (size_t)(t + 1) * kstep;
;             const char* a2 = last ? nA : cA + (size_t)(t + 2) * kstep; const char* b2 = last ? nB : cB + (size_t)(t + 2) * kstep;
;             const char* a3 = a2 + kstep; const char* b3 = b2 + kstep;
;             PG8_LDB(B0, 0, 0); PG8_SCHED; PG8_LDA(At, 0, 0); PG8_STAGE(PG8_SA(1, 1), a1 + hstep);
;             PG8_WAIT_L(8); PG8_BAR; PG8_WAIT_L(0); PG8_MMA(0, 0, At, B0); PG8_BAR; PG8_SCHED;
;             PG8_LDB(B1, 0, 1); PG8_STAGE(PG8_SB(0, 0), b2);
;             PG8_BAR; PG8_WAIT_L(0); PG8_MMA(0, 1, At, B1); PG8_BAR;
;             PG8_LDA(At, 0, 1); PG8_STAGE(PG8_SA(0, 0), a2);
;             PG8_BAR; PG8_WAIT_L(0); PG8_MMA(1, 0, At, B0); PG8_BAR; PG8_SCHED;
;             PG8_STAGE(PG8_SB(0, 1), b2 + hstep);
;             PG8_WAIT_V(6); PG8_BAR; PG8_MMA(1, 1, At, B1); PG8_BAR;
;             PG8_LDB(B0, 1, 0); PG8_SCHED; PG8_LDA(At, 1, 0); PG8_STAGE(PG8_SA(0, 1), a2 + hstep);
;             PG8_WAIT_L(8); PG8_BAR; PG8_WAIT_L(0); PG8_MMA(0, 0, At, B0); PG8_BAR; PG8_SCHED;
;             PG8_LDB(B1, 1, 1); PG8_STAGE(PG8_SB(1, 0), b3);
;             PG8_BAR; PG8_WAIT_L(0); PG8_MMA(0, 1, At, B1); PG8_BAR;
;             PG8_LDA(At, 1, 1); PG8_STAGE(PG8_SA(1, 0), a3);
;             PG8_BAR; PG8_WAIT_L(0); PG8_MMA(1, 0, At, B0); PG8_BAR; PG8_SCHED;
;             PG8_STAGE(PG8_SB(1, 1), b3 + hstep);
;             PG8_WAIT_V(6); PG8_BAR; PG8_MMA(1, 1, At, B1); PG8_BAR;
.LBB0_202:
	s_add_u32 s18, s8, 0xfff80080
	s_addc_u32 s19, s9, -1
	s_add_i32 s37, 0, 0x10000
	s_waitcnt lgkmcnt(0)
	ds_read_b128 v[128:131], v187
	ds_read_b128 v[132:135], v187 offset:1024
	ds_read_b128 v[136:139], v187 offset:2048
	ds_read_b128 v[190:193], v187 offset:3072
	s_cmp_eq_u32 s36, 28
	s_cselect_b32 s21, s4, s19
	s_cselect_b32 s20, s5, s18
	s_cselect_b32 s19, s11, s35
	s_cselect_b32 s18, s13, s33
	s_add_i32 m0, s26, 0xc000
	ds_read_b128 v[194:197], v189
	ds_read_b128 v[198:201], v189 offset:1024
	ds_read_b128 v[202:205], v189 offset:2048
	ds_read_b128 v[206:209], v189 offset:3072
	ds_read_b128 v[210:213], v189 offset:4096
	ds_read_b128 v[214:217], v189 offset:5120
	ds_read_b128 v[226:229], v189 offset:6144
	ds_read_b128 v[230:233], v189 offset:7168
	global_load_lds_dwordx4 v150, s[8:9]
	s_add_i32 m0, s26, 0xe000
	s_nop 0
	global_load_lds_dwordx4 v152, s[8:9]
	s_waitcnt lgkmcnt(8)
	s_setprio 1
	s_barrier
	s_waitcnt lgkmcnt(0)
	v_mfma_f32_16x16x32_bf16 v[124:127], v[128:131], v[194:197], v[124:127]
	v_mfma_f32_16x16x32_bf16 v[120:123], v[136:139], v[194:197], v[120:123]
	v_mfma_f32_16x16x32_bf16 v[108:111], v[128:131], v[202:205], v[108:111]
	v_mfma_f32_16x16x32_bf16 v[104:107], v[136:139], v[202:205], v[104:107]
	v_mfma_f32_16x16x32_bf16 v[92:95], v[128:131], v[210:213], v[92:95]
	v_mfma_f32_16x16x32_bf16 v[88:91], v[136:139], v[210:213], v[88:91]
	v_mfma_f32_16x16x32_bf16 v[76:79], v[128:131], v[226:229], v[76:79]
	v_mfma_f32_16x16x32_bf16 v[72:75], v[136:139], v[226:229], v[72:75]
	v_mfma_f32_16x16x32_bf16 v[124:127], v[132:135], v[198:201], v[124:127]
	v_mfma_f32_16x16x32_bf16 v[120:123], v[190:193], v[198:201], v[120:123]
	v_mfma_f32_16x16x32_bf16 v[108:111], v[132:135], v[206:209], v[108:111]
	v_mfma_f32_16x16x32_bf16 v[104:107], v[190:193], v[206:209], v[104:107]
	v_mfma_f32_16x16x32_bf16 v[92:95], v[132:135], v[214:217], v[92:95]
	v_mfma_f32_16x16x32_bf16 v[88:91], v[190:193], v[214:217], v[88:91]
	v_mfma_f32_16x16x32_bf16 v[76:79], v[132:135], v[230:233], v[76:79]
	s_setprio 0
	v_mfma_f32_16x16x32_bf16 v[72:75], v[190:193], v[230:233], v[72:75]
	s_barrier
	s_add_i32 s40, 0, 0x14000
	s_add_i32 s37, s37, s25
	ds_read_b128 v[234:237], v187 offset:16384
	ds_read_b128 v[238:241], v187 offset:17408
	ds_read_b128 v[242:245], v187 offset:18432
	ds_read_b128 v[246:249], v187 offset:19456
	s_mov_b32 m0, s37
	s_nop 0
	global_load_lds_dwordx4 v144, s[18:19]
	s_add_i32 m0, s37, 0x2000
	s_nop 0
	global_load_lds_dwordx4 v142, s[18:19]
	s_waitcnt lgkmcnt(0)
	s_setprio 1
	s_barrier
	v_mfma_f32_16x16x32_bf16 v[116:119], v[234:237], v[194:197], v[116:119]
	v_mfma_f32_16x16x32_bf16 v[112:115], v[242:245], v[194:197], v[112:115]
	v_mfma_f32_16x16x32_bf16 v[100:103], v[234:237], v[202:205], v[100:103]
	v_mfma_f32_16x16x32_bf16 v[96:99], v[242:245], v[202:205], v[96:99]
	v_mfma_f32_16x16x32_bf16 v[84:87], v[234:237], v[210:213], v[84:87]
	v_mfma_f32_16x16x32_bf16 v[80:83], v[242:245], v[210:213], v[80:83]
	v_mfma_f32_16x16x32_bf16 v[68:71], v[234:237], v[226:229], v[68:71]
	v_mfma_f32_16x16x32_bf16 v[64:67], v[242:245], v[226:229], v[64:67]
	v_mfma_f32_16x16x32_bf16 v[116:119], v[238:241], v[198:201], v[116:119]
	s_mov_b32 m0, s26
	v_mfma_f32_16x16x32_bf16 v[112:115], v[246:249], v[198:201], v[112:115]
	v_lshl_add_u64 v[218:219], s[20:21], 0, v[144:145]
	v_mfma_f32_16x16x32_bf16 v[100:103], v[238:241], v[206:209], v[100:103]
	v_mfma_f32_16x16x32_bf16 v[96:99], v[246:249], v[206:209], v[96:99]
	v_mfma_f32_16x16x32_bf16 v[84:87], v[238:241], v[214:217], v[84:87]
	v_mfma_f32_16x16x32_bf16 v[80:83], v[246:249], v[214:217], v[80:83]
	v_mfma_f32_16x16x32_bf16 v[68:71], v[238:241], v[230:233], v[68:71]
	s_setprio 0
	v_mfma_f32_16x16x32_bf16 v[64:67], v[246:249], v[230:233], v[64:67]
	s_barrier
	ds_read_b128 v[194:197], v189 offset:16384
	ds_read_b128 v[198:201], v189 offset:17408
	ds_read_b128 v[202:205], v189 offset:18432
	ds_read_b128 v[206:209], v189 offset:19456
	ds_read_b128 v[210:213], v189 offset:20480
	ds_read_b128 v[214:217], v189 offset:21504
	ds_read_b128 v[226:229], v189 offset:22528
	ds_read_b128 v[230:233], v189 offset:23552
	global_load_lds_dwordx4 v[218:219], off
	s_mov_b64 s[100:101], s[20:21]
	s_mov_b32 m0, s27
	s_nop 0
	global_load_lds_dwordx4 v142, s[20:21]
	s_waitcnt lgkmcnt(0)
	s_setprio 1
	s_barrier
	v_mfma_f32_16x16x32_bf16 v[60:63], v[128:131], v[194:197], v[60:63]
	v_mfma_f32_16x16x32_bf16 v[56:59], v[136:139], v[194:197], v[56:59]
	v_mfma_f32_16x16x32_bf16 v[44:47], v[128:131], v[202:205], v[44:47]
	v_mfma_f32_16x16x32_bf16 v[40:43], v[136:139], v[202:205], v[40:43]
	v_mfma_f32_16x16x32_bf16 v[28:31], v[128:131], v[210:213], v[28:31]
	v_mfma_f32_16x16x32_bf16 v[24:27], v[136:139], v[210:213], v[24:27]
	v_mfma_f32_16x16x32_bf16 v[12:15], v[128:131], v[226:229], v[12:15]
	v_mfma_f32_16x16x32_bf16 v[8:11], v[136:139], v[226:229], v[8:11]
	v_mfma_f32_16x16x32_bf16 v[60:63], v[132:135], v[198:201], v[60:63]
	v_mfma_f32_16x16x32_bf16 v[56:59], v[190:193], v[198:201], v[56:59]
	v_mfma_f32_16x16x32_bf16 v[44:47], v[132:135], v[206:209], v[44:47]
	v_mfma_f32_16x16x32_bf16 v[40:43], v[190:193], v[206:209], v[40:43]
	v_mfma_f32_16x16x32_bf16 v[28:31], v[132:135], v[214:217], v[28:31]
	v_mfma_f32_16x16x32_bf16 v[24:27], v[190:193], v[214:217], v[24:27]
	v_mfma_f32_16x16x32_bf16 v[12:15], v[132:135], v[230:233], v[12:15]
	s_setprio 0
	v_mfma_f32_16x16x32_bf16 v[8:11], v[190:193], v[230:233], v[8:11]
	s_barrier
	s_add_u32 s38, s18, 0x80000
	s_addc_u32 s39, s19, 0
	s_add_i32 s37, s40, s25
	s_mov_b32 m0, s37
	s_nop 0
	global_load_lds_dwordx4 v144, s[38:39]
	s_add_i32 m0, s37, 0x2000
	s_nop 0
	global_load_lds_dwordx4 v142, s[38:39]
	s_waitcnt vmcnt(6)
	s_setprio 1
	s_barrier
; #define PG8_STAGE(bufoff, gbase) do { _Pragma("unroll") for (int _i = 0; _i < 2; ++_i) \
;         __builtin_amdgcn_global_load_lds((const unsigned*)((const char*)(gbase) + voff[_i]), (LAS unsigned*)(lds + (bufoff) + ldsw + _i * 8192), 16, 0, 0); } while (0)
; #define PG8_LDA(dst, b, h) do { _Pragma("unroll") for (int m = 0; m < 4; ++m) _Pragma("unroll") for (int k = 0; k < 2; ++k) dst[m][k] = *(const LAS bf16x8*)(lds + PG8_SA(b, h) + aoff + m * 2048 + k * 1024); } while (0)
; #define PG8_LDB(dst, b, h) do { _Pragma("unroll") for (int n = 0; n < 2; ++n) _Pragma("unroll") for (int k = 0; k < 2; ++k) dst[n][k] = *(const LAS bf16x8*)(lds + PG8_SB(b, h) + boff + n * 2048 + k * 1024); } while (0)
; template <class Epi>
; DI void gemm_phase(LAS unsigned char* lds, const Gemm g, const StaticOrder& S, const Epi& E) {
;     ...
;         for (int t = 0; t < nt; t += 2) {
;             const bool last = (t == nt - 2);
;             const char* a1 = cA + (size_t)(t + 1) * kstep;
;             const char* a2 = last ? nA : cA + (size_t)(t + 2) * kstep; const char* b2 = last ? nB : cB + (size_t)(t + 2) * kstep;
;             const char* a3 = a2 + kstep; const char* b3 = b2 + kstep;
;             PG8_LDB(B0, 0, 0); PG8_SCHED; PG8_LDA(At, 0, 0); PG8_STAGE(PG8_SA(1, 1), a1 + hstep);
;             PG8_WAIT_L(8); PG8_BAR; PG8_WAIT_L(0); PG8_MMA(0, 0, At, B0); PG8_BAR; PG8_SCHED;
;             PG8_LDB(B1, 0, 1); PG8_STAGE(PG8_SB(0, 0), b2);
;             PG8_BAR; PG8_WAIT_L(0); PG8_MMA(0, 1, At, B1); PG8_BAR;
;             PG8_LDA(At, 0, 1); PG8_STAGE(PG8_SA(0, 0), a2);
;             PG8_BAR; PG8_WAIT_L(0); PG8_MMA(1, 0, At, B0); PG8_BAR; PG8_SCHED;
;             PG8_STAGE(PG8_SB(0, 1), b2 + hstep);
;             PG8_WAIT_V(6); PG8_BAR; PG8_MMA(1, 1, At, B1); PG8_BAR;
;             PG8_LDB(B0, 1, 0); PG8_SCHED; PG8_LDA(At, 1, 0); PG8_STAGE(PG8_SA(0, 1), a2 + hstep);
;             PG8_WAIT_L(8); PG8_BAR; PG8_WAIT_L(0); PG8_MMA(0, 0, At, B0); PG8_BAR; PG8_SCHED;
;             PG8_LDB(B1, 1, 1); PG8_STAGE(PG8_SB(1, 0), b3);
;             PG8_BAR; PG8_WAIT_L(0); PG8_MMA(0, 1, At, B1); PG8_BAR;
;             PG8_LDA(At, 1, 1); PG8_STAGE(PG8_SA(1, 0), a3);
;             PG8_BAR; PG8_WAIT_L(0); PG8_MMA(1, 0, At, B0); PG8_BAR; PG8_SCHED;
;             PG8_STAGE(PG8_SB(1, 1), b3 + hstep);
;             PG8_WAIT_V(6); PG8_BAR; PG8_MMA(1, 1, At, B1); PG8_BAR;
	v_mfma_f32_16x16x32_bf16 v[52:55], v[234:237], v[194:197], v[52:55]
	v_mfma_f32_16x16x32_bf16 v[48:51], v[242:245], v[194:197], v[48:51]
	v_mfma_f32_16x16x32_bf16 v[36:39], v[234:237], v[202:205], v[36:39]
	v_mfma_f32_16x16x32_bf16 v[32:35], v[242:245], v[202:205], v[32:35]
	v_mfma_f32_16x16x32_bf16 v[20:23], v[234:237], v[210:213], v[20:23]
	v_mfma_f32_16x16x32_bf16 v[16:19], v[242:245], v[210:213], v[16:19]
	v_mfma_f32_16x16x32_bf16 v[4:7], v[234:237], v[226:229], v[4:7]
	v_mfma_f32_16x16x32_bf16 v[0:3], v[242:245], v[226:229], v[0:3]
	v_mfma_f32_16x16x32_bf16 v[52:55], v[238:241], v[198:201], v[52:55]
	s_add_i32 s37, 0, 0x18000
	v_mfma_f32_16x16x32_bf16 v[48:51], v[246:249], v[198:201], v[48:51]
	v_mfma_f32_16x16x32_bf16 v[36:39], v[238:241], v[206:209], v[36:39]
	v_mfma_f32_16x16x32_bf16 v[32:35], v[246:249], v[206:209], v[32:35]
	v_mfma_f32_16x16x32_bf16 v[20:23], v[238:241], v[214:217], v[20:23]
	v_mfma_f32_16x16x32_bf16 v[16:19], v[246:249], v[214:217], v[16:19]
	v_mfma_f32_16x16x32_bf16 v[4:7], v[238:241], v[230:233], v[4:7]
	s_setprio 0
	v_mfma_f32_16x16x32_bf16 v[0:3], v[246:249], v[230:233], v[0:3]
	s_barrier
	ds_read_b128 v[128:131], v187 offset:32768
	ds_read_b128 v[132:135], v187 offset:33792
	ds_read_b128 v[136:139], v187 offset:34816
	ds_read_b128 v[190:193], v187 offset:35840
	s_add_u32 s20, s20, 0x80000
	s_addc_u32 s21, s21, 0
	s_mov_b32 m0, s28
	ds_read_b128 v[194:197], v189 offset:32768
	ds_read_b128 v[198:201], v189 offset:33792
	ds_read_b128 v[202:205], v189 offset:34816
	ds_read_b128 v[206:209], v189 offset:35840
	ds_read_b128 v[210:213], v189 offset:36864
	ds_read_b128 v[214:217], v189 offset:37888
	ds_read_b128 v[226:229], v189 offset:38912
	ds_read_b128 v[230:233], v189 offset:39936
	global_load_lds_dwordx4 v144, s[20:21]
	s_mov_b32 m0, s29
	s_nop 0
	global_load_lds_dwordx4 v142, s[20:21]
	s_waitcnt lgkmcnt(8)
	s_setprio 1
	s_barrier
	s_waitcnt lgkmcnt(0)
	v_mfma_f32_16x16x32_bf16 v[124:127], v[128:131], v[194:197], v[124:127]
	v_mfma_f32_16x16x32_bf16 v[120:123], v[136:139], v[194:197], v[120:123]
	v_mfma_f32_16x16x32_bf16 v[108:111], v[128:131], v[202:205], v[108:111]
	v_mfma_f32_16x16x32_bf16 v[104:107], v[136:139], v[202:205], v[104:107]
	v_mfma_f32_16x16x32_bf16 v[92:95], v[128:131], v[210:213], v[92:95]
	v_mfma_f32_16x16x32_bf16 v[88:91], v[136:139], v[210:213], v[88:91]
	v_mfma_f32_16x16x32_bf16 v[76:79], v[128:131], v[226:229], v[76:79]
	v_mfma_f32_16x16x32_bf16 v[72:75], v[136:139], v[226:229], v[72:75]
	v_mfma_f32_16x16x32_bf16 v[124:127], v[132:135], v[198:201], v[124:127]
	v_mfma_f32_16x16x32_bf16 v[120:123], v[190:193], v[198:201], v[120:123]
	v_mfma_f32_16x16x32_bf16 v[108:111], v[132:135], v[206:209], v[108:111]
	v_mfma_f32_16x16x32_bf16 v[104:107], v[190:193], v[206:209], v[104:107]
	v_mfma_f32_16x16x32_bf16 v[92:95], v[132:135], v[214:217], v[92:95]
	v_mfma_f32_16x16x32_bf16 v[88:91], v[190:193], v[214:217], v[88:91]
	v_mfma_f32_16x16x32_bf16 v[76:79], v[132:135], v[230:233], v[76:79]
	s_setprio 0
	v_mfma_f32_16x16x32_bf16 v[72:75], v[190:193], v[230:233], v[72:75]
	s_barrier
	s_add_i32 s20, 0, 0x1c000
	s_add_i32 s21, s37, s25
	s_add_i32 m0, s21, 0xffffff80
	ds_read_b128 v[234:237], v187 offset:49152
	ds_read_b128 v[238:241], v187 offset:50176
	ds_read_b128 v[242:245], v187 offset:51200
	ds_read_b128 v[246:249], v187 offset:52224
	global_load_lds_dwordx4 v144, s[18:19] offset:128
	s_add_i32 m0, s21, 0x1f80
	s_nop 0
	global_load_lds_dwordx4 v142, s[18:19] offset:128
	s_waitcnt lgkmcnt(0)
	s_setprio 1
	s_barrier
	v_mfma_f32_16x16x32_bf16 v[116:119], v[234:237], v[194:197], v[116:119]
	v_mfma_f32_16x16x32_bf16 v[112:115], v[242:245], v[194:197], v[112:115]
	v_mfma_f32_16x16x32_bf16 v[100:103], v[234:237], v[202:205], v[100:103]
	v_mfma_f32_16x16x32_bf16 v[96:99], v[242:245], v[202:205], v[96:99]
	v_mfma_f32_16x16x32_bf16 v[84:87], v[234:237], v[210:213], v[84:87]
	v_mfma_f32_16x16x32_bf16 v[80:83], v[242:245], v[210:213], v[80:83]
	v_mfma_f32_16x16x32_bf16 v[68:71], v[234:237], v[226:229], v[68:71]
	v_mfma_f32_16x16x32_bf16 v[64:67], v[242:245], v[226:229], v[64:67]
	v_mfma_f32_16x16x32_bf16 v[116:119], v[238:241], v[198:201], v[116:119]
	s_mov_b32 m0, s30
	v_mfma_f32_16x16x32_bf16 v[112:115], v[246:249], v[198:201], v[112:115]
	v_lshl_add_u64 v[140:141], v[218:219], 0, s[94:95]
	v_mfma_f32_16x16x32_bf16 v[100:103], v[238:241], v[206:209], v[100:103]
	v_mfma_f32_16x16x32_bf16 v[96:99], v[246:249], v[206:209], v[96:99]
	v_mfma_f32_16x16x32_bf16 v[84:87], v[238:241], v[214:217], v[84:87]
	v_mfma_f32_16x16x32_bf16 v[80:83], v[246:249], v[214:217], v[80:83]
	v_mfma_f32_16x16x32_bf16 v[68:71], v[238:241], v[230:233], v[68:71]
	s_setprio 0
	v_mfma_f32_16x16x32_bf16 v[64:67], v[246:249], v[230:233], v[64:67]
	s_barrier
; template <class Epi>
; DI void gemm_phase(LAS unsigned char* lds, const Gemm g, const StaticOrder& S, const Epi& E) {
;     ...
;         for (int t = 0; t < nt; t += 2) {
;             const bool last = (t == nt - 2);
;             const char* a1 = cA + (size_t)(t + 1) * kstep;
;             const char* a2 = last ? nA : cA + (size_t)(t + 2) * kstep; const char* b2 = last ? nB : cB + (size_t)(t + 2) * kstep;
;             const char* a3 = a2 + kstep; const char* b3 = b2 + kstep;
;             PG8_LDB(B0, 0, 0); PG8_SCHED; PG8_LDA(At, 0, 0); PG8_STAGE(PG8_SA(1, 1), a1 + hstep);
;             PG8_WAIT_L(8); PG8_BAR; PG8_WAIT_L(0); PG8_MMA(0, 0, At, B0); PG8_BAR; PG8_SCHED;
;             PG8_LDB(B1, 0, 1); PG8_STAGE(PG8_SB(0, 0), b2);
;             PG8_BAR; PG8_WAIT_L(0); PG8_MMA(0, 1, At, B1); PG8_BAR;
;             PG8_LDA(At, 0, 1); PG8_STAGE(PG8_SA(0, 0), a2);
;             PG8_BAR; PG8_WAIT_L(0); PG8_MMA(1, 0, At, B0); PG8_BAR; PG8_SCHED;
;             PG8_STAGE(PG8_SB(0, 1), b2 + hstep);
;             PG8_WAIT_V(6); PG8_BAR; PG8_MMA(1, 1, At, B1); PG8_BAR;
;             PG8_LDB(B0, 1, 0); PG8_SCHED; PG8_LDA(At, 1, 0); PG8_STAGE(PG8_SA(0, 1), a2 + hstep);
;             PG8_WAIT_L(8); PG8_BAR; PG8_WAIT_L(0); PG8_MMA(0, 0, At, B0); PG8_BAR; PG8_SCHED;
;             PG8_LDB(B1, 1, 1); PG8_STAGE(PG8_SB(1, 0), b3);
;             PG8_BAR; PG8_WAIT_L(0); PG8_MMA(0, 1, At, B1); PG8_BAR;
;             PG8_LDA(At, 1, 1); PG8_STAGE(PG8_SA(1, 0), a3);
;             PG8_BAR; PG8_WAIT_L(0); PG8_MMA(1, 0, At, B0); PG8_BAR; PG8_SCHED;
;             PG8_STAGE(PG8_SB(1, 1), b3 + hstep);
;             PG8_WAIT_V(6); PG8_BAR; PG8_MMA(1, 1, At, B1); PG8_BAR;
;     DI void operator()(const f32x4 (&acc)[2][2][4][2], const Unit& u, int wr, int wc, int fr, int fq) const {
;         const int row0 = u.pm * BM + wr * 64 + fr, col0 = u.pn * BM + wc * 16 + 4 * fq;
;         const bool rot = u.pn < 18;
; #pragma unroll
;         for (int ai = 0; ai < 2; ++ai)
; #pragma unroll
;             for (int m = 0; m < 4; ++m) { const int row = row0 + ai * HALF + m * 16; u16* rowp = O + (size_t)row * NQKV_DIL + col0;
;                 f32x4 c4 = (f32x4){1.f, 1.f, 1.f, 1.f}, s4 = (f32x4){0.f, 0.f, 0.f, 0.f};
;                 if (rot) { const int pos = row & (SEQ - 1); c4 = *(const f32x4*)(cs + pos * 64 + wc * 16 + 4 * fq); s4 = *(const f32x4*)(sn + pos * 64 + wc * 16 + 4 * fq); }
	ds_read_b128 v[194:197], v189 offset:49152
	ds_read_b128 v[198:201], v189 offset:50176
	ds_read_b128 v[202:205], v189 offset:51200
	ds_read_b128 v[206:209], v189 offset:52224
	ds_read_b128 v[210:213], v189 offset:53248
	ds_read_b128 v[214:217], v189 offset:54272
	ds_read_b128 v[226:229], v189 offset:55296
	ds_read_b128 v[230:233], v189 offset:56320
	global_load_lds_dwordx4 v[140:141], off
	s_add_i32 m0, s31, 0xffffff80
	s_nop 0
	global_load_lds_dwordx4 v142, s[100:101] offset:128
	s_waitcnt lgkmcnt(0)
	s_setprio 1
	s_barrier
	v_mfma_f32_16x16x32_bf16 v[60:63], v[128:131], v[194:197], v[60:63]
	v_mfma_f32_16x16x32_bf16 v[56:59], v[136:139], v[194:197], v[56:59]
	v_mfma_f32_16x16x32_bf16 v[44:47], v[128:131], v[202:205], v[44:47]
	v_mfma_f32_16x16x32_bf16 v[40:43], v[136:139], v[202:205], v[40:43]
	v_mfma_f32_16x16x32_bf16 v[28:31], v[128:131], v[210:213], v[28:31]
	v_mfma_f32_16x16x32_bf16 v[24:27], v[136:139], v[210:213], v[24:27]
	v_mfma_f32_16x16x32_bf16 v[12:15], v[128:131], v[226:229], v[12:15]
	v_mfma_f32_16x16x32_bf16 v[8:11], v[136:139], v[226:229], v[8:11]
	v_mfma_f32_16x16x32_bf16 v[60:63], v[132:135], v[198:201], v[60:63]
	v_mfma_f32_16x16x32_bf16 v[56:59], v[190:193], v[198:201], v[56:59]
	v_mfma_f32_16x16x32_bf16 v[44:47], v[132:135], v[206:209], v[44:47]
	v_mfma_f32_16x16x32_bf16 v[40:43], v[190:193], v[206:209], v[40:43]
	v_mfma_f32_16x16x32_bf16 v[28:31], v[132:135], v[214:217], v[28:31]
	v_mfma_f32_16x16x32_bf16 v[24:27], v[190:193], v[214:217], v[24:27]
	v_mfma_f32_16x16x32_bf16 v[12:15], v[132:135], v[230:233], v[12:15]
	s_setprio 0
	v_mfma_f32_16x16x32_bf16 v[8:11], v[190:193], v[230:233], v[8:11]
	s_barrier
	s_add_u32 s18, s18, 0x80080
	s_addc_u32 s19, s19, 0
	s_add_i32 s20, s20, s25
	s_mov_b32 m0, s20
	s_nop 0
	global_load_lds_dwordx4 v144, s[18:19]
	s_add_i32 m0, s20, 0x2000
	s_nop 0
	global_load_lds_dwordx4 v142, s[18:19]
	s_waitcnt vmcnt(6)
	s_setprio 1
	s_barrier
	v_mfma_f32_16x16x32_bf16 v[52:55], v[234:237], v[194:197], v[52:55]
	v_mfma_f32_16x16x32_bf16 v[48:51], v[242:245], v[194:197], v[48:51]
	v_mfma_f32_16x16x32_bf16 v[36:39], v[234:237], v[202:205], v[36:39]
	v_mfma_f32_16x16x32_bf16 v[32:35], v[242:245], v[202:205], v[32:35]
	v_mfma_f32_16x16x32_bf16 v[20:23], v[234:237], v[210:213], v[20:23]
	v_mfma_f32_16x16x32_bf16 v[16:19], v[242:245], v[210:213], v[16:19]
	v_mfma_f32_16x16x32_bf16 v[4:7], v[234:237], v[226:229], v[4:7]
	v_mfma_f32_16x16x32_bf16 v[0:3], v[242:245], v[226:229], v[0:3]
	v_mfma_f32_16x16x32_bf16 v[52:55], v[238:241], v[198:201], v[52:55]
	s_add_i32 s36, s36, 2
	v_mfma_f32_16x16x32_bf16 v[48:51], v[246:249], v[198:201], v[48:51]
	s_add_u32 s8, s8, 0x100
	v_mfma_f32_16x16x32_bf16 v[36:39], v[238:241], v[206:209], v[36:39]
	s_addc_u32 s9, s9, 0
	v_mfma_f32_16x16x32_bf16 v[32:35], v[246:249], v[206:209], v[32:35]
	s_add_u32 s33, s33, 0x100
	v_mfma_f32_16x16x32_bf16 v[20:23], v[238:241], v[214:217], v[20:23]
	s_addc_u32 s35, s35, 0
	v_mfma_f32_16x16x32_bf16 v[16:19], v[246:249], v[214:217], v[16:19]
	s_cmp_gt_u32 s36, 29
	v_mfma_f32_16x16x32_bf16 v[4:7], v[238:241], v[230:233], v[4:7]
	s_setprio 0
	v_mfma_f32_16x16x32_bf16 v[0:3], v[246:249], v[230:233], v[0:3]
	s_barrier
	s_cbranch_scc0 .LBB0_202
	s_cmp_lt_i32 s2, 18
	v_lshl_add_u32 v190, s3, 8, v186
	v_mov_b32_e32 v128, 1.0
	v_mov_b32_e32 v132, 0
	s_cselect_b64 s[18:19], -1, 0
	s_cmp_gt_i32 s2, 17
	v_mov_b32_e32 v134, 0
	v_mov_b32_e32 v135, 0
	v_mov_b32_e32 v136, 0
	v_mov_b32_e32 v137, 0
	v_mov_b32_e32 v138, 1.0
	v_mov_b32_e32 v139, 1.0
	v_mov_b32_e32 v140, 1.0
	v_mov_b32_e32 v141, 1.0
	s_cbranch_scc1 .LBB0_205
	v_lshlrev_b32_e32 v129, 8, v190
	v_and_b32_e32 v158, 0xfcf00, v129
	v_lshl_add_u64 v[130:131], v[146:147], 0, v[158:159]
	v_lshl_add_u64 v[134:135], v[148:149], 0, v[158:159]
	global_load_dwordx4 v[138:141], v[130:131], off
	s_nop 0
	global_load_dwordx4 v[134:137], v[134:135], off

; #define PG8_STAGE(bufoff, gbase) do { _Pragma("unroll") for (int _i = 0; _i < 2; ++_i) \
;         __builtin_amdgcn_global_load_lds((const unsigned*)((const char*)(gbase) + voff[_i]), (LAS unsigned*)(lds + (bufoff) + ldsw + _i * 8192), 16, 0, 0); } while (0)
; #define PG8_LDA(dst, b, h) do { _Pragma("unroll") for (int m = 0; m < 4; ++m) _Pragma("unroll") for (int k = 0; k < 2; ++k) dst[m][k] = *(const LAS bf16x8*)(lds + PG8_SA(b, h) + aoff + m * 2048 + k * 1024); } while (0)
; #define PG8_LDB(dst, b, h) do { _Pragma("unroll") for (int n = 0; n < 2; ++n) _Pragma("unroll") for (int k = 0; k < 2; ++k) dst[n][k] = *(const LAS bf16x8*)(lds + PG8_SB(b, h) + boff + n * 2048 + k * 1024); } while (0)
; template <class Epi>
; DI void gemm_phase(LAS unsigned char* lds, const Gemm g, const StaticOrder& S, const Epi& E) {
;     ...
;         for (int t = 0; t < nt; t += 2) {
;             const bool last = (t == nt - 2);
;             const char* a1 = cA + (size_t)(t + 1) * kstep;
;             const char* a2 = last ? nA : cA + (size_t)(t + 2) * kstep; const char* b2 = last ? nB : cB + (size_t)(t + 2) * kstep;
;             const char* a3 = a2 + kstep; const char* b3 = b2 + kstep;
;             PG8_LDB(B0, 0, 0); PG8_SCHED; PG8_LDA(At, 0, 0); PG8_STAGE(PG8_SA(1, 1), a1 + hstep);
;             PG8_WAIT_L(8); PG8_BAR; PG8_WAIT_L(0); PG8_MMA(0, 0, At, B0); PG8_BAR; PG8_SCHED;
;             PG8_LDB(B1, 0, 1); PG8_STAGE(PG8_SB(0, 0), b2);
;             PG8_BAR; PG8_WAIT_L(0); PG8_MMA(0, 1, At, B1); PG8_BAR;
;             PG8_LDA(At, 0, 1); PG8_STAGE(PG8_SA(0, 0), a2);
;             PG8_BAR; PG8_WAIT_L(0); PG8_MMA(1, 0, At, B0); PG8_BAR; PG8_SCHED;
;             PG8_STAGE(PG8_SB(0, 1), b2 + hstep);
;             PG8_WAIT_V(6); PG8_BAR; PG8_MMA(1, 1, At, B1); PG8_BAR;
;             PG8_LDB(B0, 1, 0); PG8_SCHED; PG8_LDA(At, 1, 0); PG8_STAGE(PG8_SA(0, 1), a2 + hstep);
;             PG8_WAIT_L(8); PG8_BAR; PG8_WAIT_L(0); PG8_MMA(0, 0, At, B0); PG8_BAR; PG8_SCHED;
;             PG8_LDB(B1, 1, 1); PG8_STAGE(PG8_SB(1, 0), b3);
;             PG8_BAR; PG8_WAIT_L(0); PG8_MMA(0, 1, At, B1); PG8_BAR;
;             PG8_LDA(At, 1, 1); PG8_STAGE(PG8_SA(1, 0), a3);
;             PG8_BAR; PG8_WAIT_L(0); PG8_MMA(1, 0, At, B0); PG8_BAR; PG8_SCHED;
;             PG8_STAGE(PG8_SB(1, 1), b3 + hstep);
;             PG8_WAIT_V(6); PG8_BAR; PG8_MMA(1, 1, At, B1); PG8_BAR;
.LBB0_231:
	s_add_u32 s18, s16, 0xfff80080
	s_addc_u32 s19, s17, -1
	s_add_i32 s37, 0, 0x10000
	ds_read_b128 v[138:141], v135
	ds_read_b128 v[142:145], v135 offset:1024
	ds_read_b128 v[146:149], v135 offset:2048
	ds_read_b128 v[150:153], v135 offset:3072
	s_cmp_eq_u32 s36, 28
	s_cselect_b32 s21, s4, s19
	s_cselect_b32 s20, s5, s18
	s_cselect_b32 s19, s9, s35
	s_cselect_b32 s18, s11, s34
	s_add_i32 m0, s24, 0xc000
	ds_read_b128 v[186:189], v137
	ds_read_b128 v[190:193], v137 offset:1024
	ds_read_b128 v[194:197], v137 offset:2048
	ds_read_b128 v[198:201], v137 offset:3072
	ds_read_b128 v[202:205], v137 offset:4096
	ds_read_b128 v[206:209], v137 offset:5120
	ds_read_b128 v[210:213], v137 offset:6144
	ds_read_b128 v[214:217], v137 offset:7168
	global_load_lds_dwordx4 v130, s[16:17]
	s_add_i32 m0, s24, 0xe000
	s_nop 0
	global_load_lds_dwordx4 v132, s[16:17]
	s_waitcnt lgkmcnt(8)
	s_setprio 1
	s_barrier
	s_waitcnt lgkmcnt(0)
	v_mfma_f32_16x16x32_bf16 v[124:127], v[138:141], v[186:189], v[124:127]
	v_mfma_f32_16x16x32_bf16 v[120:123], v[146:149], v[186:189], v[120:123]
	v_mfma_f32_16x16x32_bf16 v[116:119], v[138:141], v[194:197], v[116:119]
	v_mfma_f32_16x16x32_bf16 v[112:115], v[146:149], v[194:197], v[112:115]
	v_mfma_f32_16x16x32_bf16 v[100:103], v[138:141], v[202:205], v[100:103]
	v_mfma_f32_16x16x32_bf16 v[96:99], v[146:149], v[202:205], v[96:99]
	v_mfma_f32_16x16x32_bf16 v[84:87], v[138:141], v[210:213], v[84:87]
	v_mfma_f32_16x16x32_bf16 v[80:83], v[146:149], v[210:213], v[80:83]
	v_mfma_f32_16x16x32_bf16 v[124:127], v[142:145], v[190:193], v[124:127]
	v_mfma_f32_16x16x32_bf16 v[120:123], v[150:153], v[190:193], v[120:123]
	v_mfma_f32_16x16x32_bf16 v[116:119], v[142:145], v[198:201], v[116:119]
	v_mfma_f32_16x16x32_bf16 v[112:115], v[150:153], v[198:201], v[112:115]
	v_mfma_f32_16x16x32_bf16 v[100:103], v[142:145], v[206:209], v[100:103]
	v_mfma_f32_16x16x32_bf16 v[96:99], v[150:153], v[206:209], v[96:99]
	v_mfma_f32_16x16x32_bf16 v[84:87], v[142:145], v[214:217], v[84:87]
	s_setprio 0
	v_mfma_f32_16x16x32_bf16 v[80:83], v[150:153], v[214:217], v[80:83]
	s_barrier
	s_add_i32 s40, 0, 0x14000
	s_add_i32 s37, s37, s23
	ds_read_b128 v[226:229], v135 offset:16384
	ds_read_b128 v[230:233], v135 offset:17408
	ds_read_b128 v[234:237], v135 offset:18432
	ds_read_b128 v[238:241], v135 offset:19456
	s_mov_b32 m0, s37
	s_nop 0
	global_load_lds_dwordx4 v158, s[18:19]
	s_add_i32 m0, s37, 0x2000
	s_nop 0
	global_load_lds_dwordx4 v128, s[18:19]
	s_waitcnt lgkmcnt(0)
	s_setprio 1
	s_barrier
	v_mfma_f32_16x16x32_bf16 v[108:111], v[226:229], v[186:189], v[108:111]
	v_mfma_f32_16x16x32_bf16 v[104:107], v[234:237], v[186:189], v[104:107]
	v_mfma_f32_16x16x32_bf16 v[92:95], v[226:229], v[194:197], v[92:95]
	v_mfma_f32_16x16x32_bf16 v[88:91], v[234:237], v[194:197], v[88:91]
	v_mfma_f32_16x16x32_bf16 v[76:79], v[226:229], v[202:205], v[76:79]
	v_mfma_f32_16x16x32_bf16 v[72:75], v[234:237], v[202:205], v[72:75]
	v_mfma_f32_16x16x32_bf16 v[68:71], v[226:229], v[210:213], v[68:71]
	v_mfma_f32_16x16x32_bf16 v[64:67], v[234:237], v[210:213], v[64:67]
	v_mfma_f32_16x16x32_bf16 v[108:111], v[230:233], v[190:193], v[108:111]
	s_mov_b32 m0, s24
	v_mfma_f32_16x16x32_bf16 v[104:107], v[238:241], v[190:193], v[104:107]
	v_lshl_add_u64 v[242:243], s[20:21], 0, v[158:159]
	v_mfma_f32_16x16x32_bf16 v[92:95], v[230:233], v[198:201], v[92:95]
	v_mfma_f32_16x16x32_bf16 v[88:91], v[238:241], v[198:201], v[88:91]
	v_mfma_f32_16x16x32_bf16 v[76:79], v[230:233], v[206:209], v[76:79]
	v_mfma_f32_16x16x32_bf16 v[72:75], v[238:241], v[206:209], v[72:75]
	v_mfma_f32_16x16x32_bf16 v[68:71], v[230:233], v[214:217], v[68:71]
	s_setprio 0
	v_mfma_f32_16x16x32_bf16 v[64:67], v[238:241], v[214:217], v[64:67]
	s_barrier
	ds_read_b128 v[186:189], v137 offset:16384
	ds_read_b128 v[190:193], v137 offset:17408
	ds_read_b128 v[194:197], v137 offset:18432
	ds_read_b128 v[198:201], v137 offset:19456
	ds_read_b128 v[202:205], v137 offset:20480
	ds_read_b128 v[206:209], v137 offset:21504
	ds_read_b128 v[210:213], v137 offset:22528
	ds_read_b128 v[214:217], v137 offset:23552
	global_load_lds_dwordx4 v[242:243], off
	s_mov_b64 s[100:101], s[20:21]
	s_mov_b32 m0, s25
	s_nop 0
	global_load_lds_dwordx4 v128, s[20:21]
	s_waitcnt lgkmcnt(0)
	s_setprio 1
	s_barrier
	v_mfma_f32_16x16x32_bf16 v[60:63], v[138:141], v[186:189], v[60:63]
	v_mfma_f32_16x16x32_bf16 v[56:59], v[146:149], v[186:189], v[56:59]
	v_mfma_f32_16x16x32_bf16 v[52:55], v[138:141], v[194:197], v[52:55]
	v_mfma_f32_16x16x32_bf16 v[48:51], v[146:149], v[194:197], v[48:51]
	v_mfma_f32_16x16x32_bf16 v[36:39], v[138:141], v[202:205], v[36:39]
	v_mfma_f32_16x16x32_bf16 v[32:35], v[146:149], v[202:205], v[32:35]
	v_mfma_f32_16x16x32_bf16 v[20:23], v[138:141], v[210:213], v[20:23]
	v_mfma_f32_16x16x32_bf16 v[16:19], v[146:149], v[210:213], v[16:19]
	v_mfma_f32_16x16x32_bf16 v[60:63], v[142:145], v[190:193], v[60:63]
	v_mfma_f32_16x16x32_bf16 v[56:59], v[150:153], v[190:193], v[56:59]
	v_mfma_f32_16x16x32_bf16 v[52:55], v[142:145], v[198:201], v[52:55]
	v_mfma_f32_16x16x32_bf16 v[48:51], v[150:153], v[198:201], v[48:51]
	v_mfma_f32_16x16x32_bf16 v[36:39], v[142:145], v[206:209], v[36:39]
	v_mfma_f32_16x16x32_bf16 v[32:35], v[150:153], v[206:209], v[32:35]
	v_mfma_f32_16x16x32_bf16 v[20:23], v[142:145], v[214:217], v[20:23]
	s_setprio 0
	v_mfma_f32_16x16x32_bf16 v[16:19], v[150:153], v[214:217], v[16:19]
	s_barrier
	s_add_u32 s38, s18, 0x80000
	s_addc_u32 s39, s19, 0
	s_add_i32 s37, s40, s23
	s_mov_b32 m0, s37
	s_nop 0
	global_load_lds_dwordx4 v158, s[38:39]
	s_add_i32 m0, s37, 0x2000
	s_nop 0
	global_load_lds_dwordx4 v128, s[38:39]
	s_waitcnt vmcnt(6)
	s_setprio 1
	s_barrier
; #define PG8_STAGE(bufoff, gbase) do { _Pragma("unroll") for (int _i = 0; _i < 2; ++_i) \
;         __builtin_amdgcn_global_load_lds((const unsigned*)((const char*)(gbase) + voff[_i]), (LAS unsigned*)(lds + (bufoff) + ldsw + _i * 8192), 16, 0, 0); } while (0)
; #define PG8_LDA(dst, b, h) do { _Pragma("unroll") for (int m = 0; m < 4; ++m) _Pragma("unroll") for (int k = 0; k < 2; ++k) dst[m][k] = *(const LAS bf16x8*)(lds + PG8_SA(b, h) + aoff + m * 2048 + k * 1024); } while (0)
; #define PG8_LDB(dst, b, h) do { _Pragma("unroll") for (int n = 0; n < 2; ++n) _Pragma("unroll") for (int k = 0; k < 2; ++k) dst[n][k] = *(const LAS bf16x8*)(lds + PG8_SB(b, h) + boff + n * 2048 + k * 1024); } while (0)
; template <class Epi>
; DI void gemm_phase(LAS unsigned char* lds, const Gemm g, const StaticOrder& S, const Epi& E) {
;     ...
;         for (int t = 0; t < nt; t += 2) {
;             const bool last = (t == nt - 2);
;             const char* a1 = cA + (size_t)(t + 1) * kstep;
;             const char* a2 = last ? nA : cA + (size_t)(t + 2) * kstep; const char* b2 = last ? nB : cB + (size_t)(t + 2) * kstep;
;             const char* a3 = a2 + kstep; const char* b3 = b2 + kstep;
;             PG8_LDB(B0, 0, 0); PG8_SCHED; PG8_LDA(At, 0, 0); PG8_STAGE(PG8_SA(1, 1), a1 + hstep);
;             PG8_WAIT_L(8); PG8_BAR; PG8_WAIT_L(0); PG8_MMA(0, 0, At, B0); PG8_BAR; PG8_SCHED;
;             PG8_LDB(B1, 0, 1); PG8_STAGE(PG8_SB(0, 0), b2);
;             PG8_BAR; PG8_WAIT_L(0); PG8_MMA(0, 1, At, B1); PG8_BAR;
;             PG8_LDA(At, 0, 1); PG8_STAGE(PG8_SA(0, 0), a2);
;             PG8_BAR; PG8_WAIT_L(0); PG8_MMA(1, 0, At, B0); PG8_BAR; PG8_SCHED;
;             PG8_STAGE(PG8_SB(0, 1), b2 + hstep);
;             PG8_WAIT_V(6); PG8_BAR; PG8_MMA(1, 1, At, B1); PG8_BAR;
;             PG8_LDB(B0, 1, 0); PG8_SCHED; PG8_LDA(At, 1, 0); PG8_STAGE(PG8_SA(0, 1), a2 + hstep);
;             PG8_WAIT_L(8); PG8_BAR; PG8_WAIT_L(0); PG8_MMA(0, 0, At, B0); PG8_BAR; PG8_SCHED;
;             PG8_LDB(B1, 1, 1); PG8_STAGE(PG8_SB(1, 0), b3);
;             PG8_BAR; PG8_WAIT_L(0); PG8_MMA(0, 1, At, B1); PG8_BAR;
;             PG8_LDA(At, 1, 1); PG8_STAGE(PG8_SA(1, 0), a3);
;             PG8_BAR; PG8_WAIT_L(0); PG8_MMA(1, 0, At, B0); PG8_BAR; PG8_SCHED;
;             PG8_STAGE(PG8_SB(1, 1), b3 + hstep);
;             PG8_WAIT_V(6); PG8_BAR; PG8_MMA(1, 1, At, B1); PG8_BAR;
	v_mfma_f32_16x16x32_bf16 v[44:47], v[226:229], v[186:189], v[44:47]
	v_mfma_f32_16x16x32_bf16 v[40:43], v[234:237], v[186:189], v[40:43]
	v_mfma_f32_16x16x32_bf16 v[28:31], v[226:229], v[194:197], v[28:31]
	v_mfma_f32_16x16x32_bf16 v[24:27], v[234:237], v[194:197], v[24:27]
	v_mfma_f32_16x16x32_bf16 v[12:15], v[226:229], v[202:205], v[12:15]
	v_mfma_f32_16x16x32_bf16 v[8:11], v[234:237], v[202:205], v[8:11]
	v_mfma_f32_16x16x32_bf16 v[4:7], v[226:229], v[210:213], v[4:7]
	v_mfma_f32_16x16x32_bf16 v[0:3], v[234:237], v[210:213], v[0:3]
	v_mfma_f32_16x16x32_bf16 v[44:47], v[230:233], v[190:193], v[44:47]
	s_add_i32 s37, 0, 0x18000
	v_mfma_f32_16x16x32_bf16 v[40:43], v[238:241], v[190:193], v[40:43]
	v_mfma_f32_16x16x32_bf16 v[28:31], v[230:233], v[198:201], v[28:31]
	v_mfma_f32_16x16x32_bf16 v[24:27], v[238:241], v[198:201], v[24:27]
	v_mfma_f32_16x16x32_bf16 v[12:15], v[230:233], v[206:209], v[12:15]
	v_mfma_f32_16x16x32_bf16 v[8:11], v[238:241], v[206:209], v[8:11]
	v_mfma_f32_16x16x32_bf16 v[4:7], v[230:233], v[214:217], v[4:7]
	s_setprio 0
	v_mfma_f32_16x16x32_bf16 v[0:3], v[238:241], v[214:217], v[0:3]
	s_barrier
	ds_read_b128 v[138:141], v135 offset:32768
	ds_read_b128 v[142:145], v135 offset:33792
	ds_read_b128 v[146:149], v135 offset:34816
	ds_read_b128 v[150:153], v135 offset:35840
	s_add_u32 s20, s20, 0x80000
	s_addc_u32 s21, s21, 0
	s_mov_b32 m0, s26
	ds_read_b128 v[186:189], v137 offset:32768
	ds_read_b128 v[190:193], v137 offset:33792
	ds_read_b128 v[194:197], v137 offset:34816
	ds_read_b128 v[198:201], v137 offset:35840
	ds_read_b128 v[202:205], v137 offset:36864
	ds_read_b128 v[206:209], v137 offset:37888
	ds_read_b128 v[210:213], v137 offset:38912
	ds_read_b128 v[214:217], v137 offset:39936
	global_load_lds_dwordx4 v158, s[20:21]
	s_mov_b32 m0, s27
	s_nop 0
	global_load_lds_dwordx4 v128, s[20:21]
	s_waitcnt lgkmcnt(8)
	s_setprio 1
	s_barrier
	s_waitcnt lgkmcnt(0)
	v_mfma_f32_16x16x32_bf16 v[124:127], v[138:141], v[186:189], v[124:127]
	v_mfma_f32_16x16x32_bf16 v[120:123], v[146:149], v[186:189], v[120:123]
	v_mfma_f32_16x16x32_bf16 v[116:119], v[138:141], v[194:197], v[116:119]
	v_mfma_f32_16x16x32_bf16 v[112:115], v[146:149], v[194:197], v[112:115]
	v_mfma_f32_16x16x32_bf16 v[100:103], v[138:141], v[202:205], v[100:103]
	v_mfma_f32_16x16x32_bf16 v[96:99], v[146:149], v[202:205], v[96:99]
	v_mfma_f32_16x16x32_bf16 v[84:87], v[138:141], v[210:213], v[84:87]
	v_mfma_f32_16x16x32_bf16 v[80:83], v[146:149], v[210:213], v[80:83]
	v_mfma_f32_16x16x32_bf16 v[124:127], v[142:145], v[190:193], v[124:127]
	v_mfma_f32_16x16x32_bf16 v[120:123], v[150:153], v[190:193], v[120:123]
	v_mfma_f32_16x16x32_bf16 v[116:119], v[142:145], v[198:201], v[116:119]
	v_mfma_f32_16x16x32_bf16 v[112:115], v[150:153], v[198:201], v[112:115]
	v_mfma_f32_16x16x32_bf16 v[100:103], v[142:145], v[206:209], v[100:103]
	v_mfma_f32_16x16x32_bf16 v[96:99], v[150:153], v[206:209], v[96:99]
	v_mfma_f32_16x16x32_bf16 v[84:87], v[142:145], v[214:217], v[84:87]
	s_setprio 0
	v_mfma_f32_16x16x32_bf16 v[80:83], v[150:153], v[214:217], v[80:83]
	s_barrier
	s_add_i32 s20, 0, 0x1c000
	s_add_i32 s21, s37, s23
	s_add_i32 m0, s21, 0xffffff80
	ds_read_b128 v[226:229], v135 offset:49152
	ds_read_b128 v[230:233], v135 offset:50176
	ds_read_b128 v[234:237], v135 offset:51200
	ds_read_b128 v[238:241], v135 offset:52224
	global_load_lds_dwordx4 v158, s[18:19] offset:128
	s_add_i32 m0, s21, 0x1f80
	s_nop 0
	global_load_lds_dwordx4 v128, s[18:19] offset:128
	s_waitcnt lgkmcnt(0)
	s_setprio 1
	s_barrier
	v_mfma_f32_16x16x32_bf16 v[108:111], v[226:229], v[186:189], v[108:111]
	v_mfma_f32_16x16x32_bf16 v[104:107], v[234:237], v[186:189], v[104:107]
	v_mfma_f32_16x16x32_bf16 v[92:95], v[226:229], v[194:197], v[92:95]
	v_mfma_f32_16x16x32_bf16 v[88:91], v[234:237], v[194:197], v[88:91]
	v_mfma_f32_16x16x32_bf16 v[76:79], v[226:229], v[202:205], v[76:79]
	v_mfma_f32_16x16x32_bf16 v[72:75], v[234:237], v[202:205], v[72:75]
	v_mfma_f32_16x16x32_bf16 v[68:71], v[226:229], v[210:213], v[68:71]
	v_mfma_f32_16x16x32_bf16 v[64:67], v[234:237], v[210:213], v[64:67]
	v_mfma_f32_16x16x32_bf16 v[108:111], v[230:233], v[190:193], v[108:111]
	s_mov_b32 m0, s28
	v_mfma_f32_16x16x32_bf16 v[104:107], v[238:241], v[190:193], v[104:107]
	v_lshl_add_u64 v[154:155], v[242:243], 0, s[94:95]
	v_mfma_f32_16x16x32_bf16 v[92:95], v[230:233], v[198:201], v[92:95]
	v_mfma_f32_16x16x32_bf16 v[88:91], v[238:241], v[198:201], v[88:91]
	v_mfma_f32_16x16x32_bf16 v[76:79], v[230:233], v[206:209], v[76:79]
	v_mfma_f32_16x16x32_bf16 v[72:75], v[238:241], v[206:209], v[72:75]
	v_mfma_f32_16x16x32_bf16 v[68:71], v[230:233], v[214:217], v[68:71]
	s_setprio 0
	v_mfma_f32_16x16x32_bf16 v[64:67], v[238:241], v[214:217], v[64:67]
	s_barrier
	ds_read_b128 v[186:189], v137 offset:49152
	ds_read_b128 v[190:193], v137 offset:50176
	ds_read_b128 v[194:197], v137 offset:51200
	ds_read_b128 v[198:201], v137 offset:52224
	ds_read_b128 v[202:205], v137 offset:53248
	ds_read_b128 v[206:209], v137 offset:54272
	ds_read_b128 v[210:213], v137 offset:55296
	ds_read_b128 v[214:217], v137 offset:56320
	global_load_lds_dwordx4 v[154:155], off
	s_add_i32 m0, s29, 0xffffff80
	s_nop 0
	global_load_lds_dwordx4 v128, s[100:101] offset:128
	s_waitcnt lgkmcnt(0)
	s_setprio 1
	s_barrier
; #define PG8_STAGE(bufoff, gbase) do { _Pragma("unroll") for (int _i = 0; _i < 2; ++_i) \
;         __builtin_amdgcn_global_load_lds((const unsigned*)((const char*)(gbase) + voff[_i]), (LAS unsigned*)(lds + (bufoff) + ldsw + _i * 8192), 16, 0, 0); } while (0)
; #define PG8_LDA(dst, b, h) do { _Pragma("unroll") for (int m = 0; m < 4; ++m) _Pragma("unroll") for (int k = 0; k < 2; ++k) dst[m][k] = *(const LAS bf16x8*)(lds + PG8_SA(b, h) + aoff + m * 2048 + k * 1024); } while (0)
; #define PG8_LDB(dst, b, h) do { _Pragma("unroll") for (int n = 0; n < 2; ++n) _Pragma("unroll") for (int k = 0; k < 2; ++k) dst[n][k] = *(const LAS bf16x8*)(lds + PG8_SB(b, h) + boff + n * 2048 + k * 1024); } while (0)
; template <class Epi>
; DI void gemm_phase(LAS unsigned char* lds, const Gemm g, const StaticOrder& S, const Epi& E) {
;     ...
;         for (int t = 0; t < nt; t += 2) {
;             const bool last = (t == nt - 2);
;             const char* a1 = cA + (size_t)(t + 1) * kstep;
;             const char* a2 = last ? nA : cA + (size_t)(t + 2) * kstep; const char* b2 = last ? nB : cB + (size_t)(t + 2) * kstep;
;             const char* a3 = a2 + kstep; const char* b3 = b2 + kstep;
;             PG8_LDB(B0, 0, 0); PG8_SCHED; PG8_LDA(At, 0, 0); PG8_STAGE(PG8_SA(1, 1), a1 + hstep);
;             PG8_WAIT_L(8); PG8_BAR; PG8_WAIT_L(0); PG8_MMA(0, 0, At, B0); PG8_BAR; PG8_SCHED;
;             PG8_LDB(B1, 0, 1); PG8_STAGE(PG8_SB(0, 0), b2);
;             PG8_BAR; PG8_WAIT_L(0); PG8_MMA(0, 1, At, B1); PG8_BAR;
;             PG8_LDA(At, 0, 1); PG8_STAGE(PG8_SA(0, 0), a2);
;             PG8_BAR; PG8_WAIT_L(0); PG8_MMA(1, 0, At, B0); PG8_BAR; PG8_SCHED;
;             PG8_STAGE(PG8_SB(0, 1), b2 + hstep);
;             PG8_WAIT_V(6); PG8_BAR; PG8_MMA(1, 1, At, B1); PG8_BAR;
;             PG8_LDB(B0, 1, 0); PG8_SCHED; PG8_LDA(At, 1, 0); PG8_STAGE(PG8_SA(0, 1), a2 + hstep);
;             PG8_WAIT_L(8); PG8_BAR; PG8_WAIT_L(0); PG8_MMA(0, 0, At, B0); PG8_BAR; PG8_SCHED;
;             PG8_LDB(B1, 1, 1); PG8_STAGE(PG8_SB(1, 0), b3);
;             PG8_BAR; PG8_WAIT_L(0); PG8_MMA(0, 1, At, B1); PG8_BAR;
;             PG8_LDA(At, 1, 1); PG8_STAGE(PG8_SA(1, 0), a3);
;             PG8_BAR; PG8_WAIT_L(0); PG8_MMA(1, 0, At, B0); PG8_BAR; PG8_SCHED;
;             PG8_STAGE(PG8_SB(1, 1), b3 + hstep);
;             PG8_WAIT_V(6); PG8_BAR; PG8_MMA(1, 1, At, B1); PG8_BAR;
	v_mfma_f32_16x16x32_bf16 v[60:63], v[138:141], v[186:189], v[60:63]
	v_mfma_f32_16x16x32_bf16 v[56:59], v[146:149], v[186:189], v[56:59]
	v_mfma_f32_16x16x32_bf16 v[52:55], v[138:141], v[194:197], v[52:55]
	v_mfma_f32_16x16x32_bf16 v[48:51], v[146:149], v[194:197], v[48:51]
	v_mfma_f32_16x16x32_bf16 v[36:39], v[138:141], v[202:205], v[36:39]
	v_mfma_f32_16x16x32_bf16 v[32:35], v[146:149], v[202:205], v[32:35]
	v_mfma_f32_16x16x32_bf16 v[20:23], v[138:141], v[210:213], v[20:23]
	v_mfma_f32_16x16x32_bf16 v[16:19], v[146:149], v[210:213], v[16:19]
	v_mfma_f32_16x16x32_bf16 v[60:63], v[142:145], v[190:193], v[60:63]
	v_mfma_f32_16x16x32_bf16 v[56:59], v[150:153], v[190:193], v[56:59]
	v_mfma_f32_16x16x32_bf16 v[52:55], v[142:145], v[198:201], v[52:55]
	v_mfma_f32_16x16x32_bf16 v[48:51], v[150:153], v[198:201], v[48:51]
	v_mfma_f32_16x16x32_bf16 v[36:39], v[142:145], v[206:209], v[36:39]
	v_mfma_f32_16x16x32_bf16 v[32:35], v[150:153], v[206:209], v[32:35]
	v_mfma_f32_16x16x32_bf16 v[20:23], v[142:145], v[214:217], v[20:23]
	s_setprio 0
	v_mfma_f32_16x16x32_bf16 v[16:19], v[150:153], v[214:217], v[16:19]
	s_barrier
	s_add_u32 s18, s18, 0x80080
	s_addc_u32 s19, s19, 0
	s_add_i32 s20, s20, s23
	s_mov_b32 m0, s20
	s_nop 0
	global_load_lds_dwordx4 v158, s[18:19]
	s_add_i32 m0, s20, 0x2000
	s_nop 0
	global_load_lds_dwordx4 v128, s[18:19]
	s_waitcnt vmcnt(6)
	s_setprio 1
	s_barrier
	v_mfma_f32_16x16x32_bf16 v[44:47], v[226:229], v[186:189], v[44:47]
	v_mfma_f32_16x16x32_bf16 v[40:43], v[234:237], v[186:189], v[40:43]
	v_mfma_f32_16x16x32_bf16 v[28:31], v[226:229], v[194:197], v[28:31]
	v_mfma_f32_16x16x32_bf16 v[24:27], v[234:237], v[194:197], v[24:27]
	v_mfma_f32_16x16x32_bf16 v[12:15], v[226:229], v[202:205], v[12:15]
	v_mfma_f32_16x16x32_bf16 v[8:11], v[234:237], v[202:205], v[8:11]
	v_mfma_f32_16x16x32_bf16 v[4:7], v[226:229], v[210:213], v[4:7]
	v_mfma_f32_16x16x32_bf16 v[0:3], v[234:237], v[210:213], v[0:3]
	v_mfma_f32_16x16x32_bf16 v[44:47], v[230:233], v[190:193], v[44:47]
	s_add_i32 s36, s36, 2
	v_mfma_f32_16x16x32_bf16 v[40:43], v[238:241], v[190:193], v[40:43]
	s_add_u32 s16, s16, 0x100
	v_mfma_f32_16x16x32_bf16 v[28:31], v[230:233], v[198:201], v[28:31]
	s_addc_u32 s17, s17, 0
	v_mfma_f32_16x16x32_bf16 v[24:27], v[238:241], v[198:201], v[24:27]
	s_add_u32 s34, s34, 0x100
	v_mfma_f32_16x16x32_bf16 v[12:15], v[230:233], v[206:209], v[12:15]
	s_addc_u32 s35, s35, 0
	v_mfma_f32_16x16x32_bf16 v[8:11], v[238:241], v[206:209], v[8:11]
	s_cmp_gt_u32 s36, 29
	v_mfma_f32_16x16x32_bf16 v[4:7], v[230:233], v[214:217], v[4:7]
	s_setprio 0
	v_mfma_f32_16x16x32_bf16 v[0:3], v[238:241], v[214:217], v[0:3]
	s_barrier
	s_cbranch_scc0 .LBB0_231
; #define PG8_WAIT_V(n) asm volatile("s_waitcnt vmcnt(" #n ")" ::: "memory")
; #define PG8_BAR __builtin_amdgcn_s_barrier()
; template <class Epi>
; DI void gemm_phase(LAS unsigned char* lds, const Gemm g, const StaticOrder& S, const Epi& E) {
;     ...
;         E(acc, cur, wr, wc, fr, fq);
;         if (!has_next) break;
; #pragma unroll
;         for (int a = 0; a < 2; ++a)
; #pragma unroll
;             for (int b = 0; b < 2; ++b)
; #pragma unroll
;                 for (int m = 0; m < 4; ++m)
; #pragma unroll
;                     for (int n = 0; n < 2; ++n) acc[a][b][m][n] = (f32x4){0.f, 0.f, 0.f, 0.f};
;         cur = nxt; cA = nA; cB = nB; ++ui;
;     }
;     PG8_WAIT_V(0);
;     if (wr == 0) PG8_BAR;
;     PG8_BAR;
;     DI void operator()(const f32x4 (&acc)[2][2][4][2], const Unit& u, int wr, int wc, int fr, int fq) const {
;         const int row0 = u.pm * BM + wr * 64 + fr, col0 = u.pn * BM + wc * 32 + 8 * fq;
; #pragma unroll
;         for (int ai = 0; ai < 2; ++ai)
; #pragma unroll
;             for (int m = 0; m < 4; ++m) { u16* rowp = O + (size_t)(row0 + ai * HALF + m * 16) * ldc + col0;
; #pragma unroll
;                 for (int bj = 0; bj < 2; ++bj) { const f32x4 v0 = acc[ai][bj][m][0], v1 = acc[ai][bj][m][1];
;                     *(u32x4*)(rowp + bj * HALF) = (u32x4){pk(v0[0], v0[1]), pk(v0[2], v0[3]), pk(v1[0], v1[1]), pk(v1[2], v1[3])}; } }
	v_lshl_add_u32 v144, s33, 8, v134
	v_lshl_or_b32 v138, s31, 8, v136
	v_ashrrev_i32_e32 v139, 31, v138
	v_mov_b64_e32 v[140:141], s[50:51]
	s_movk_i32 s9, 0x3000
	v_cvt_pk_bf16_f32 v68, v68, v69
	v_cvt_pk_bf16_f32 v69, v70, v71
	v_cvt_pk_bf16_f32 v70, v64, v65
	v_add_u32_e32 v64, 0x80, v144
	v_mad_i64_i32 v[142:143], s[4:5], v144, s9, v[140:141]
	v_lshlrev_b64 v[138:139], 1, v[138:139]
	v_cvt_pk_bf16_f32 v108, v108, v109
	v_cvt_pk_bf16_f32 v109, v110, v111
	v_cvt_pk_bf16_f32 v110, v104, v105
	v_or_b32_e32 v104, 16, v144
	v_mad_i64_i32 v[64:65], s[4:5], v64, s9, v[140:141]
	v_cvt_pk_bf16_f32 v44, v44, v45
	v_cvt_pk_bf16_f32 v45, v46, v47
	v_cvt_pk_bf16_f32 v46, v40, v41
	v_add_u32_e32 v40, 0x90, v144
	v_lshl_add_u64 v[142:143], v[142:143], 0, v[138:139]
	v_cvt_pk_bf16_f32 v111, v106, v107
	v_mad_i64_i32 v[104:105], s[4:5], v104, s9, v[140:141]
	v_cvt_pk_bf16_f32 v92, v92, v93
	v_cvt_pk_bf16_f32 v93, v94, v95
	v_cvt_pk_bf16_f32 v94, v88, v89
	v_or_b32_e32 v88, 32, v144
	v_lshl_add_u64 v[64:65], v[64:65], 0, v[138:139]
	v_cvt_pk_bf16_f32 v47, v42, v43
	v_mad_i64_i32 v[40:41], s[4:5], v40, s9, v[140:141]
	v_cvt_pk_bf16_f32 v28, v28, v29
	v_cvt_pk_bf16_f32 v29, v30, v31
	v_cvt_pk_bf16_f32 v30, v24, v25
	v_add_u32_e32 v24, 0xa0, v144
	global_store_dwordx4 v[142:143], v[108:111], off offset:256
	v_cvt_pk_bf16_f32 v95, v90, v91
	v_mad_i64_i32 v[88:89], s[4:5], v88, s9, v[140:141]
	v_lshl_add_u64 v[108:109], v[104:105], 0, v[138:139]
	v_cvt_pk_bf16_f32 v76, v76, v77
	v_cvt_pk_bf16_f32 v77, v78, v79
	v_cvt_pk_bf16_f32 v78, v72, v73
	v_or_b32_e32 v72, 48, v144
	global_store_dwordx4 v[64:65], v[44:47], off offset:256
	v_cvt_pk_bf16_f32 v31, v26, v27
	v_mad_i64_i32 v[24:25], s[4:5], v24, s9, v[140:141]
	v_lshl_add_u64 v[44:45], v[40:41], 0, v[138:139]
	v_cvt_pk_bf16_f32 v12, v12, v13
	v_cvt_pk_bf16_f32 v13, v14, v15
	v_cvt_pk_bf16_f32 v14, v8, v9
	v_add_u32_e32 v8, 0xb0, v144
	global_store_dwordx4 v[108:109], v[92:95], off offset:256
	v_cvt_pk_bf16_f32 v79, v74, v75
	v_mad_i64_i32 v[72:73], s[4:5], v72, s9, v[140:141]
	v_lshl_add_u64 v[92:93], v[88:89], 0, v[138:139]
	global_store_dwordx4 v[44:45], v[28:31], off offset:256
	v_cvt_pk_bf16_f32 v15, v10, v11
	v_mad_i64_i32 v[8:9], s[4:5], v8, s9, v[140:141]
	v_lshl_add_u64 v[28:29], v[24:25], 0, v[138:139]
	v_cvt_pk_bf16_f32 v124, v124, v125
	v_cvt_pk_bf16_f32 v125, v126, v127
	v_cvt_pk_bf16_f32 v126, v120, v121
	v_cvt_pk_bf16_f32 v127, v122, v123
	v_cvt_pk_bf16_f32 v104, v116, v117
	v_cvt_pk_bf16_f32 v105, v118, v119
	v_cvt_pk_bf16_f32 v106, v112, v113
	v_cvt_pk_bf16_f32 v107, v114, v115
	v_cvt_pk_bf16_f32 v88, v100, v101
	v_cvt_pk_bf16_f32 v89, v102, v103
	v_cvt_pk_bf16_f32 v90, v96, v97
	v_cvt_pk_bf16_f32 v91, v98, v99
	global_store_dwordx4 v[92:93], v[76:79], off offset:256
	v_cvt_pk_bf16_f32 v74, v80, v81
	v_cvt_pk_bf16_f32 v75, v82, v83
	v_lshl_add_u64 v[76:77], v[72:73], 0, v[138:139]
	v_cvt_pk_bf16_f32 v72, v84, v85
	v_cvt_pk_bf16_f32 v73, v86, v87
	v_cvt_pk_bf16_f32 v71, v66, v67
	v_cvt_pk_bf16_f32 v60, v60, v61
	v_cvt_pk_bf16_f32 v61, v62, v63
	v_cvt_pk_bf16_f32 v62, v56, v57
	v_cvt_pk_bf16_f32 v63, v58, v59
	v_cvt_pk_bf16_f32 v40, v52, v53
	v_cvt_pk_bf16_f32 v41, v54, v55
	v_cvt_pk_bf16_f32 v42, v48, v49
	v_cvt_pk_bf16_f32 v43, v50, v51
	v_cvt_pk_bf16_f32 v24, v36, v37
	v_cvt_pk_bf16_f32 v25, v38, v39
	v_cvt_pk_bf16_f32 v26, v32, v33
	v_cvt_pk_bf16_f32 v27, v34, v35
	global_store_dwordx4 v[28:29], v[12:15], off offset:256
	v_cvt_pk_bf16_f32 v10, v16, v17
	v_cvt_pk_bf16_f32 v11, v18, v19
	v_lshl_add_u64 v[12:13], v[8:9], 0, v[138:139]
	v_cvt_pk_bf16_f32 v8, v20, v21
	v_cvt_pk_bf16_f32 v9, v22, v23
	v_cvt_pk_bf16_f32 v4, v4, v5
	v_cvt_pk_bf16_f32 v5, v6, v7
	v_cvt_pk_bf16_f32 v6, v0, v1
	v_cvt_pk_bf16_f32 v7, v2, v3
	s_and_b64 vcc, exec, s[6:7]
	s_mov_b32 s31, s8
	s_mov_b32 s33, s10
	s_mov_b64 s[18:19], s[14:15]
	s_mov_b64 s[16:17], s[12:13]
	global_store_dwordx4 v[142:143], v[124:127], off
	global_store_dwordx4 v[108:109], v[104:107], off
	global_store_dwordx4 v[92:93], v[88:91], off
	global_store_dwordx4 v[76:77], v[72:75], off
	global_store_dwordx4 v[76:77], v[68:71], off offset:256
	global_store_dwordx4 v[64:65], v[60:63], off
	global_store_dwordx4 v[44:45], v[40:43], off
	global_store_dwordx4 v[28:29], v[24:27], off
	global_store_dwordx4 v[12:13], v[8:11], off
	global_store_dwordx4 v[12:13], v[4:7], off offset:256
	s_cbranch_vccz .LBB0_228
	s_waitcnt vmcnt(0)
	s_cmpk_gt_u32 s2, 0xff
	s_cbranch_scc1 .LBB0_235
	s_barrier

; #define PG8_STAGE(bufoff, gbase) do { _Pragma("unroll") for (int _i = 0; _i < 2; ++_i) \
;         __builtin_amdgcn_global_load_lds((const unsigned*)((const char*)(gbase) + voff[_i]), (LAS unsigned*)(lds + (bufoff) + ldsw + _i * 8192), 16, 0, 0); } while (0)
; #define PG8_LDA(dst, b, h) do { _Pragma("unroll") for (int m = 0; m < 4; ++m) _Pragma("unroll") for (int k = 0; k < 2; ++k) dst[m][k] = *(const LAS bf16x8*)(lds + PG8_SA(b, h) + aoff + m * 2048 + k * 1024); } while (0)
; #define PG8_LDB(dst, b, h) do { _Pragma("unroll") for (int n = 0; n < 2; ++n) _Pragma("unroll") for (int k = 0; k < 2; ++k) dst[n][k] = *(const LAS bf16x8*)(lds + PG8_SB(b, h) + boff + n * 2048 + k * 1024); } while (0)
; template <class Epi>
; DI void gemm_phase(LAS unsigned char* lds, const Gemm g, const StaticOrder& S, const Epi& E) {
;     ...
;         for (int t = 0; t < nt; t += 2) {
;             const bool last = (t == nt - 2);
;             const char* a1 = cA + (size_t)(t + 1) * kstep;
;             const char* a2 = last ? nA : cA + (size_t)(t + 2) * kstep; const char* b2 = last ? nB : cB + (size_t)(t + 2) * kstep;
;             const char* a3 = a2 + kstep; const char* b3 = b2 + kstep;
;             PG8_LDB(B0, 0, 0); PG8_SCHED; PG8_LDA(At, 0, 0); PG8_STAGE(PG8_SA(1, 1), a1 + hstep);
;             PG8_WAIT_L(8); PG8_BAR; PG8_WAIT_L(0); PG8_MMA(0, 0, At, B0); PG8_BAR; PG8_SCHED;
;             PG8_LDB(B1, 0, 1); PG8_STAGE(PG8_SB(0, 0), b2);
;             PG8_BAR; PG8_WAIT_L(0); PG8_MMA(0, 1, At, B1); PG8_BAR;
;             PG8_LDA(At, 0, 1); PG8_STAGE(PG8_SA(0, 0), a2);
;             PG8_BAR; PG8_WAIT_L(0); PG8_MMA(1, 0, At, B0); PG8_BAR; PG8_SCHED;
;             PG8_STAGE(PG8_SB(0, 1), b2 + hstep);
;             PG8_WAIT_V(6); PG8_BAR; PG8_MMA(1, 1, At, B1); PG8_BAR;
;             PG8_LDB(B0, 1, 0); PG8_SCHED; PG8_LDA(At, 1, 0); PG8_STAGE(PG8_SA(0, 1), a2 + hstep);
;             PG8_WAIT_L(8); PG8_BAR; PG8_WAIT_L(0); PG8_MMA(0, 0, At, B0); PG8_BAR; PG8_SCHED;
;             PG8_LDB(B1, 1, 1); PG8_STAGE(PG8_SB(1, 0), b3);
;             PG8_BAR; PG8_WAIT_L(0); PG8_MMA(0, 1, At, B1); PG8_BAR;
;             PG8_LDA(At, 1, 1); PG8_STAGE(PG8_SA(1, 0), a3);
;             PG8_BAR; PG8_WAIT_L(0); PG8_MMA(1, 0, At, B0); PG8_BAR; PG8_SCHED;
;             PG8_STAGE(PG8_SB(1, 1), b3 + hstep);
;             PG8_WAIT_V(6); PG8_BAR; PG8_MMA(1, 1, At, B1); PG8_BAR;
.LBB0_320:
	s_add_u32 s26, s24, 0x100
	s_addc_u32 s27, s25, 0
	s_add_i32 s47, 0, 0x10000
	ds_read_b128 v[128:131], v226
	ds_read_b128 v[132:135], v226 offset:1024
	ds_read_b128 v[136:139], v226 offset:2048
	ds_read_b128 v[140:143], v226 offset:3072
	s_cmp_eq_u32 s46, 28
	s_cselect_b32 s31, s4, s27
	s_cselect_b32 s30, s5, s26
	s_cselect_b32 s29, s9, s45
	s_cselect_b32 s28, s11, s33
	v_lshl_add_u64 v[214:215], s[24:25], 0, v[190:191]
	s_add_i32 m0, s38, 0xc000
	ds_read_b128 v[144:147], v228
	ds_read_b128 v[148:151], v228 offset:1024
	ds_read_b128 v[152:155], v228 offset:2048
	ds_read_b128 v[194:197], v228 offset:3072
	ds_read_b128 v[198:201], v228 offset:4096
	ds_read_b128 v[202:205], v228 offset:5120
	ds_read_b128 v[206:209], v228 offset:6144
	ds_read_b128 v[210:213], v228 offset:7168
	global_load_lds_dwordx4 v[214:215], off
	v_lshl_add_u64 v[214:215], s[24:25], 0, v[192:193]
	s_add_i32 m0, s38, 0xe000
	s_nop 0
	global_load_lds_dwordx4 v[214:215], off
	s_waitcnt lgkmcnt(8)
	s_setprio 1
	s_barrier
	s_waitcnt lgkmcnt(0)
	v_mfma_f32_16x16x32_bf16 v[124:127], v[128:131], v[144:147], v[124:127]
	v_mfma_f32_16x16x32_bf16 v[120:123], v[136:139], v[144:147], v[120:123]
	v_mfma_f32_16x16x32_bf16 v[116:119], v[128:131], v[152:155], v[116:119]
	v_mfma_f32_16x16x32_bf16 v[112:115], v[136:139], v[152:155], v[112:115]
	v_mfma_f32_16x16x32_bf16 v[108:111], v[128:131], v[198:201], v[108:111]
	v_mfma_f32_16x16x32_bf16 v[104:107], v[136:139], v[198:201], v[104:107]
	v_mfma_f32_16x16x32_bf16 v[100:103], v[128:131], v[206:209], v[100:103]
	v_mfma_f32_16x16x32_bf16 v[96:99], v[136:139], v[206:209], v[96:99]
	v_mfma_f32_16x16x32_bf16 v[124:127], v[132:135], v[148:151], v[124:127]
	v_mfma_f32_16x16x32_bf16 v[120:123], v[140:143], v[148:151], v[120:123]
	v_mfma_f32_16x16x32_bf16 v[116:119], v[132:135], v[194:197], v[116:119]
	v_mfma_f32_16x16x32_bf16 v[112:115], v[140:143], v[194:197], v[112:115]
	v_mfma_f32_16x16x32_bf16 v[108:111], v[132:135], v[202:205], v[108:111]
	v_mfma_f32_16x16x32_bf16 v[104:107], v[140:143], v[202:205], v[104:107]
	v_mfma_f32_16x16x32_bf16 v[100:103], v[132:135], v[210:213], v[100:103]
	s_setprio 0
	v_mfma_f32_16x16x32_bf16 v[96:99], v[140:143], v[210:213], v[96:99]
	s_barrier
	s_add_i32 s48, 0, 0x14000
	s_add_i32 s24, s47, s37
	s_mov_b32 m0, s24
	ds_read_b128 v[214:217], v226 offset:16384
	ds_read_b128 v[230:233], v226 offset:17408
	ds_read_b128 v[234:237], v226 offset:18432
	ds_read_b128 v[238:241], v226 offset:19456
	global_load_lds_dwordx4 v188, s[28:29]
	s_add_i32 m0, s24, 0x2000
	s_nop 0
	global_load_lds_dwordx4 v186, s[28:29]
	s_waitcnt lgkmcnt(0)
	s_setprio 1
	s_barrier
	v_mfma_f32_16x16x32_bf16 v[60:63], v[214:217], v[144:147], v[60:63]
	v_mfma_f32_16x16x32_bf16 v[56:59], v[234:237], v[144:147], v[56:59]
	v_mfma_f32_16x16x32_bf16 v[52:55], v[214:217], v[152:155], v[52:55]
	v_mfma_f32_16x16x32_bf16 v[48:51], v[234:237], v[152:155], v[48:51]
	v_mfma_f32_16x16x32_bf16 v[44:47], v[214:217], v[198:201], v[44:47]
	v_mfma_f32_16x16x32_bf16 v[40:43], v[234:237], v[198:201], v[40:43]
	v_mfma_f32_16x16x32_bf16 v[36:39], v[214:217], v[206:209], v[36:39]
	v_mfma_f32_16x16x32_bf16 v[32:35], v[234:237], v[206:209], v[32:35]
	v_mfma_f32_16x16x32_bf16 v[60:63], v[230:233], v[148:151], v[60:63]
	s_mov_b32 m0, s38
	v_mfma_f32_16x16x32_bf16 v[56:59], v[238:241], v[148:151], v[56:59]
	v_lshl_add_u64 v[242:243], s[30:31], 0, v[188:189]
	v_mfma_f32_16x16x32_bf16 v[52:55], v[230:233], v[194:197], v[52:55]
	v_mfma_f32_16x16x32_bf16 v[48:51], v[238:241], v[194:197], v[48:51]
	v_mfma_f32_16x16x32_bf16 v[44:47], v[230:233], v[202:205], v[44:47]
	v_mfma_f32_16x16x32_bf16 v[40:43], v[238:241], v[202:205], v[40:43]
	v_mfma_f32_16x16x32_bf16 v[36:39], v[230:233], v[210:213], v[36:39]
	s_setprio 0
	v_mfma_f32_16x16x32_bf16 v[32:35], v[238:241], v[210:213], v[32:35]
	s_barrier
	ds_read_b128 v[144:147], v228 offset:16384
	ds_read_b128 v[148:151], v228 offset:17408
	ds_read_b128 v[152:155], v228 offset:18432
	ds_read_b128 v[194:197], v228 offset:19456
	ds_read_b128 v[198:201], v228 offset:20480
	ds_read_b128 v[202:205], v228 offset:21504
	ds_read_b128 v[206:209], v228 offset:22528
	ds_read_b128 v[210:213], v228 offset:23552
	global_load_lds_dwordx4 v[242:243], off
	s_mov_b64 s[100:101], s[30:31]
	s_mov_b32 m0, s39
	s_nop 0
	global_load_lds_dwordx4 v186, s[30:31]
	s_waitcnt lgkmcnt(0)
	s_setprio 1
	s_barrier
	v_mfma_f32_16x16x32_bf16 v[92:95], v[128:131], v[144:147], v[92:95]
	v_mfma_f32_16x16x32_bf16 v[88:91], v[136:139], v[144:147], v[88:91]
	v_mfma_f32_16x16x32_bf16 v[84:87], v[128:131], v[152:155], v[84:87]
	v_mfma_f32_16x16x32_bf16 v[80:83], v[136:139], v[152:155], v[80:83]
	v_mfma_f32_16x16x32_bf16 v[76:79], v[128:131], v[198:201], v[76:79]
	v_mfma_f32_16x16x32_bf16 v[72:75], v[136:139], v[198:201], v[72:75]
	v_mfma_f32_16x16x32_bf16 v[68:71], v[128:131], v[206:209], v[68:71]
	v_mfma_f32_16x16x32_bf16 v[64:67], v[136:139], v[206:209], v[64:67]
	v_mfma_f32_16x16x32_bf16 v[92:95], v[132:135], v[148:151], v[92:95]
	v_mfma_f32_16x16x32_bf16 v[88:91], v[140:143], v[148:151], v[88:91]
	v_mfma_f32_16x16x32_bf16 v[84:87], v[132:135], v[194:197], v[84:87]
	v_mfma_f32_16x16x32_bf16 v[80:83], v[140:143], v[194:197], v[80:83]
	v_mfma_f32_16x16x32_bf16 v[76:79], v[132:135], v[202:205], v[76:79]
	v_mfma_f32_16x16x32_bf16 v[72:75], v[140:143], v[202:205], v[72:75]
	v_mfma_f32_16x16x32_bf16 v[68:71], v[132:135], v[210:213], v[68:71]
	s_setprio 0
	v_mfma_f32_16x16x32_bf16 v[64:67], v[140:143], v[210:213], v[64:67]
	s_barrier
	s_add_u32 s24, s28, 0x80000
	s_addc_u32 s25, s29, 0
	s_add_i32 s47, s48, s37
	s_mov_b32 m0, s47
	s_nop 0
	global_load_lds_dwordx4 v188, s[24:25]
	s_add_i32 m0, s47, 0x2000
	s_nop 0
	global_load_lds_dwordx4 v186, s[24:25]
	s_waitcnt vmcnt(6)
	s_setprio 1
	s_barrier
; #define PG8_STAGE(bufoff, gbase) do { _Pragma("unroll") for (int _i = 0; _i < 2; ++_i) \
;         __builtin_amdgcn_global_load_lds((const unsigned*)((const char*)(gbase) + voff[_i]), (LAS unsigned*)(lds + (bufoff) + ldsw + _i * 8192), 16, 0, 0); } while (0)
; #define PG8_LDA(dst, b, h) do { _Pragma("unroll") for (int m = 0; m < 4; ++m) _Pragma("unroll") for (int k = 0; k < 2; ++k) dst[m][k] = *(const LAS bf16x8*)(lds + PG8_SA(b, h) + aoff + m * 2048 + k * 1024); } while (0)
; #define PG8_LDB(dst, b, h) do { _Pragma("unroll") for (int n = 0; n < 2; ++n) _Pragma("unroll") for (int k = 0; k < 2; ++k) dst[n][k] = *(const LAS bf16x8*)(lds + PG8_SB(b, h) + boff + n * 2048 + k * 1024); } while (0)
; template <class Epi>
; DI void gemm_phase(LAS unsigned char* lds, const Gemm g, const StaticOrder& S, const Epi& E) {
;     ...
;         for (int t = 0; t < nt; t += 2) {
;             const bool last = (t == nt - 2);
;             const char* a1 = cA + (size_t)(t + 1) * kstep;
;             const char* a2 = last ? nA : cA + (size_t)(t + 2) * kstep; const char* b2 = last ? nB : cB + (size_t)(t + 2) * kstep;
;             const char* a3 = a2 + kstep; const char* b3 = b2 + kstep;
;             PG8_LDB(B0, 0, 0); PG8_SCHED; PG8_LDA(At, 0, 0); PG8_STAGE(PG8_SA(1, 1), a1 + hstep);
;             PG8_WAIT_L(8); PG8_BAR; PG8_WAIT_L(0); PG8_MMA(0, 0, At, B0); PG8_BAR; PG8_SCHED;
;             PG8_LDB(B1, 0, 1); PG8_STAGE(PG8_SB(0, 0), b2);
;             PG8_BAR; PG8_WAIT_L(0); PG8_MMA(0, 1, At, B1); PG8_BAR;
;             PG8_LDA(At, 0, 1); PG8_STAGE(PG8_SA(0, 0), a2);
;             PG8_BAR; PG8_WAIT_L(0); PG8_MMA(1, 0, At, B0); PG8_BAR; PG8_SCHED;
;             PG8_STAGE(PG8_SB(0, 1), b2 + hstep);
;             PG8_WAIT_V(6); PG8_BAR; PG8_MMA(1, 1, At, B1); PG8_BAR;
;             PG8_LDB(B0, 1, 0); PG8_SCHED; PG8_LDA(At, 1, 0); PG8_STAGE(PG8_SA(0, 1), a2 + hstep);
;             PG8_WAIT_L(8); PG8_BAR; PG8_WAIT_L(0); PG8_MMA(0, 0, At, B0); PG8_BAR; PG8_SCHED;
;             PG8_LDB(B1, 1, 1); PG8_STAGE(PG8_SB(1, 0), b3);
;             PG8_BAR; PG8_WAIT_L(0); PG8_MMA(0, 1, At, B1); PG8_BAR;
;             PG8_LDA(At, 1, 1); PG8_STAGE(PG8_SA(1, 0), a3);
;             PG8_BAR; PG8_WAIT_L(0); PG8_MMA(1, 0, At, B0); PG8_BAR; PG8_SCHED;
;             PG8_STAGE(PG8_SB(1, 1), b3 + hstep);
;             PG8_WAIT_V(6); PG8_BAR; PG8_MMA(1, 1, At, B1); PG8_BAR;
	v_mfma_f32_16x16x32_bf16 v[28:31], v[214:217], v[144:147], v[28:31]
	v_mfma_f32_16x16x32_bf16 v[24:27], v[234:237], v[144:147], v[24:27]
	v_mfma_f32_16x16x32_bf16 v[20:23], v[214:217], v[152:155], v[20:23]
	v_mfma_f32_16x16x32_bf16 v[16:19], v[234:237], v[152:155], v[16:19]
	v_mfma_f32_16x16x32_bf16 v[12:15], v[214:217], v[198:201], v[12:15]
	v_mfma_f32_16x16x32_bf16 v[8:11], v[234:237], v[198:201], v[8:11]
	v_mfma_f32_16x16x32_bf16 v[4:7], v[214:217], v[206:209], v[4:7]
	v_mfma_f32_16x16x32_bf16 v[0:3], v[234:237], v[206:209], v[0:3]
	v_mfma_f32_16x16x32_bf16 v[28:31], v[230:233], v[148:151], v[28:31]
	s_add_i32 s47, 0, 0x18000
	v_mfma_f32_16x16x32_bf16 v[24:27], v[238:241], v[148:151], v[24:27]
	v_mfma_f32_16x16x32_bf16 v[20:23], v[230:233], v[194:197], v[20:23]
	v_mfma_f32_16x16x32_bf16 v[16:19], v[238:241], v[194:197], v[16:19]
	v_mfma_f32_16x16x32_bf16 v[12:15], v[230:233], v[202:205], v[12:15]
	v_mfma_f32_16x16x32_bf16 v[8:11], v[238:241], v[202:205], v[8:11]
	v_mfma_f32_16x16x32_bf16 v[4:7], v[230:233], v[210:213], v[4:7]
	s_setprio 0
	v_mfma_f32_16x16x32_bf16 v[0:3], v[238:241], v[210:213], v[0:3]
	s_barrier
	ds_read_b128 v[128:131], v226 offset:32768
	ds_read_b128 v[132:135], v226 offset:33792
	ds_read_b128 v[136:139], v226 offset:34816
	ds_read_b128 v[140:143], v226 offset:35840
	s_add_u32 s24, s30, 0x80000
	s_addc_u32 s25, s31, 0
	s_mov_b32 m0, s40
	ds_read_b128 v[144:147], v228 offset:32768
	ds_read_b128 v[148:151], v228 offset:33792
	ds_read_b128 v[152:155], v228 offset:34816
	ds_read_b128 v[194:197], v228 offset:35840
	ds_read_b128 v[198:201], v228 offset:36864
	ds_read_b128 v[202:205], v228 offset:37888
	ds_read_b128 v[206:209], v228 offset:38912
	ds_read_b128 v[210:213], v228 offset:39936
	global_load_lds_dwordx4 v188, s[24:25]
	s_mov_b32 m0, s41
	s_nop 0
	global_load_lds_dwordx4 v186, s[24:25]
	s_waitcnt lgkmcnt(8)
	s_setprio 1
	s_barrier
	s_waitcnt lgkmcnt(0)
	v_mfma_f32_16x16x32_bf16 v[124:127], v[128:131], v[144:147], v[124:127]
	v_mfma_f32_16x16x32_bf16 v[120:123], v[136:139], v[144:147], v[120:123]
	v_mfma_f32_16x16x32_bf16 v[116:119], v[128:131], v[152:155], v[116:119]
	v_mfma_f32_16x16x32_bf16 v[112:115], v[136:139], v[152:155], v[112:115]
	v_mfma_f32_16x16x32_bf16 v[108:111], v[128:131], v[198:201], v[108:111]
	v_mfma_f32_16x16x32_bf16 v[104:107], v[136:139], v[198:201], v[104:107]
	v_mfma_f32_16x16x32_bf16 v[100:103], v[128:131], v[206:209], v[100:103]
	v_mfma_f32_16x16x32_bf16 v[96:99], v[136:139], v[206:209], v[96:99]
	v_mfma_f32_16x16x32_bf16 v[124:127], v[132:135], v[148:151], v[124:127]
	v_mfma_f32_16x16x32_bf16 v[120:123], v[140:143], v[148:151], v[120:123]
	v_mfma_f32_16x16x32_bf16 v[116:119], v[132:135], v[194:197], v[116:119]
	v_mfma_f32_16x16x32_bf16 v[112:115], v[140:143], v[194:197], v[112:115]
	v_mfma_f32_16x16x32_bf16 v[108:111], v[132:135], v[202:205], v[108:111]
	v_mfma_f32_16x16x32_bf16 v[104:107], v[140:143], v[202:205], v[104:107]
	v_mfma_f32_16x16x32_bf16 v[100:103], v[132:135], v[210:213], v[100:103]
	s_setprio 0
	v_mfma_f32_16x16x32_bf16 v[96:99], v[140:143], v[210:213], v[96:99]
	s_barrier
	s_add_i32 s30, 0, 0x1c000
	s_add_i32 s24, s47, s37
	s_add_i32 m0, s24, 0xffffff80
	ds_read_b128 v[214:217], v226 offset:49152
	ds_read_b128 v[230:233], v226 offset:50176
	ds_read_b128 v[234:237], v226 offset:51200
	ds_read_b128 v[238:241], v226 offset:52224
	global_load_lds_dwordx4 v188, s[28:29] offset:128
	s_add_i32 m0, s24, 0x1f80
	s_nop 0
	global_load_lds_dwordx4 v186, s[28:29] offset:128
	s_waitcnt lgkmcnt(0)
	s_setprio 1
	s_barrier
	v_mfma_f32_16x16x32_bf16 v[60:63], v[214:217], v[144:147], v[60:63]
	v_mfma_f32_16x16x32_bf16 v[56:59], v[234:237], v[144:147], v[56:59]
	v_mfma_f32_16x16x32_bf16 v[52:55], v[214:217], v[152:155], v[52:55]
	v_mfma_f32_16x16x32_bf16 v[48:51], v[234:237], v[152:155], v[48:51]
	v_mfma_f32_16x16x32_bf16 v[44:47], v[214:217], v[198:201], v[44:47]
	v_mfma_f32_16x16x32_bf16 v[40:43], v[234:237], v[198:201], v[40:43]
	v_mfma_f32_16x16x32_bf16 v[36:39], v[214:217], v[206:209], v[36:39]
	v_mfma_f32_16x16x32_bf16 v[32:35], v[234:237], v[206:209], v[32:35]
	v_mfma_f32_16x16x32_bf16 v[60:63], v[230:233], v[148:151], v[60:63]
	s_mov_b32 m0, s42
	v_mfma_f32_16x16x32_bf16 v[56:59], v[238:241], v[148:151], v[56:59]
	v_lshl_add_u64 v[218:219], v[242:243], 0, s[94:95]
	v_mfma_f32_16x16x32_bf16 v[52:55], v[230:233], v[194:197], v[52:55]
	v_mfma_f32_16x16x32_bf16 v[48:51], v[238:241], v[194:197], v[48:51]
	v_mfma_f32_16x16x32_bf16 v[44:47], v[230:233], v[202:205], v[44:47]
	v_mfma_f32_16x16x32_bf16 v[40:43], v[238:241], v[202:205], v[40:43]
	v_mfma_f32_16x16x32_bf16 v[36:39], v[230:233], v[210:213], v[36:39]
	s_setprio 0
	v_mfma_f32_16x16x32_bf16 v[32:35], v[238:241], v[210:213], v[32:35]
	s_barrier
	ds_read_b128 v[144:147], v228 offset:49152
	ds_read_b128 v[148:151], v228 offset:50176
	ds_read_b128 v[152:155], v228 offset:51200
	ds_read_b128 v[194:197], v228 offset:52224
	ds_read_b128 v[198:201], v228 offset:53248
	ds_read_b128 v[202:205], v228 offset:54272
	ds_read_b128 v[206:209], v228 offset:55296
	ds_read_b128 v[210:213], v228 offset:56320
	global_load_lds_dwordx4 v[218:219], off
	s_add_i32 m0, s43, 0xffffff80
	s_nop 0
	global_load_lds_dwordx4 v186, s[100:101] offset:128
	s_waitcnt lgkmcnt(0)
	s_setprio 1
	s_barrier
; template <class Epi>
; DI void gemm_phase(LAS unsigned char* lds, const Gemm g, const StaticOrder& S, const Epi& E) {
;     ...
;         for (int t = 0; t < nt; t += 2) {
;             const bool last = (t == nt - 2);
;             const char* a1 = cA + (size_t)(t + 1) * kstep;
;             const char* a2 = last ? nA : cA + (size_t)(t + 2) * kstep; const char* b2 = last ? nB : cB + (size_t)(t + 2) * kstep;
;             const char* a3 = a2 + kstep; const char* b3 = b2 + kstep;
;             PG8_LDB(B0, 0, 0); PG8_SCHED; PG8_LDA(At, 0, 0); PG8_STAGE(PG8_SA(1, 1), a1 + hstep);
;             PG8_WAIT_L(8); PG8_BAR; PG8_WAIT_L(0); PG8_MMA(0, 0, At, B0); PG8_BAR; PG8_SCHED;
;             PG8_LDB(B1, 0, 1); PG8_STAGE(PG8_SB(0, 0), b2);
;             PG8_BAR; PG8_WAIT_L(0); PG8_MMA(0, 1, At, B1); PG8_BAR;
;             PG8_LDA(At, 0, 1); PG8_STAGE(PG8_SA(0, 0), a2);
;             PG8_BAR; PG8_WAIT_L(0); PG8_MMA(1, 0, At, B0); PG8_BAR; PG8_SCHED;
;             PG8_STAGE(PG8_SB(0, 1), b2 + hstep);
;             PG8_WAIT_V(6); PG8_BAR; PG8_MMA(1, 1, At, B1); PG8_BAR;
;             PG8_LDB(B0, 1, 0); PG8_SCHED; PG8_LDA(At, 1, 0); PG8_STAGE(PG8_SA(0, 1), a2 + hstep);
;             PG8_WAIT_L(8); PG8_BAR; PG8_WAIT_L(0); PG8_MMA(0, 0, At, B0); PG8_BAR; PG8_SCHED;
;             PG8_LDB(B1, 1, 1); PG8_STAGE(PG8_SB(1, 0), b3);
;             PG8_BAR; PG8_WAIT_L(0); PG8_MMA(0, 1, At, B1); PG8_BAR;
;             PG8_LDA(At, 1, 1); PG8_STAGE(PG8_SA(1, 0), a3);
;             PG8_BAR; PG8_WAIT_L(0); PG8_MMA(1, 0, At, B0); PG8_BAR; PG8_SCHED;
;             PG8_STAGE(PG8_SB(1, 1), b3 + hstep);
;             PG8_WAIT_V(6); PG8_BAR; PG8_MMA(1, 1, At, B1); PG8_BAR;
;     template <bool LN, int BJ, int LO, int HI> DI void batch(const f32x4 (&acc)[2][2][4][2], unsigned row0, unsigned col0, const f32x4 (&gv)[2], const f32x4 (&bv)[2]) const {
;         f32x4 r[HI - LO]; float mean[(HI - LO) / 2], rstd[(HI - LO) / 2];
; #pragma unroll
;         for (int i = LO; i < HI; ++i) { const int ai = i >> 3, m = (i >> 1) & 3, n = i & 1; const unsigned row = row0 + ai * HALF + m * 16;
;             if (n == 0) { mean[(i - LO) >> 1] = 0.f; rstd[(i - LO) >> 1] = 1.f;
;                 if (LN) { const float2 st = *(const float2*)(stats + row * 2u); mean[(i - LO) >> 1] = st.x; rstd[(i - LO) >> 1] = st.y; } }
;             r[i - LO] = *(const f32x4*)(src + (row * (unsigned)DM + col0 + BJ * HALF + n * 16)); }
	v_mfma_f32_16x16x32_bf16 v[92:95], v[128:131], v[144:147], v[92:95]
	v_mfma_f32_16x16x32_bf16 v[88:91], v[136:139], v[144:147], v[88:91]
	v_mfma_f32_16x16x32_bf16 v[84:87], v[128:131], v[152:155], v[84:87]
	v_mfma_f32_16x16x32_bf16 v[80:83], v[136:139], v[152:155], v[80:83]
	v_mfma_f32_16x16x32_bf16 v[76:79], v[128:131], v[198:201], v[76:79]
	v_mfma_f32_16x16x32_bf16 v[72:75], v[136:139], v[198:201], v[72:75]
	v_mfma_f32_16x16x32_bf16 v[68:71], v[128:131], v[206:209], v[68:71]
	v_mfma_f32_16x16x32_bf16 v[64:67], v[136:139], v[206:209], v[64:67]
	v_mfma_f32_16x16x32_bf16 v[92:95], v[132:135], v[148:151], v[92:95]
	v_mfma_f32_16x16x32_bf16 v[88:91], v[140:143], v[148:151], v[88:91]
	v_mfma_f32_16x16x32_bf16 v[84:87], v[132:135], v[194:197], v[84:87]
	v_mfma_f32_16x16x32_bf16 v[80:83], v[140:143], v[194:197], v[80:83]
	v_mfma_f32_16x16x32_bf16 v[76:79], v[132:135], v[202:205], v[76:79]
	v_mfma_f32_16x16x32_bf16 v[72:75], v[140:143], v[202:205], v[72:75]
	v_mfma_f32_16x16x32_bf16 v[68:71], v[132:135], v[210:213], v[68:71]
	s_setprio 0
	v_mfma_f32_16x16x32_bf16 v[64:67], v[140:143], v[210:213], v[64:67]
	s_barrier
	s_add_u32 s24, s28, 0x80080
	s_addc_u32 s25, s29, 0
	s_add_i32 s28, s30, s37
	s_mov_b32 m0, s28
	s_nop 0
	global_load_lds_dwordx4 v188, s[24:25]
	s_add_i32 m0, s28, 0x2000
	s_nop 0
	global_load_lds_dwordx4 v186, s[24:25]
	s_waitcnt vmcnt(6)
	s_setprio 1
	s_barrier
	v_mfma_f32_16x16x32_bf16 v[28:31], v[214:217], v[144:147], v[28:31]
	v_mfma_f32_16x16x32_bf16 v[24:27], v[234:237], v[144:147], v[24:27]
	v_mfma_f32_16x16x32_bf16 v[20:23], v[214:217], v[152:155], v[20:23]
	v_mfma_f32_16x16x32_bf16 v[16:19], v[234:237], v[152:155], v[16:19]
	v_mfma_f32_16x16x32_bf16 v[12:15], v[214:217], v[198:201], v[12:15]
	v_mfma_f32_16x16x32_bf16 v[8:11], v[234:237], v[198:201], v[8:11]
	v_mfma_f32_16x16x32_bf16 v[4:7], v[214:217], v[206:209], v[4:7]
	v_mfma_f32_16x16x32_bf16 v[0:3], v[234:237], v[206:209], v[0:3]
	v_mfma_f32_16x16x32_bf16 v[28:31], v[230:233], v[148:151], v[28:31]
	s_add_i32 s46, s46, 2
	v_mfma_f32_16x16x32_bf16 v[24:27], v[238:241], v[148:151], v[24:27]
	s_add_u32 s33, s33, 0x100
	v_mfma_f32_16x16x32_bf16 v[20:23], v[230:233], v[194:197], v[20:23]
	s_addc_u32 s45, s45, 0
	v_mfma_f32_16x16x32_bf16 v[16:19], v[238:241], v[194:197], v[16:19]
	s_cmp_gt_u32 s46, 29
	v_mfma_f32_16x16x32_bf16 v[12:15], v[230:233], v[202:205], v[12:15]
	s_mov_b64 s[24:25], s[26:27]
	v_mfma_f32_16x16x32_bf16 v[8:11], v[238:241], v[202:205], v[8:11]
	v_mfma_f32_16x16x32_bf16 v[4:7], v[230:233], v[210:213], v[4:7]
	s_setprio 0
	v_mfma_f32_16x16x32_bf16 v[0:3], v[238:241], v[210:213], v[0:3]
	s_barrier
	s_cbranch_scc0 .LBB0_320
	v_lshl_add_u32 v206, s3, 8, v225
	v_lshl_or_b32 v158, s2, 8, v227
	v_lshlrev_b32_e32 v232, 11, v206
	s_andn2_b64 vcc, exec, s[14:15]
	v_or_b32_e32 v231, 16, v158
	v_add_u32_e32 v194, v232, v158
	v_or_b32_e32 v230, 0x80, v158
	v_or_b32_e32 v229, 0x90, v158
	s_cbranch_vccnz .LBB0_323
	v_lshlrev_b64 v[132:133], 2, v[158:159]
	v_lshl_add_u64 v[140:141], s[16:17], 0, v[132:133]
	global_load_dwordx4 v[128:131], v[140:141], off
	v_lshl_add_u64 v[142:143], s[18:19], 0, v[132:133]
	v_readlane_b32 s2, v253, 8
	v_mov_b32_e32 v195, v159
	v_lshlrev_b32_e32 v136, 1, v206
	v_mov_b32_e32 v137, v159
	v_readlane_b32 s3, v253, 9
	v_lshlrev_b64 v[212:213], 2, v[194:195]
	v_add_u32_e32 v146, v232, v231
	v_lshl_add_u64 v[144:145], v[136:137], 2, s[2:3]
	v_lshl_add_u64 v[136:137], s[88:89], 0, v[212:213]
	v_mov_b32_e32 v147, v159
	v_lshl_add_u64 v[146:147], v[146:147], 2, s[88:89]
	v_or_b32_e32 v195, 16, v206
	v_mov_b32_e32 v201, v159
	v_mov_b32_e32 v209, v159
	v_lshl_add_u64 v[212:213], s[90:91], 0, v[212:213]
	s_waitcnt vmcnt(0)
	v_pk_mul_f32 v[152:153], v[130:131], s[78:79] op_sel_hi:[1,0]
	v_pk_mul_f32 v[154:155], v[128:129], s[78:79] op_sel_hi:[1,0]
	global_load_dwordx4 v[132:135], v[142:143], off
	global_load_dwordx4 v[128:131], v[140:141], off offset:64
	global_load_dwordx2 v[204:205], v[144:145], off
	global_load_dwordx4 v[196:199], v[146:147], off
	v_lshlrev_b32_e32 v146, 1, v195
	global_load_dwordx4 v[136:139], v[136:137], off
	v_lshlrev_b32_e32 v195, 11, v195
	v_mov_b32_e32 v147, v159
	v_add_u32_e32 v200, v195, v158
	v_lshl_add_u64 v[146:147], v[146:147], 2, s[2:3]
	v_lshl_add_u64 v[200:201], v[200:201], 2, s[88:89]
	global_load_dwordx2 v[214:215], v[146:147], off
	v_add_u32_e32 v208, v195, v231
	global_load_dwordx4 v[200:203], v[200:201], off
	v_lshl_add_u64 v[208:209], v[208:209], 2, s[88:89]
	global_load_dwordx4 v[208:211], v[208:209], off
	s_waitcnt vmcnt(0)
	v_pk_mul_f32 v[148:149], v[130:131], s[78:79] op_sel_hi:[1,0]
	v_pk_mul_f32 v[150:151], v[128:129], s[78:79] op_sel_hi:[1,0]
	global_load_dwordx4 v[128:131], v[142:143], off offset:64
	v_sub_f32_e32 v137, v137, v204
	v_sub_f32_e32 v136, v136, v204
	v_sub_f32_e32 v139, v139, v204
	v_sub_f32_e32 v138, v138, v204
	v_pk_mul_f32 v[138:139], v[204:205], v[138:139] op_sel:[1,0]
	v_pk_mul_f32 v[136:137], v[204:205], v[136:137] op_sel:[1,0]
	v_pk_fma_f32 v[138:139], v[152:153], v[138:139], v[126:127]
	v_pk_fma_f32 v[136:137], v[154:155], v[136:137], v[124:125]
	v_pk_fma_f32 v[138:139], v[134:135], s[78:79], v[138:139] op_sel_hi:[1,0,1]
	v_pk_fma_f32 v[136:137], v[132:133], s[78:79], v[136:137] op_sel_hi:[1,0,1]
	global_store_dwordx4 v[212:213], v[136:139], off
	s_nop 1
	v_sub_f32_e32 v137, v197, v204
	v_sub_f32_e32 v136, v196, v204
	v_sub_f32_e32 v139, v199, v204
	v_sub_f32_e32 v138, v198, v204
	v_pk_mul_f32 v[138:139], v[204:205], v[138:139] op_sel:[1,0]
	v_pk_mul_f32 v[136:137], v[204:205], v[136:137] op_sel:[1,0]
	v_pk_fma_f32 v[138:139], v[148:149], v[138:139], v[122:123]
	v_pk_fma_f32 v[136:137], v[150:151], v[136:137], v[120:121]
	v_or_b32_e32 v196, 16, v194
	v_mov_b32_e32 v197, v159
	v_lshl_add_u64 v[196:197], v[196:197], 2, s[90:91]
	s_waitcnt vmcnt(0)
;     template <bool LN, int BJ, int LO, int HI> DI void batch(const f32x4 (&acc)[2][2][4][2], unsigned row0, unsigned col0, const f32x4 (&gv)[2], const f32x4 (&bv)[2]) const {
;         f32x4 r[HI - LO]; float mean[(HI - LO) / 2], rstd[(HI - LO) / 2];
; #pragma unroll
;         for (int i = LO; i < HI; ++i) { const int ai = i >> 3, m = (i >> 1) & 3, n = i & 1; const unsigned row = row0 + ai * HALF + m * 16;
;             if (n == 0) { mean[(i - LO) >> 1] = 0.f; rstd[(i - LO) >> 1] = 1.f;
;                 if (LN) { const float2 st = *(const float2*)(stats + row * 2u); mean[(i - LO) >> 1] = st.x; rstd[(i - LO) >> 1] = st.y; } }
;             r[i - LO] = *(const f32x4*)(src + (row * (unsigned)DM + col0 + BJ * HALF + n * 16)); }
; #pragma unroll
;         for (int i = LO; i < HI; ++i) { const int ai = i >> 3, m = (i >> 1) & 3, n = i & 1; const unsigned row = row0 + ai * HALF + m * 16;
;             *(f32x4*)(Y + (row * (unsigned)DM + col0 + BJ * HALF + n * 16)) = acc[ai][BJ][m][n] + ((r[i - LO] - mean[(i - LO) >> 1]) * rstd[(i - LO) >> 1]) * gv[n] + bv[n]; }
;         __builtin_amdgcn_sched_barrier(0);
;     }
;     template <bool LN, int BJ> DI void load_gb(unsigned col0, f32x4 (&gv)[2], f32x4 (&bv)[2]) const {
; #pragma unroll
;         for (int n = 0; n < 2; ++n) {
;             if (LN) { gv[n] = *(const f32x4*)(gam + col0 + BJ * HALF + n * 16) * ALPHA; bv[n] = *(const f32x4*)(bet + col0 + BJ * HALF + n * 16) * ALPHA; }
;             else { gv[n] = (f32x4){ALPHA, ALPHA, ALPHA, ALPHA}; bv[n] = (f32x4){0.f, 0.f, 0.f, 0.f}; }
;         }
;     }
;     template <bool LN> DI void run(const f32x4 (&acc)[2][2][4][2], const Unit& u, int wr, int wc, int fr, int fq) const {
;         const unsigned row0 = u.pm * BM + wr * 64 + fr, col0 = u.pn * BM + wc * 32 + 4 * fq;
;         f32x4 gv[2], bv[2];
;         load_gb<LN, 0>(col0, gv, bv);
;         batch<LN, 0, 0, 4>(acc, row0, col0, gv, bv);
;         batch<LN, 0, 4, 8>(acc, row0, col0, gv, bv);
;         batch<LN, 0, 8, 12>(acc, row0, col0, gv, bv);
;         batch<LN, 0, 12, 16>(acc, row0, col0, gv, bv);
;         load_gb<LN, 1>(col0, gv, bv);
;         batch<LN, 1, 0, 8>(acc, row0, col0, gv, bv);
;         batch<LN, 1, 8, 16>(acc, row0, col0, gv, bv);
;     }
	v_pk_fma_f32 v[138:139], v[130:131], s[78:79], v[138:139] op_sel_hi:[1,0,1]
	v_pk_fma_f32 v[136:137], v[128:129], s[78:79], v[136:137] op_sel_hi:[1,0,1]
	global_store_dwordx4 v[196:197], v[136:139], off
	v_add_u32_e32 v196, 0x8000, v194
	v_mov_b32_e32 v197, v159
	v_sub_f32_e32 v137, v201, v214
	v_sub_f32_e32 v136, v200, v214
	v_sub_f32_e32 v139, v203, v214
	v_sub_f32_e32 v138, v202, v214
	v_pk_mul_f32 v[138:139], v[214:215], v[138:139] op_sel:[1,0]
	v_pk_mul_f32 v[136:137], v[214:215], v[136:137] op_sel:[1,0]
	v_pk_fma_f32 v[138:139], v[152:153], v[138:139], v[118:119]
	v_pk_fma_f32 v[136:137], v[154:155], v[136:137], v[116:117]
	v_pk_fma_f32 v[138:139], v[134:135], s[78:79], v[138:139] op_sel_hi:[1,0,1]
	v_pk_fma_f32 v[136:137], v[132:133], s[78:79], v[136:137] op_sel_hi:[1,0,1]
	v_lshl_add_u64 v[196:197], v[196:197], 2, s[90:91]
	global_store_dwordx4 v[196:197], v[136:139], off
	v_add_u32_e32 v196, 0x8010, v194
	v_mov_b32_e32 v197, v159
	v_sub_f32_e32 v137, v209, v214
	v_sub_f32_e32 v136, v208, v214
	v_sub_f32_e32 v139, v211, v214
	v_sub_f32_e32 v138, v210, v214
	v_pk_mul_f32 v[138:139], v[214:215], v[138:139] op_sel:[1,0]
	v_pk_mul_f32 v[136:137], v[214:215], v[136:137] op_sel:[1,0]
	v_pk_fma_f32 v[138:139], v[148:149], v[138:139], v[114:115]
	v_pk_fma_f32 v[136:137], v[150:151], v[136:137], v[112:113]
	v_pk_fma_f32 v[138:139], v[130:131], s[78:79], v[138:139] op_sel_hi:[1,0,1]
	v_pk_fma_f32 v[136:137], v[128:129], s[78:79], v[136:137] op_sel_hi:[1,0,1]
	v_lshl_add_u64 v[196:197], v[196:197], 2, s[90:91]
	global_store_dwordx4 v[196:197], v[136:139], off
	s_nop 1
	v_or_b32_e32 v138, 32, v206
	v_lshlrev_b32_e32 v136, 1, v138
	v_mov_b32_e32 v137, v159
	v_lshlrev_b32_e32 v236, 11, v138
	v_lshl_add_u64 v[200:201], v[136:137], 2, s[2:3]
	v_add_u32_e32 v136, v236, v158
	v_lshl_add_u64 v[136:137], v[136:137], 2, s[88:89]
	global_load_dwordx2 v[204:205], v[200:201], off
	v_add_u32_e32 v196, v236, v231
	global_load_dwordx4 v[136:139], v[136:137], off
	v_mov_b32_e32 v197, v159
	v_lshl_add_u64 v[196:197], v[196:197], 2, s[88:89]
	global_load_dwordx4 v[196:199], v[196:197], off
	v_or_b32_e32 v207, 48, v206
	v_lshlrev_b32_e32 v235, 11, v207
	v_lshlrev_b32_e32 v202, 1, v207
	v_mov_b32_e32 v203, v159
	v_add_u32_e32 v208, v235, v158
	v_mov_b32_e32 v209, v159
	v_lshl_add_u64 v[202:203], v[202:203], 2, s[2:3]
	v_lshl_add_u64 v[208:209], v[208:209], 2, s[88:89]
	global_load_dwordx2 v[216:217], v[202:203], off
	v_add_u32_e32 v212, v235, v231
	global_load_dwordx4 v[208:211], v[208:209], off
	v_mov_b32_e32 v213, v159
	v_lshl_add_u64 v[212:213], v[212:213], 2, s[88:89]
	global_load_dwordx4 v[212:215], v[212:213], off
	v_add_u32_e32 v218, 0x10000, v194
	v_mov_b32_e32 v219, v159
	v_lshl_add_u64 v[218:219], v[218:219], 2, s[90:91]
	s_waitcnt vmcnt(0)
	v_sub_f32_e32 v137, v137, v204
	v_sub_f32_e32 v136, v136, v204
	v_sub_f32_e32 v139, v139, v204
	v_sub_f32_e32 v138, v138, v204
	v_pk_mul_f32 v[138:139], v[204:205], v[138:139] op_sel:[1,0]
	v_pk_mul_f32 v[136:137], v[204:205], v[136:137] op_sel:[1,0]
	v_pk_fma_f32 v[138:139], v[152:153], v[138:139], v[110:111]
	v_pk_fma_f32 v[136:137], v[154:155], v[136:137], v[108:109]
	v_pk_fma_f32 v[138:139], v[134:135], s[78:79], v[138:139] op_sel_hi:[1,0,1]
	v_pk_fma_f32 v[136:137], v[132:133], s[78:79], v[136:137] op_sel_hi:[1,0,1]
	global_store_dwordx4 v[218:219], v[136:139], off
	s_nop 1
	v_sub_f32_e32 v137, v197, v204
	v_sub_f32_e32 v136, v196, v204
	v_sub_f32_e32 v139, v199, v204
	v_sub_f32_e32 v138, v198, v204
	v_pk_mul_f32 v[138:139], v[204:205], v[138:139] op_sel:[1,0]
	v_pk_mul_f32 v[136:137], v[204:205], v[136:137] op_sel:[1,0]
	v_pk_fma_f32 v[138:139], v[148:149], v[138:139], v[106:107]
	v_pk_fma_f32 v[136:137], v[150:151], v[136:137], v[104:105]
	v_add_u32_e32 v196, 0x10010, v194
	v_mov_b32_e32 v197, v159
	v_pk_fma_f32 v[138:139], v[130:131], s[78:79], v[138:139] op_sel_hi:[1,0,1]
	v_pk_fma_f32 v[136:137], v[128:129], s[78:79], v[136:137] op_sel_hi:[1,0,1]
	v_lshl_add_u64 v[196:197], v[196:197], 2, s[90:91]
	global_store_dwordx4 v[196:197], v[136:139], off
	v_add_u32_e32 v196, 0x18000, v194
	v_mov_b32_e32 v197, v159
	v_sub_f32_e32 v137, v209, v216
	v_sub_f32_e32 v136, v208, v216
	v_sub_f32_e32 v139, v211, v216
	v_sub_f32_e32 v138, v210, v216
	v_pk_mul_f32 v[138:139], v[216:217], v[138:139] op_sel:[1,0]
	v_pk_mul_f32 v[136:137], v[216:217], v[136:137] op_sel:[1,0]
	v_pk_fma_f32 v[138:139], v[152:153], v[138:139], v[102:103]
	v_pk_fma_f32 v[136:137], v[154:155], v[136:137], v[100:101]
	v_pk_fma_f32 v[138:139], v[134:135], s[78:79], v[138:139] op_sel_hi:[1,0,1]
	v_pk_fma_f32 v[136:137], v[132:133], s[78:79], v[136:137] op_sel_hi:[1,0,1]
	v_lshl_add_u64 v[196:197], v[196:197], 2, s[90:91]
	global_store_dwordx4 v[196:197], v[136:139], off
	v_add_u32_e32 v196, 0x18010, v194
	v_mov_b32_e32 v197, v159
	v_sub_f32_e32 v137, v213, v216
	v_sub_f32_e32 v136, v212, v216
	v_sub_f32_e32 v139, v215, v216
	v_sub_f32_e32 v138, v214, v216
	v_pk_mul_f32 v[138:139], v[216:217], v[138:139] op_sel:[1,0]
	v_pk_mul_f32 v[136:137], v[216:217], v[136:137] op_sel:[1,0]
	v_pk_fma_f32 v[138:139], v[148:149], v[138:139], v[98:99]
	v_pk_fma_f32 v[136:137], v[150:151], v[136:137], v[96:97]
	v_pk_fma_f32 v[138:139], v[130:131], s[78:79], v[138:139] op_sel_hi:[1,0,1]
	v_pk_fma_f32 v[136:137], v[128:129], s[78:79], v[136:137] op_sel_hi:[1,0,1]
	v_lshl_add_u64 v[196:197], v[196:197], 2, s[90:91]
	global_store_dwordx4 v[196:197], v[136:139], off
	s_nop 1
	v_add_u32_e32 v138, 0x80, v206
	v_lshlrev_b32_e32 v136, 1, v138
	v_mov_b32_e32 v137, v159
	v_lshlrev_b32_e32 v233, 11, v138
	v_lshl_add_u64 v[196:197], v[136:137], 2, s[2:3]
	v_add_u32_e32 v136, v233, v158
	v_lshl_add_u64 v[136:137], v[136:137], 2, s[88:89]
	global_load_dwordx2 v[204:205], v[196:197], off
	v_add_u32_e32 v198, v233, v231
	global_load_dwordx4 v[136:139], v[136:137], off
	v_mov_b32_e32 v199, v159
	v_add_u32_e32 v207, 0x90, v206
	v_lshl_add_u64 v[198:199], v[198:199], 2, s[88:89]
	v_lshlrev_b32_e32 v234, 11, v207
	global_load_dwordx4 v[208:211], v[198:199], off
	v_add_u32_e32 v212, v234, v158
	v_mov_b32_e32 v213, v159
	v_lshl_add_u64 v[212:213], v[212:213], 2, s[88:89]
	global_load_dwordx4 v[212:215], v[212:213], off
	v_lshlrev_b32_e32 v198, 1, v207
	v_mov_b32_e32 v199, v159
	v_lshl_add_u64 v[198:199], v[198:199], 2, s[2:3]
	global_load_dwordx2 v[238:239], v[198:199], off
	v_add_u32_e32 v216, v234, v231
	v_mov_b32_e32 v217, v159
	v_lshl_add_u64 v[216:217], v[216:217], 2, s[88:89]
	global_load_dwordx4 v[216:219], v[216:217], off
	v_add_u32_e32 v240, 0x40000, v194
	v_mov_b32_e32 v241, v159
	v_lshl_add_u64 v[240:241], v[240:241], 2, s[90:91]
	s_waitcnt vmcnt(0)
;     template <bool LN, int BJ, int LO, int HI> DI void batch(const f32x4 (&acc)[2][2][4][2], unsigned row0, unsigned col0, const f32x4 (&gv)[2], const f32x4 (&bv)[2]) const {
;         f32x4 r[HI - LO]; float mean[(HI - LO) / 2], rstd[(HI - LO) / 2];
; #pragma unroll
;         for (int i = LO; i < HI; ++i) { const int ai = i >> 3, m = (i >> 1) & 3, n = i & 1; const unsigned row = row0 + ai * HALF + m * 16;
;             if (n == 0) { mean[(i - LO) >> 1] = 0.f; rstd[(i - LO) >> 1] = 1.f;
;                 if (LN) { const float2 st = *(const float2*)(stats + row * 2u); mean[(i - LO) >> 1] = st.x; rstd[(i - LO) >> 1] = st.y; } }
;             r[i - LO] = *(const f32x4*)(src + (row * (unsigned)DM + col0 + BJ * HALF + n * 16)); }
; #pragma unroll
;         for (int i = LO; i < HI; ++i) { const int ai = i >> 3, m = (i >> 1) & 3, n = i & 1; const unsigned row = row0 + ai * HALF + m * 16;
;             *(f32x4*)(Y + (row * (unsigned)DM + col0 + BJ * HALF + n * 16)) = acc[ai][BJ][m][n] + ((r[i - LO] - mean[(i - LO) >> 1]) * rstd[(i - LO) >> 1]) * gv[n] + bv[n]; }
;         __builtin_amdgcn_sched_barrier(0);
;     }
;     template <bool LN, int BJ> DI void load_gb(unsigned col0, f32x4 (&gv)[2], f32x4 (&bv)[2]) const {
; #pragma unroll
;         for (int n = 0; n < 2; ++n) {
;             if (LN) { gv[n] = *(const f32x4*)(gam + col0 + BJ * HALF + n * 16) * ALPHA; bv[n] = *(const f32x4*)(bet + col0 + BJ * HALF + n * 16) * ALPHA; }
;             else { gv[n] = (f32x4){ALPHA, ALPHA, ALPHA, ALPHA}; bv[n] = (f32x4){0.f, 0.f, 0.f, 0.f}; }
;         }
;     }
;     template <bool LN> DI void run(const f32x4 (&acc)[2][2][4][2], const Unit& u, int wr, int wc, int fr, int fq) const {
;         const unsigned row0 = u.pm * BM + wr * 64 + fr, col0 = u.pn * BM + wc * 32 + 4 * fq;
;         f32x4 gv[2], bv[2];
;         load_gb<LN, 0>(col0, gv, bv);
;         batch<LN, 0, 0, 4>(acc, row0, col0, gv, bv);
;         batch<LN, 0, 4, 8>(acc, row0, col0, gv, bv);
;         batch<LN, 0, 8, 12>(acc, row0, col0, gv, bv);
;         batch<LN, 0, 12, 16>(acc, row0, col0, gv, bv);
;         load_gb<LN, 1>(col0, gv, bv);
;         batch<LN, 1, 0, 8>(acc, row0, col0, gv, bv);
;         batch<LN, 1, 8, 16>(acc, row0, col0, gv, bv);
;     }
	v_sub_f32_e32 v137, v137, v204
	v_sub_f32_e32 v136, v136, v204
	v_sub_f32_e32 v139, v139, v204
	v_sub_f32_e32 v138, v138, v204
	v_pk_mul_f32 v[138:139], v[204:205], v[138:139] op_sel:[1,0]
	v_pk_mul_f32 v[136:137], v[204:205], v[136:137] op_sel:[1,0]
	v_pk_fma_f32 v[138:139], v[152:153], v[138:139], v[94:95]
	v_pk_fma_f32 v[136:137], v[154:155], v[136:137], v[92:93]
	v_pk_fma_f32 v[138:139], v[134:135], s[78:79], v[138:139] op_sel_hi:[1,0,1]
	v_pk_fma_f32 v[136:137], v[132:133], s[78:79], v[136:137] op_sel_hi:[1,0,1]
	global_store_dwordx4 v[240:241], v[136:139], off
	s_nop 1
	v_sub_f32_e32 v137, v209, v204
	v_sub_f32_e32 v136, v208, v204
	v_sub_f32_e32 v139, v211, v204
	v_sub_f32_e32 v138, v210, v204
	v_pk_mul_f32 v[138:139], v[204:205], v[138:139] op_sel:[1,0]
	v_pk_mul_f32 v[136:137], v[204:205], v[136:137] op_sel:[1,0]
	v_pk_fma_f32 v[138:139], v[148:149], v[138:139], v[90:91]
	v_pk_fma_f32 v[136:137], v[150:151], v[136:137], v[88:89]
	v_add_u32_e32 v204, 0x40010, v194
	v_mov_b32_e32 v205, v159
	v_pk_fma_f32 v[138:139], v[130:131], s[78:79], v[138:139] op_sel_hi:[1,0,1]
	v_pk_fma_f32 v[136:137], v[128:129], s[78:79], v[136:137] op_sel_hi:[1,0,1]
	v_lshl_add_u64 v[204:205], v[204:205], 2, s[90:91]
	global_store_dwordx4 v[204:205], v[136:139], off
	v_add_u32_e32 v204, 0x48000, v194
	v_mov_b32_e32 v205, v159
	v_sub_f32_e32 v137, v213, v238
	v_sub_f32_e32 v136, v212, v238
	v_sub_f32_e32 v139, v215, v238
	v_sub_f32_e32 v138, v214, v238
	v_pk_mul_f32 v[138:139], v[238:239], v[138:139] op_sel:[1,0]
	v_pk_mul_f32 v[136:137], v[238:239], v[136:137] op_sel:[1,0]
	v_pk_fma_f32 v[138:139], v[152:153], v[138:139], v[86:87]
	v_pk_fma_f32 v[136:137], v[154:155], v[136:137], v[84:85]
	v_pk_fma_f32 v[138:139], v[134:135], s[78:79], v[138:139] op_sel_hi:[1,0,1]
	v_pk_fma_f32 v[136:137], v[132:133], s[78:79], v[136:137] op_sel_hi:[1,0,1]
	v_lshl_add_u64 v[204:205], v[204:205], 2, s[90:91]
	global_store_dwordx4 v[204:205], v[136:139], off
	v_add_u32_e32 v204, 0x48010, v194
	v_mov_b32_e32 v205, v159
	v_sub_f32_e32 v137, v217, v238
	v_sub_f32_e32 v136, v216, v238
	v_sub_f32_e32 v139, v219, v238
	v_sub_f32_e32 v138, v218, v238
	v_pk_mul_f32 v[138:139], v[238:239], v[138:139] op_sel:[1,0]
	v_pk_mul_f32 v[136:137], v[238:239], v[136:137] op_sel:[1,0]
	v_pk_fma_f32 v[138:139], v[148:149], v[138:139], v[82:83]
	v_pk_fma_f32 v[136:137], v[150:151], v[136:137], v[80:81]
	v_pk_fma_f32 v[138:139], v[130:131], s[78:79], v[138:139] op_sel_hi:[1,0,1]
	v_pk_fma_f32 v[136:137], v[128:129], s[78:79], v[136:137] op_sel_hi:[1,0,1]
	v_lshl_add_u64 v[204:205], v[204:205], 2, s[90:91]
	global_store_dwordx4 v[204:205], v[136:139], off
	s_nop 1
	v_add_u32_e32 v138, 0xa0, v206
	v_lshlrev_b32_e32 v136, 1, v138
	v_mov_b32_e32 v137, v159
	v_lshlrev_b32_e32 v237, 11, v138
	v_lshl_add_u64 v[204:205], v[136:137], 2, s[2:3]
	v_add_u32_e32 v136, v237, v158
	v_lshl_add_u64 v[136:137], v[136:137], 2, s[88:89]
	global_load_dwordx2 v[240:241], v[204:205], off
	v_add_u32_e32 v208, v237, v231
	global_load_dwordx4 v[136:139], v[136:137], off
	v_mov_b32_e32 v209, v159
	v_lshl_add_u64 v[208:209], v[208:209], 2, s[88:89]
	global_load_dwordx4 v[212:215], v[208:209], off
	v_add_u32_e32 v208, 0xb0, v206
	v_lshlrev_b32_e32 v206, 1, v208
	v_mov_b32_e32 v207, v159
	v_lshlrev_b32_e32 v238, 11, v208
	v_lshl_add_u64 v[210:211], v[206:207], 2, s[2:3]
	v_add_u32_e32 v206, v238, v158
	v_lshl_add_u64 v[206:207], v[206:207], 2, s[88:89]
	global_load_dwordx2 v[242:243], v[210:211], off
	v_add_u32_e32 v216, v238, v231
	global_load_dwordx4 v[206:209], v[206:207], off
	v_mov_b32_e32 v217, v159
	v_lshl_add_u64 v[216:217], v[216:217], 2, s[88:89]
	global_load_dwordx4 v[216:219], v[216:217], off
	v_add_u32_e32 v244, 0x50000, v194
	v_mov_b32_e32 v245, v159
	v_lshl_add_u64 v[244:245], v[244:245], 2, s[90:91]
	s_waitcnt vmcnt(0)
	v_sub_f32_e32 v137, v137, v240
	v_sub_f32_e32 v136, v136, v240
	v_sub_f32_e32 v139, v139, v240
	v_sub_f32_e32 v138, v138, v240
	v_pk_mul_f32 v[138:139], v[240:241], v[138:139] op_sel:[1,0]
	v_pk_mul_f32 v[136:137], v[240:241], v[136:137] op_sel:[1,0]
	v_pk_fma_f32 v[138:139], v[152:153], v[138:139], v[78:79]
	v_pk_fma_f32 v[136:137], v[154:155], v[136:137], v[76:77]
	v_pk_fma_f32 v[138:139], v[134:135], s[78:79], v[138:139] op_sel_hi:[1,0,1]
	v_pk_fma_f32 v[136:137], v[132:133], s[78:79], v[136:137] op_sel_hi:[1,0,1]
	global_store_dwordx4 v[244:245], v[136:139], off
	s_nop 1
	v_sub_f32_e32 v137, v213, v240
	v_sub_f32_e32 v136, v212, v240
	v_sub_f32_e32 v139, v215, v240
	v_sub_f32_e32 v138, v214, v240
	v_pk_mul_f32 v[138:139], v[240:241], v[138:139] op_sel:[1,0]
	v_pk_mul_f32 v[136:137], v[240:241], v[136:137] op_sel:[1,0]
	v_pk_fma_f32 v[138:139], v[148:149], v[138:139], v[74:75]
	v_pk_fma_f32 v[136:137], v[150:151], v[136:137], v[72:73]
	v_add_u32_e32 v212, 0x50010, v194
	v_mov_b32_e32 v213, v159
	v_pk_fma_f32 v[138:139], v[130:131], s[78:79], v[138:139] op_sel_hi:[1,0,1]
	v_pk_fma_f32 v[136:137], v[128:129], s[78:79], v[136:137] op_sel_hi:[1,0,1]
	v_lshl_add_u64 v[212:213], v[212:213], 2, s[90:91]
	global_store_dwordx4 v[212:213], v[136:139], off
	s_nop 1
	v_sub_f32_e32 v137, v207, v242
	v_sub_f32_e32 v136, v206, v242
	v_sub_f32_e32 v139, v209, v242
	v_sub_f32_e32 v138, v208, v242
	v_pk_mul_f32 v[136:137], v[242:243], v[136:137] op_sel:[1,0]
	v_pk_mul_f32 v[138:139], v[242:243], v[138:139] op_sel:[1,0]
	v_pk_fma_f32 v[136:137], v[154:155], v[136:137], v[68:69]
	v_pk_fma_f32 v[138:139], v[152:153], v[138:139], v[70:71]
	v_pk_fma_f32 v[132:133], v[132:133], s[78:79], v[136:137] op_sel_hi:[1,0,1]
	v_add_u32_e32 v136, 0x58000, v194
	v_mov_b32_e32 v137, v159
	v_pk_fma_f32 v[134:135], v[134:135], s[78:79], v[138:139] op_sel_hi:[1,0,1]
	v_lshl_add_u64 v[136:137], v[136:137], 2, s[90:91]
	global_store_dwordx4 v[136:137], v[132:135], off
	s_nop 1
	v_sub_f32_e32 v133, v217, v242
	v_sub_f32_e32 v132, v216, v242
	v_sub_f32_e32 v135, v219, v242
	v_sub_f32_e32 v134, v218, v242
	v_pk_mul_f32 v[132:133], v[242:243], v[132:133] op_sel:[1,0]
	v_pk_mul_f32 v[134:135], v[242:243], v[134:135] op_sel:[1,0]
	v_pk_fma_f32 v[132:133], v[150:151], v[132:133], v[64:65]
	v_pk_fma_f32 v[134:135], v[148:149], v[134:135], v[66:67]
	v_pk_fma_f32 v[128:129], v[128:129], s[78:79], v[132:133] op_sel_hi:[1,0,1]
	v_add_u32_e32 v132, 0x58010, v194
	v_mov_b32_e32 v133, v159
	v_pk_fma_f32 v[130:131], v[130:131], s[78:79], v[134:135] op_sel_hi:[1,0,1]
	v_lshl_add_u64 v[132:133], v[132:133], 2, s[90:91]
	global_store_dwordx4 v[132:133], v[128:131], off
	global_load_dwordx4 v[128:131], v[140:141], off offset:512
	v_add_u32_e32 v136, v232, v230
	v_mov_b32_e32 v137, v159
	v_lshl_add_u64 v[136:137], v[136:137], 2, s[88:89]
	s_waitcnt vmcnt(0)
;     template <bool LN, int BJ, int LO, int HI> DI void batch(const f32x4 (&acc)[2][2][4][2], unsigned row0, unsigned col0, const f32x4 (&gv)[2], const f32x4 (&bv)[2]) const {
;         f32x4 r[HI - LO]; float mean[(HI - LO) / 2], rstd[(HI - LO) / 2];
; #pragma unroll
;         for (int i = LO; i < HI; ++i) { const int ai = i >> 3, m = (i >> 1) & 3, n = i & 1; const unsigned row = row0 + ai * HALF + m * 16;
;             if (n == 0) { mean[(i - LO) >> 1] = 0.f; rstd[(i - LO) >> 1] = 1.f;
;                 if (LN) { const float2 st = *(const float2*)(stats + row * 2u); mean[(i - LO) >> 1] = st.x; rstd[(i - LO) >> 1] = st.y; } }
;             r[i - LO] = *(const f32x4*)(src + (row * (unsigned)DM + col0 + BJ * HALF + n * 16)); }
; #pragma unroll
;         for (int i = LO; i < HI; ++i) { const int ai = i >> 3, m = (i >> 1) & 3, n = i & 1; const unsigned row = row0 + ai * HALF + m * 16;
;             *(f32x4*)(Y + (row * (unsigned)DM + col0 + BJ * HALF + n * 16)) = acc[ai][BJ][m][n] + ((r[i - LO] - mean[(i - LO) >> 1]) * rstd[(i - LO) >> 1]) * gv[n] + bv[n]; }
;         __builtin_amdgcn_sched_barrier(0);
;     }
;     template <bool LN, int BJ> DI void load_gb(unsigned col0, f32x4 (&gv)[2], f32x4 (&bv)[2]) const {
; #pragma unroll
;         for (int n = 0; n < 2; ++n) {
;             if (LN) { gv[n] = *(const f32x4*)(gam + col0 + BJ * HALF + n * 16) * ALPHA; bv[n] = *(const f32x4*)(bet + col0 + BJ * HALF + n * 16) * ALPHA; }
;             else { gv[n] = (f32x4){ALPHA, ALPHA, ALPHA, ALPHA}; bv[n] = (f32x4){0.f, 0.f, 0.f, 0.f}; }
;         }
;     }
;     template <bool LN> DI void run(const f32x4 (&acc)[2][2][4][2], const Unit& u, int wr, int wc, int fr, int fq) const {
;         const unsigned row0 = u.pm * BM + wr * 64 + fr, col0 = u.pn * BM + wc * 32 + 4 * fq;
;         f32x4 gv[2], bv[2];
;         load_gb<LN, 0>(col0, gv, bv);
;         batch<LN, 0, 0, 4>(acc, row0, col0, gv, bv);
;         batch<LN, 0, 4, 8>(acc, row0, col0, gv, bv);
;         batch<LN, 0, 8, 12>(acc, row0, col0, gv, bv);
;         batch<LN, 0, 12, 16>(acc, row0, col0, gv, bv);
;         load_gb<LN, 1>(col0, gv, bv);
;         batch<LN, 1, 0, 8>(acc, row0, col0, gv, bv);
;         batch<LN, 1, 8, 16>(acc, row0, col0, gv, bv);
;     }
	v_pk_mul_f32 v[212:213], v[130:131], s[78:79] op_sel_hi:[1,0]
	v_pk_mul_f32 v[214:215], v[128:129], s[78:79] op_sel_hi:[1,0]
	global_load_dwordx4 v[132:135], v[142:143], off offset:512
	global_load_dwordx4 v[128:131], v[140:141], off offset:576
	s_waitcnt vmcnt(0)
	v_pk_mul_f32 v[206:207], v[130:131], s[78:79] op_sel_hi:[1,0]
	v_pk_mul_f32 v[208:209], v[128:129], s[78:79] op_sel_hi:[1,0]
	global_load_dwordx4 v[128:131], v[142:143], off offset:576
	global_load_dwordx2 v[220:221], v[144:145], off
	global_load_dwordx4 v[240:243], v[136:137], off
	v_add_u32_e32 v136, v232, v229
	v_mov_b32_e32 v137, v159
	v_lshl_add_u64 v[136:137], v[136:137], 2, s[88:89]
	global_load_dwordx4 v[244:247], v[136:137], off
	global_load_dwordx2 v[218:219], v[146:147], off
	v_add_u32_e32 v136, v195, v230
	v_mov_b32_e32 v137, v159
	v_lshl_add_u64 v[136:137], v[136:137], 2, s[88:89]
	global_load_dwordx4 v[248:251], v[136:137], off
	v_add_u32_e32 v136, v195, v229
	v_mov_b32_e32 v137, v159
	v_lshl_add_u64 v[136:137], v[136:137], 2, s[88:89]
	global_load_dwordx4 v[152:155], v[136:137], off
	global_load_dwordx2 v[216:217], v[200:201], off
	v_add_u32_e32 v136, v236, v230
	v_mov_b32_e32 v137, v159
	v_lshl_add_u64 v[136:137], v[136:137], 2, s[88:89]
	global_load_dwordx4 v[148:151], v[136:137], off
	v_add_u32_e32 v136, v236, v229
	v_mov_b32_e32 v137, v159
	v_lshl_add_u64 v[136:137], v[136:137], 2, s[88:89]
	global_load_dwordx4 v[144:147], v[136:137], off
	global_load_dwordx2 v[200:201], v[202:203], off
	v_add_u32_e32 v136, v235, v230
	v_mov_b32_e32 v137, v159
	v_lshl_add_u64 v[136:137], v[136:137], 2, s[88:89]
	global_load_dwordx4 v[140:143], v[136:137], off
	v_add_u32_e32 v136, v235, v229
	v_mov_b32_e32 v137, v159
	v_lshl_add_u64 v[136:137], v[136:137], 2, s[88:89]
	global_load_dwordx4 v[136:139], v[136:137], off
	v_add_u32_e32 v202, 0x80, v194
	v_mov_b32_e32 v203, v159
	v_lshl_add_u64 v[202:203], v[202:203], 2, s[90:91]
	s_waitcnt vmcnt(0)
	v_sub_f32_e32 v241, v241, v220
	v_sub_f32_e32 v240, v240, v220
	v_sub_f32_e32 v243, v243, v220
	v_sub_f32_e32 v242, v242, v220
	v_pk_mul_f32 v[242:243], v[220:221], v[242:243] op_sel:[1,0]
	v_pk_mul_f32 v[240:241], v[220:221], v[240:241] op_sel:[1,0]
	v_pk_fma_f32 v[242:243], v[212:213], v[242:243], v[62:63]
	v_pk_fma_f32 v[240:241], v[214:215], v[240:241], v[60:61]
	v_pk_fma_f32 v[242:243], v[134:135], s[78:79], v[242:243] op_sel_hi:[1,0,1]
	v_pk_fma_f32 v[240:241], v[132:133], s[78:79], v[240:241] op_sel_hi:[1,0,1]
	global_store_dwordx4 v[202:203], v[240:243], off
	v_sub_f32_e32 v203, v245, v220
	v_sub_f32_e32 v202, v244, v220
	v_sub_f32_e32 v241, v247, v220
	v_sub_f32_e32 v240, v246, v220
	v_pk_mul_f32 v[202:203], v[220:221], v[202:203] op_sel:[1,0]
	v_pk_mul_f32 v[240:241], v[220:221], v[240:241] op_sel:[1,0]
	v_pk_fma_f32 v[202:203], v[208:209], v[202:203], v[56:57]
	v_pk_fma_f32 v[220:221], v[206:207], v[240:241], v[58:59]
	v_pk_fma_f32 v[240:241], v[128:129], s[78:79], v[202:203] op_sel_hi:[1,0,1]
	v_add_u32_e32 v202, 0x90, v194
	v_mov_b32_e32 v203, v159
	v_pk_fma_f32 v[242:243], v[130:131], s[78:79], v[220:221] op_sel_hi:[1,0,1]
	v_lshl_add_u64 v[202:203], v[202:203], 2, s[90:91]
	global_store_dwordx4 v[202:203], v[240:243], off
	v_sub_f32_e32 v203, v249, v218
	v_sub_f32_e32 v202, v248, v218
	v_sub_f32_e32 v221, v251, v218
	v_sub_f32_e32 v220, v250, v218
	v_pk_mul_f32 v[202:203], v[218:219], v[202:203] op_sel:[1,0]
	v_pk_mul_f32 v[220:221], v[218:219], v[220:221] op_sel:[1,0]
	v_pk_fma_f32 v[202:203], v[214:215], v[202:203], v[52:53]
	v_pk_fma_f32 v[220:221], v[212:213], v[220:221], v[54:55]
	v_pk_fma_f32 v[240:241], v[132:133], s[78:79], v[202:203] op_sel_hi:[1,0,1]
	v_add_u32_e32 v202, 0x8080, v194
	v_mov_b32_e32 v203, v159
	v_sub_f32_e32 v153, v153, v218
	v_sub_f32_e32 v152, v152, v218
	v_sub_f32_e32 v155, v155, v218
	v_sub_f32_e32 v154, v154, v218
	v_pk_fma_f32 v[242:243], v[134:135], s[78:79], v[220:221] op_sel_hi:[1,0,1]
	v_lshl_add_u64 v[202:203], v[202:203], 2, s[90:91]
	v_pk_mul_f32 v[154:155], v[218:219], v[154:155] op_sel:[1,0]
	v_pk_mul_f32 v[152:153], v[218:219], v[152:153] op_sel:[1,0]
	global_store_dwordx4 v[202:203], v[240:243], off
	v_pk_fma_f32 v[152:153], v[208:209], v[152:153], v[48:49]
	v_pk_fma_f32 v[154:155], v[206:207], v[154:155], v[50:51]
	v_add_u32_e32 v202, 0x8090, v194
	v_mov_b32_e32 v203, v159
	v_sub_f32_e32 v149, v149, v216
	v_sub_f32_e32 v148, v148, v216
	v_sub_f32_e32 v151, v151, v216
	v_sub_f32_e32 v150, v150, v216
	v_pk_fma_f32 v[154:155], v[130:131], s[78:79], v[154:155] op_sel_hi:[1,0,1]
	v_pk_fma_f32 v[152:153], v[128:129], s[78:79], v[152:153] op_sel_hi:[1,0,1]
	v_lshl_add_u64 v[202:203], v[202:203], 2, s[90:91]
	v_pk_mul_f32 v[150:151], v[216:217], v[150:151] op_sel:[1,0]
	v_pk_mul_f32 v[148:149], v[216:217], v[148:149] op_sel:[1,0]
	global_store_dwordx4 v[202:203], v[152:155], off
	v_pk_fma_f32 v[148:149], v[214:215], v[148:149], v[44:45]
	v_pk_fma_f32 v[150:151], v[212:213], v[150:151], v[46:47]
	v_add_u32_e32 v152, 0x10080, v194
	v_mov_b32_e32 v153, v159
	v_sub_f32_e32 v145, v145, v216
	v_sub_f32_e32 v144, v144, v216
	v_sub_f32_e32 v147, v147, v216
	v_sub_f32_e32 v146, v146, v216
	v_pk_fma_f32 v[150:151], v[134:135], s[78:79], v[150:151] op_sel_hi:[1,0,1]
	v_pk_fma_f32 v[148:149], v[132:133], s[78:79], v[148:149] op_sel_hi:[1,0,1]
	v_lshl_add_u64 v[152:153], v[152:153], 2, s[90:91]
	v_pk_mul_f32 v[146:147], v[216:217], v[146:147] op_sel:[1,0]
	v_pk_mul_f32 v[144:145], v[216:217], v[144:145] op_sel:[1,0]
	global_store_dwordx4 v[152:153], v[148:151], off
	v_pk_fma_f32 v[144:145], v[208:209], v[144:145], v[40:41]
	v_pk_fma_f32 v[146:147], v[206:207], v[146:147], v[42:43]
;     template <bool LN, int BJ, int LO, int HI> DI void batch(const f32x4 (&acc)[2][2][4][2], unsigned row0, unsigned col0, const f32x4 (&gv)[2], const f32x4 (&bv)[2]) const {
;         f32x4 r[HI - LO]; float mean[(HI - LO) / 2], rstd[(HI - LO) / 2];
; #pragma unroll
;         for (int i = LO; i < HI; ++i) { const int ai = i >> 3, m = (i >> 1) & 3, n = i & 1; const unsigned row = row0 + ai * HALF + m * 16;
;             if (n == 0) { mean[(i - LO) >> 1] = 0.f; rstd[(i - LO) >> 1] = 1.f;
;                 if (LN) { const float2 st = *(const float2*)(stats + row * 2u); mean[(i - LO) >> 1] = st.x; rstd[(i - LO) >> 1] = st.y; } }
;             r[i - LO] = *(const f32x4*)(src + (row * (unsigned)DM + col0 + BJ * HALF + n * 16)); }
; #pragma unroll
;         for (int i = LO; i < HI; ++i) { const int ai = i >> 3, m = (i >> 1) & 3, n = i & 1; const unsigned row = row0 + ai * HALF + m * 16;
;             *(f32x4*)(Y + (row * (unsigned)DM + col0 + BJ * HALF + n * 16)) = acc[ai][BJ][m][n] + ((r[i - LO] - mean[(i - LO) >> 1]) * rstd[(i - LO) >> 1]) * gv[n] + bv[n]; }
;         __builtin_amdgcn_sched_barrier(0);
;     }
;     template <bool LN, int BJ> DI void load_gb(unsigned col0, f32x4 (&gv)[2], f32x4 (&bv)[2]) const {
; #pragma unroll
;         for (int n = 0; n < 2; ++n) {
;             if (LN) { gv[n] = *(const f32x4*)(gam + col0 + BJ * HALF + n * 16) * ALPHA; bv[n] = *(const f32x4*)(bet + col0 + BJ * HALF + n * 16) * ALPHA; }
;             else { gv[n] = (f32x4){ALPHA, ALPHA, ALPHA, ALPHA}; bv[n] = (f32x4){0.f, 0.f, 0.f, 0.f}; }
;         }
;     }
;     template <bool LN> DI void run(const f32x4 (&acc)[2][2][4][2], const Unit& u, int wr, int wc, int fr, int fq) const {
;         const unsigned row0 = u.pm * BM + wr * 64 + fr, col0 = u.pn * BM + wc * 32 + 4 * fq;
;         f32x4 gv[2], bv[2];
;         load_gb<LN, 0>(col0, gv, bv);
;         batch<LN, 0, 0, 4>(acc, row0, col0, gv, bv);
;         batch<LN, 0, 4, 8>(acc, row0, col0, gv, bv);
;         batch<LN, 0, 8, 12>(acc, row0, col0, gv, bv);
;         batch<LN, 0, 12, 16>(acc, row0, col0, gv, bv);
;         load_gb<LN, 1>(col0, gv, bv);
;         batch<LN, 1, 0, 8>(acc, row0, col0, gv, bv);
;         batch<LN, 1, 8, 16>(acc, row0, col0, gv, bv);
;     }
	v_add_u32_e32 v148, 0x10090, v194
	v_mov_b32_e32 v149, v159
	v_sub_f32_e32 v141, v141, v200
	v_sub_f32_e32 v140, v140, v200
	v_sub_f32_e32 v143, v143, v200
	v_sub_f32_e32 v142, v142, v200
	v_pk_fma_f32 v[146:147], v[130:131], s[78:79], v[146:147] op_sel_hi:[1,0,1]
	v_pk_fma_f32 v[144:145], v[128:129], s[78:79], v[144:145] op_sel_hi:[1,0,1]
	v_lshl_add_u64 v[148:149], v[148:149], 2, s[90:91]
	v_pk_mul_f32 v[142:143], v[200:201], v[142:143] op_sel:[1,0]
	v_pk_mul_f32 v[140:141], v[200:201], v[140:141] op_sel:[1,0]
	global_store_dwordx4 v[148:149], v[144:147], off
	v_pk_fma_f32 v[140:141], v[214:215], v[140:141], v[36:37]
	v_pk_fma_f32 v[142:143], v[212:213], v[142:143], v[38:39]
	v_add_u32_e32 v144, 0x18080, v194
	v_mov_b32_e32 v145, v159
	v_sub_f32_e32 v137, v137, v200
	v_sub_f32_e32 v136, v136, v200
	v_sub_f32_e32 v139, v139, v200
	v_sub_f32_e32 v138, v138, v200
	v_pk_fma_f32 v[142:143], v[134:135], s[78:79], v[142:143] op_sel_hi:[1,0,1]
	v_pk_fma_f32 v[140:141], v[132:133], s[78:79], v[140:141] op_sel_hi:[1,0,1]
	v_lshl_add_u64 v[144:145], v[144:145], 2, s[90:91]
	v_pk_mul_f32 v[138:139], v[200:201], v[138:139] op_sel:[1,0]
	v_pk_mul_f32 v[136:137], v[200:201], v[136:137] op_sel:[1,0]
	global_store_dwordx4 v[144:145], v[140:143], off
	v_pk_fma_f32 v[136:137], v[208:209], v[136:137], v[32:33]
	v_pk_fma_f32 v[138:139], v[206:207], v[138:139], v[34:35]
	v_add_u32_e32 v140, 0x18090, v194
	v_mov_b32_e32 v141, v159
	v_pk_fma_f32 v[138:139], v[130:131], s[78:79], v[138:139] op_sel_hi:[1,0,1]
	v_pk_fma_f32 v[136:137], v[128:129], s[78:79], v[136:137] op_sel_hi:[1,0,1]
	v_lshl_add_u64 v[140:141], v[140:141], 2, s[90:91]
	global_store_dwordx4 v[140:141], v[136:139], off
	s_nop 1
	v_add_u32_e32 v136, v233, v230
	v_mov_b32_e32 v137, v159
	v_lshl_add_u64 v[136:137], v[136:137], 2, s[88:89]
	global_load_dwordx2 v[220:221], v[196:197], off
	global_load_dwordx4 v[216:219], v[136:137], off
	v_add_u32_e32 v136, v233, v229
	v_mov_b32_e32 v137, v159
	v_lshl_add_u64 v[136:137], v[136:137], 2, s[88:89]
	global_load_dwordx4 v[240:243], v[136:137], off
	global_load_dwordx2 v[200:201], v[198:199], off
	v_add_u32_e32 v136, v234, v230
	v_mov_b32_e32 v137, v159
	v_lshl_add_u64 v[136:137], v[136:137], 2, s[88:89]
	global_load_dwordx4 v[244:247], v[136:137], off
	v_add_u32_e32 v136, v234, v229
	v_mov_b32_e32 v137, v159
	v_lshl_add_u64 v[136:137], v[136:137], 2, s[88:89]
	global_load_dwordx4 v[152:155], v[136:137], off
	global_load_dwordx2 v[198:199], v[204:205], off
	v_add_u32_e32 v136, v237, v230
	v_mov_b32_e32 v137, v159
	v_lshl_add_u64 v[136:137], v[136:137], 2, s[88:89]
	global_load_dwordx4 v[148:151], v[136:137], off
	v_add_u32_e32 v136, v237, v229
	v_mov_b32_e32 v137, v159
	v_lshl_add_u64 v[136:137], v[136:137], 2, s[88:89]
	global_load_dwordx4 v[144:147], v[136:137], off
	global_load_dwordx2 v[196:197], v[210:211], off
	v_add_u32_e32 v136, v238, v230
	v_mov_b32_e32 v137, v159
	v_lshl_add_u64 v[136:137], v[136:137], 2, s[88:89]
	global_load_dwordx4 v[140:143], v[136:137], off
	v_add_u32_e32 v136, v238, v229
	v_mov_b32_e32 v137, v159
	v_lshl_add_u64 v[136:137], v[136:137], 2, s[88:89]
	global_load_dwordx4 v[136:139], v[136:137], off
	v_add_u32_e32 v210, 0x40080, v194
	v_mov_b32_e32 v211, v159
	v_lshl_add_u64 v[210:211], v[210:211], 2, s[90:91]
	s_waitcnt vmcnt(0)
;     template <bool LN, int BJ, int LO, int HI> DI void batch(const f32x4 (&acc)[2][2][4][2], unsigned row0, unsigned col0, const f32x4 (&gv)[2], const f32x4 (&bv)[2]) const {
;         f32x4 r[HI - LO]; float mean[(HI - LO) / 2], rstd[(HI - LO) / 2];
; #pragma unroll
;         for (int i = LO; i < HI; ++i) { const int ai = i >> 3, m = (i >> 1) & 3, n = i & 1; const unsigned row = row0 + ai * HALF + m * 16;
;             if (n == 0) { mean[(i - LO) >> 1] = 0.f; rstd[(i - LO) >> 1] = 1.f;
;                 if (LN) { const float2 st = *(const float2*)(stats + row * 2u); mean[(i - LO) >> 1] = st.x; rstd[(i - LO) >> 1] = st.y; } }
;             r[i - LO] = *(const f32x4*)(src + (row * (unsigned)DM + col0 + BJ * HALF + n * 16)); }
; #pragma unroll
;         for (int i = LO; i < HI; ++i) { const int ai = i >> 3, m = (i >> 1) & 3, n = i & 1; const unsigned row = row0 + ai * HALF + m * 16;
;             *(f32x4*)(Y + (row * (unsigned)DM + col0 + BJ * HALF + n * 16)) = acc[ai][BJ][m][n] + ((r[i - LO] - mean[(i - LO) >> 1]) * rstd[(i - LO) >> 1]) * gv[n] + bv[n]; }
;         __builtin_amdgcn_sched_barrier(0);
;     }
;     template <bool LN, int BJ> DI void load_gb(unsigned col0, f32x4 (&gv)[2], f32x4 (&bv)[2]) const {
; #pragma unroll
;         for (int n = 0; n < 2; ++n) {
;             if (LN) { gv[n] = *(const f32x4*)(gam + col0 + BJ * HALF + n * 16) * ALPHA; bv[n] = *(const f32x4*)(bet + col0 + BJ * HALF + n * 16) * ALPHA; }
;             else { gv[n] = (f32x4){ALPHA, ALPHA, ALPHA, ALPHA}; bv[n] = (f32x4){0.f, 0.f, 0.f, 0.f}; }
;         }
;     }
;     template <bool LN> DI void run(const f32x4 (&acc)[2][2][4][2], const Unit& u, int wr, int wc, int fr, int fq) const {
;         const unsigned row0 = u.pm * BM + wr * 64 + fr, col0 = u.pn * BM + wc * 32 + 4 * fq;
;         f32x4 gv[2], bv[2];
;         load_gb<LN, 0>(col0, gv, bv);
;         batch<LN, 0, 0, 4>(acc, row0, col0, gv, bv);
;         batch<LN, 0, 4, 8>(acc, row0, col0, gv, bv);
;         batch<LN, 0, 8, 12>(acc, row0, col0, gv, bv);
;         batch<LN, 0, 12, 16>(acc, row0, col0, gv, bv);
;         load_gb<LN, 1>(col0, gv, bv);
;         batch<LN, 1, 0, 8>(acc, row0, col0, gv, bv);
;         batch<LN, 1, 8, 16>(acc, row0, col0, gv, bv);
;     }
	v_sub_f32_e32 v203, v217, v220
	v_sub_f32_e32 v202, v216, v220
	v_sub_f32_e32 v205, v219, v220
	v_sub_f32_e32 v204, v218, v220
	v_pk_mul_f32 v[204:205], v[220:221], v[204:205] op_sel:[1,0]
	v_pk_mul_f32 v[202:203], v[220:221], v[202:203] op_sel:[1,0]
	v_pk_fma_f32 v[204:205], v[212:213], v[204:205], v[30:31]
	v_pk_fma_f32 v[202:203], v[214:215], v[202:203], v[28:29]
	v_pk_fma_f32 v[204:205], v[134:135], s[78:79], v[204:205] op_sel_hi:[1,0,1]
	v_pk_fma_f32 v[202:203], v[132:133], s[78:79], v[202:203] op_sel_hi:[1,0,1]
	global_store_dwordx4 v[210:211], v[202:205], off
	v_add_u32_e32 v210, 0x40090, v194
	v_mov_b32_e32 v211, v159
	v_sub_f32_e32 v203, v241, v220
	v_sub_f32_e32 v202, v240, v220
	v_sub_f32_e32 v205, v243, v220
	v_sub_f32_e32 v204, v242, v220
	v_pk_mul_f32 v[204:205], v[220:221], v[204:205] op_sel:[1,0]
	v_pk_mul_f32 v[202:203], v[220:221], v[202:203] op_sel:[1,0]
	v_pk_fma_f32 v[204:205], v[206:207], v[204:205], v[26:27]
	v_pk_fma_f32 v[202:203], v[208:209], v[202:203], v[24:25]
	v_pk_fma_f32 v[204:205], v[130:131], s[78:79], v[204:205] op_sel_hi:[1,0,1]
	v_pk_fma_f32 v[202:203], v[128:129], s[78:79], v[202:203] op_sel_hi:[1,0,1]
	v_lshl_add_u64 v[210:211], v[210:211], 2, s[90:91]
	global_store_dwordx4 v[210:211], v[202:205], off
	v_sub_f32_e32 v149, v149, v198
	v_sub_f32_e32 v148, v148, v198
	v_sub_f32_e32 v203, v245, v200
	v_sub_f32_e32 v202, v244, v200
	v_sub_f32_e32 v141, v141, v196
	v_sub_f32_e32 v140, v140, v196
	v_sub_f32_e32 v205, v247, v200
	v_sub_f32_e32 v204, v246, v200
	v_pk_mul_f32 v[202:203], v[200:201], v[202:203] op_sel:[1,0]
	v_sub_f32_e32 v151, v151, v198
	v_sub_f32_e32 v150, v150, v198
	v_pk_mul_f32 v[148:149], v[198:199], v[148:149] op_sel:[1,0]
	v_sub_f32_e32 v143, v143, v196
	v_sub_f32_e32 v142, v142, v196
	v_pk_mul_f32 v[140:141], v[196:197], v[140:141] op_sel:[1,0]
	v_pk_mul_f32 v[204:205], v[200:201], v[204:205] op_sel:[1,0]
	v_pk_fma_f32 v[202:203], v[214:215], v[202:203], v[20:21]
	v_sub_f32_e32 v153, v153, v200
	v_sub_f32_e32 v152, v152, v200
	v_sub_f32_e32 v155, v155, v200
	v_sub_f32_e32 v154, v154, v200
	v_pk_mul_f32 v[150:151], v[198:199], v[150:151] op_sel:[1,0]
	v_pk_fma_f32 v[148:149], v[214:215], v[148:149], v[12:13]
	v_pk_mul_f32 v[142:143], v[196:197], v[142:143] op_sel:[1,0]
	v_pk_fma_f32 v[140:141], v[214:215], v[140:141], v[4:5]
	v_pk_fma_f32 v[204:205], v[212:213], v[204:205], v[22:23]
	v_pk_fma_f32 v[202:203], v[132:133], s[78:79], v[202:203] op_sel_hi:[1,0,1]
	v_pk_mul_f32 v[154:155], v[200:201], v[154:155] op_sel:[1,0]
	v_pk_mul_f32 v[152:153], v[200:201], v[152:153] op_sel:[1,0]
	v_pk_fma_f32 v[150:151], v[212:213], v[150:151], v[14:15]
	v_pk_fma_f32 v[148:149], v[132:133], s[78:79], v[148:149] op_sel_hi:[1,0,1]
	v_pk_fma_f32 v[142:143], v[212:213], v[142:143], v[6:7]
	v_pk_fma_f32 v[132:133], v[132:133], s[78:79], v[140:141] op_sel_hi:[1,0,1]
	v_add_u32_e32 v140, 0x58080, v194
	v_mov_b32_e32 v141, v159
	v_pk_fma_f32 v[204:205], v[134:135], s[78:79], v[204:205] op_sel_hi:[1,0,1]
	v_pk_fma_f32 v[152:153], v[208:209], v[152:153], v[16:17]
	v_pk_fma_f32 v[154:155], v[206:207], v[154:155], v[18:19]
	v_add_u32_e32 v200, 0x48090, v194
	v_mov_b32_e32 v201, v159
	v_pk_fma_f32 v[150:151], v[134:135], s[78:79], v[150:151] op_sel_hi:[1,0,1]
	v_pk_fma_f32 v[134:135], v[134:135], s[78:79], v[142:143] op_sel_hi:[1,0,1]
	v_lshl_add_u64 v[140:141], v[140:141], 2, s[90:91]
	v_pk_fma_f32 v[154:155], v[130:131], s[78:79], v[154:155] op_sel_hi:[1,0,1]
	v_pk_fma_f32 v[152:153], v[128:129], s[78:79], v[152:153] op_sel_hi:[1,0,1]
	v_lshl_add_u64 v[200:201], v[200:201], 2, s[90:91]
	v_sub_f32_e32 v145, v145, v198
	v_sub_f32_e32 v144, v144, v198
	global_store_dwordx4 v[140:141], v[132:135], off
	global_store_dwordx4 v[200:201], v[152:155], off
	v_sub_f32_e32 v147, v147, v198
	v_sub_f32_e32 v133, v137, v196
	v_sub_f32_e32 v132, v136, v196
	v_add_u32_e32 v152, 0x50080, v194
	v_mov_b32_e32 v153, v159
	v_sub_f32_e32 v146, v146, v198
	v_pk_mul_f32 v[144:145], v[198:199], v[144:145] op_sel:[1,0]
	v_sub_f32_e32 v135, v139, v196
	v_sub_f32_e32 v134, v138, v196
	v_pk_mul_f32 v[132:133], v[196:197], v[132:133] op_sel:[1,0]
	v_lshl_add_u64 v[152:153], v[152:153], 2, s[90:91]
	v_pk_mul_f32 v[146:147], v[198:199], v[146:147] op_sel:[1,0]
	v_pk_fma_f32 v[144:145], v[208:209], v[144:145], v[8:9]
	v_pk_mul_f32 v[134:135], v[196:197], v[134:135] op_sel:[1,0]
	v_pk_fma_f32 v[132:133], v[208:209], v[132:133], v[0:1]
	v_add_u32_e32 v210, 0x48080, v194
	v_mov_b32_e32 v211, v159
	global_store_dwordx4 v[152:153], v[148:151], off
	v_pk_fma_f32 v[146:147], v[206:207], v[146:147], v[10:11]
	v_pk_fma_f32 v[144:145], v[128:129], s[78:79], v[144:145] op_sel_hi:[1,0,1]
	v_add_u32_e32 v148, 0x50090, v194
	v_mov_b32_e32 v149, v159
	v_pk_fma_f32 v[134:135], v[206:207], v[134:135], v[2:3]
	v_pk_fma_f32 v[128:129], v[128:129], s[78:79], v[132:133] op_sel_hi:[1,0,1]
	v_add_u32_e32 v132, 0x58090, v194
	v_mov_b32_e32 v133, v159
	v_lshl_add_u64 v[210:211], v[210:211], 2, s[90:91]
	v_pk_fma_f32 v[146:147], v[130:131], s[78:79], v[146:147] op_sel_hi:[1,0,1]
	v_lshl_add_u64 v[148:149], v[148:149], 2, s[90:91]
	v_pk_fma_f32 v[130:131], v[130:131], s[78:79], v[134:135] op_sel_hi:[1,0,1]
	v_lshl_add_u64 v[132:133], v[132:133], 2, s[90:91]
	global_store_dwordx4 v[210:211], v[202:205], off
	global_store_dwordx4 v[148:149], v[144:147], off
	global_store_dwordx4 v[132:133], v[128:131], off
	s_mov_b64 s[24:25], 0
	s_branch .LBB0_324

; #define LAS __attribute__((address_space(3)))
; __global__ void __launch_bounds__(512, 2) mega_fwd(Params p) {
;     extern __shared__ __attribute__((aligned(16))) unsigned char shm[];
;     LAS unsigned char* lds = (LAS unsigned char*)shm;
;     cg::grid_group grid = cg::this_grid();
	.amdhsa_kernel _Z8mega_fwd6Params
		.amdhsa_group_segment_fixed_size 0
		.amdhsa_private_segment_fixed_size 0
		.amdhsa_kernarg_size 832
		.amdhsa_user_sgpr_count 2
		.amdhsa_user_sgpr_dispatch_ptr 0
		.amdhsa_user_sgpr_queue_ptr 0
		.amdhsa_user_sgpr_kernarg_segment_ptr 1
		.amdhsa_user_sgpr_dispatch_id 0
		.amdhsa_user_sgpr_kernarg_preload_length 0
		.amdhsa_user_sgpr_kernarg_preload_offset 0
		.amdhsa_user_sgpr_private_segment_size 0
		.amdhsa_uses_dynamic_stack 0
		.amdhsa_enable_private_segment 0
		.amdhsa_system_sgpr_workgroup_id_x 1
		.amdhsa_system_sgpr_workgroup_id_y 0
		.amdhsa_system_sgpr_workgroup_id_z 0
		.amdhsa_system_sgpr_workgroup_info 0
		.amdhsa_system_vgpr_workitem_id 2
		.amdhsa_next_free_vgpr 256
		.amdhsa_next_free_sgpr 102
		.amdhsa_accum_offset 256
		.amdhsa_reserve_vcc 1
		.amdhsa_float_round_mode_32 0
		.amdhsa_float_round_mode_16_64 0
		.amdhsa_float_denorm_mode_32 3
		.amdhsa_float_denorm_mode_16_64 3
		.amdhsa_dx10_clamp 1
		.amdhsa_ieee_mode 1
		.amdhsa_fp16_overflow 0
		.amdhsa_tg_split 0
		.amdhsa_exception_fp_ieee_invalid_op 0
		.amdhsa_exception_fp_denorm_src 0
		.amdhsa_exception_fp_ieee_div_zero 0
		.amdhsa_exception_fp_ieee_overflow 0
		.amdhsa_exception_fp_ieee_underflow 0
		.amdhsa_exception_fp_ieee_inexact 0
		.amdhsa_exception_int_div_zero 0
	.end_amdhsa_kernel

; #define LAS __attribute__((address_space(3)))
; __global__ void __launch_bounds__(512, 2) mega_fwd(Params p) {
;     extern __shared__ __attribute__((aligned(16))) unsigned char shm[];
;     LAS unsigned char* lds = (LAS unsigned char*)shm;
;     cg::grid_group grid = cg::this_grid();
amdhsa.kernels:
  - .agpr_count:     0
    .args:
      - .offset:         0
        .size:           576
        .value_kind:     by_value
      - .offset:         576
        .size:           4
        .value_kind:     hidden_block_count_x
      - .offset:         580
        .size:           4
        .value_kind:     hidden_block_count_y
      - .offset:         584
        .size:           4
        .value_kind:     hidden_block_count_z
      - .offset:         588
        .size:           2
        .value_kind:     hidden_group_size_x
      - .offset:         590
        .size:           2
        .value_kind:     hidden_group_size_y
      - .offset:         592
        .size:           2
        .value_kind:     hidden_group_size_z
      - .offset:         594
        .size:           2
        .value_kind:     hidden_remainder_x
      - .offset:         596
        .size:           2
        .value_kind:     hidden_remainder_y
      - .offset:         598
        .size:           2
        .value_kind:     hidden_remainder_z
      - .offset:         616
        .size:           8
        .value_kind:     hidden_global_offset_x
      - .offset:         624
        .size:           8
        .value_kind:     hidden_global_offset_y
      - .offset:         632
        .size:           8
        .value_kind:     hidden_global_offset_z
      - .offset:         640
        .size:           2
        .value_kind:     hidden_grid_dims
      - .offset:         664
        .size:           8
        .value_kind:     hidden_multigrid_sync_arg
      - .offset:         696
        .size:           4
        .value_kind:     hidden_dynamic_lds_size
    .group_segment_fixed_size: 0
    .kernarg_segment_align: 8
    .kernarg_segment_size: 832
    .language:       OpenCL C
    .language_version:
      - 2
      - 0
    .max_flat_workgroup_size: 512
    .name:           _Z8mega_fwd6Params
    .private_segment_fixed_size: 0
    .sgpr_count:     108
    .sgpr_spill_count: 189
    .symbol:         _Z8mega_fwd6Params.kd
    .uniform_work_group_size: 1
    .uses_dynamic_stack: false
    .vgpr_count:     256
    .vgpr_spill_count: 0
    .wavefront_size: 64
